# GEMM main loops: removed the compiler's duplicate lgkmcnt(0) after each phase barrier (48 sites); on top of v30
# speedup vs baseline: 1.0058x; 1.0058x over previous
.LBB0_170:
	s_add_u32 s36, s70, 0xfff00080
	s_addc_u32 s72, s71, -1
	s_add_i32 s85, 0, 0x10000
	s_cmp_eq_u32 s84, 60
	s_cselect_b32 s73, s47, s72
	s_cselect_b32 s72, s74, s36
	v_add_u32_e32 v132, s85, v137
	s_cselect_b32 s87, s7, s81
	s_cselect_b32 s86, s75, s77
	s_add_i32 s36, 0, 0x14000
	ds_read_b128 v[156:159], v132
	ds_read_b128 v[160:163], v132 offset:1024
	ds_read_b128 v[164:167], v132 offset:2048
	ds_read_b128 v[180:183], v132 offset:3072
	v_add_u32_e32 v132, s36, v137
	ds_read_b128 v[184:187], v132
	ds_read_b128 v[188:191], v132 offset:1024
	ds_read_b128 v[192:195], v132 offset:2048
	ds_read_b128 v[196:199], v132 offset:3072
	v_lshl_add_u64 v[134:135], s[70:71], 0, v[130:131]
	s_add_i32 m0, s18, 0xc000
	ds_read_b128 v[204:207], v141
	ds_read_b128 v[208:211], v141 offset:1024
	ds_read_b128 v[212:215], v141 offset:2048
	ds_read_b128 v[216:219], v141 offset:3072
	ds_read_b128 v[220:223], v141 offset:4096
	ds_read_b128 v[224:227], v141 offset:5120
	ds_read_b128 v[228:231], v141 offset:6144
	ds_read_b128 v[232:235], v141 offset:7168
	global_load_lds_dwordx4 v[134:135], off
	v_lshl_add_u64 v[134:135], v[134:135], 0, s[56:57]
	s_add_i32 m0, s18, 0xe000
	s_nop 0
	global_load_lds_dwordx4 v[134:135], off
	s_waitcnt vmcnt(8)
	s_waitcnt lgkmcnt(0)
	s_barrier
	s_setprio 1
	v_mfma_f32_16x16x32_bf16 v[124:127], v[156:159], v[204:207], v[124:127]
	v_mfma_f32_16x16x32_bf16 v[120:123], v[164:167], v[204:207], v[120:123]
	v_mfma_f32_16x16x32_bf16 v[108:111], v[156:159], v[212:215], v[108:111]
	v_mfma_f32_16x16x32_bf16 v[104:107], v[164:167], v[212:215], v[104:107]
	v_mfma_f32_16x16x32_bf16 v[92:95], v[156:159], v[220:223], v[92:95]
	v_mfma_f32_16x16x32_bf16 v[88:91], v[164:167], v[220:223], v[88:91]
	v_mfma_f32_16x16x32_bf16 v[76:79], v[156:159], v[228:231], v[76:79]
	v_mfma_f32_16x16x32_bf16 v[72:75], v[164:167], v[228:231], v[72:75]
	v_mfma_f32_16x16x32_bf16 v[124:127], v[160:163], v[208:211], v[124:127]
	v_mfma_f32_16x16x32_bf16 v[120:123], v[180:183], v[208:211], v[120:123]
	v_mfma_f32_16x16x32_bf16 v[108:111], v[160:163], v[216:219], v[108:111]
	v_mfma_f32_16x16x32_bf16 v[104:107], v[180:183], v[216:219], v[104:107]
	v_mfma_f32_16x16x32_bf16 v[92:95], v[160:163], v[224:227], v[92:95]
	v_mfma_f32_16x16x32_bf16 v[88:91], v[180:183], v[224:227], v[88:91]
	v_mfma_f32_16x16x32_bf16 v[76:79], v[160:163], v[232:235], v[76:79]
	v_mfma_f32_16x16x32_bf16 v[72:75], v[180:183], v[232:235], v[72:75]
	s_setprio 0
	s_setprio 1
	v_mfma_f32_16x16x32_bf16 v[116:119], v[184:187], v[204:207], v[116:119]
	v_mfma_f32_16x16x32_bf16 v[112:115], v[192:195], v[204:207], v[112:115]
	v_mfma_f32_16x16x32_bf16 v[100:103], v[184:187], v[212:215], v[100:103]
	v_mfma_f32_16x16x32_bf16 v[96:99], v[192:195], v[212:215], v[96:99]
	v_mfma_f32_16x16x32_bf16 v[84:87], v[184:187], v[220:223], v[84:87]
	v_mfma_f32_16x16x32_bf16 v[80:83], v[192:195], v[220:223], v[80:83]
	v_mfma_f32_16x16x32_bf16 v[68:71], v[184:187], v[228:231], v[68:71]
	v_mfma_f32_16x16x32_bf16 v[64:67], v[192:195], v[228:231], v[64:67]
	v_mfma_f32_16x16x32_bf16 v[116:119], v[188:191], v[208:211], v[116:119]
	v_mfma_f32_16x16x32_bf16 v[112:115], v[196:199], v[208:211], v[112:115]
	v_mfma_f32_16x16x32_bf16 v[100:103], v[188:191], v[216:219], v[100:103]
	v_mfma_f32_16x16x32_bf16 v[96:99], v[196:199], v[216:219], v[96:99]
	v_mfma_f32_16x16x32_bf16 v[84:87], v[188:191], v[224:227], v[84:87]
	v_mfma_f32_16x16x32_bf16 v[80:83], v[196:199], v[224:227], v[80:83]
	v_mfma_f32_16x16x32_bf16 v[68:71], v[188:191], v[232:235], v[68:71]
	v_mfma_f32_16x16x32_bf16 v[64:67], v[196:199], v[232:235], v[64:67]
	s_setprio 0
	s_barrier
	s_add_i32 s85, s85, s17
	v_lshl_add_u64 v[134:135], s[86:87], 0, v[144:145]
	s_mov_b32 m0, s85
	ds_read_b128 v[204:207], v141 offset:16384
	ds_read_b128 v[208:211], v141 offset:17408
	ds_read_b128 v[212:215], v141 offset:18432
	ds_read_b128 v[216:219], v141 offset:19456
	ds_read_b128 v[220:223], v141 offset:20480
	ds_read_b128 v[224:227], v141 offset:21504
	ds_read_b128 v[228:231], v141 offset:22528
	ds_read_b128 v[232:235], v141 offset:23552
	global_load_lds_dwordx4 v[134:135], off
	v_lshl_add_u64 v[142:143], v[134:135], 0, s[56:57]
	s_add_i32 m0, s85, 0x2000
	s_add_i32 s36, s36, s17
	global_load_lds_dwordx4 v[142:143], off
	v_lshl_add_u64 v[142:143], v[134:135], 0, s[54:55]
	s_mov_b32 m0, s36
	s_nop 0
	global_load_lds_dwordx4 v[142:143], off
	v_lshl_add_u64 v[142:143], v[134:135], 0, s[58:59]
	s_add_i32 m0, s36, 0x2000
	s_nop 0
	global_load_lds_dwordx4 v[142:143], off
	v_lshl_add_u64 v[142:143], s[72:73], 0, v[128:129]
	s_mov_b32 m0, s18
	v_lshl_add_u64 v[150:151], v[142:143], 0, s[56:57]
	global_load_lds_dwordx4 v[142:143], off
	s_mov_b32 m0, s19
	s_nop 0
	global_load_lds_dwordx4 v[150:151], off
	s_waitcnt vmcnt(8)
	s_waitcnt lgkmcnt(0)
	s_barrier
	s_setprio 1
	v_mfma_f32_16x16x32_bf16 v[60:63], v[156:159], v[204:207], v[60:63]
	v_mfma_f32_16x16x32_bf16 v[56:59], v[164:167], v[204:207], v[56:59]
	v_mfma_f32_16x16x32_bf16 v[44:47], v[156:159], v[212:215], v[44:47]
	v_mfma_f32_16x16x32_bf16 v[40:43], v[164:167], v[212:215], v[40:43]
	v_mfma_f32_16x16x32_bf16 v[28:31], v[156:159], v[220:223], v[28:31]
	v_mfma_f32_16x16x32_bf16 v[24:27], v[164:167], v[220:223], v[24:27]
	v_mfma_f32_16x16x32_bf16 v[12:15], v[156:159], v[228:231], v[12:15]
	v_mfma_f32_16x16x32_bf16 v[8:11], v[164:167], v[228:231], v[8:11]
	v_mfma_f32_16x16x32_bf16 v[60:63], v[160:163], v[208:211], v[60:63]
	v_mfma_f32_16x16x32_bf16 v[56:59], v[180:183], v[208:211], v[56:59]
	v_mfma_f32_16x16x32_bf16 v[44:47], v[160:163], v[216:219], v[44:47]
	v_mfma_f32_16x16x32_bf16 v[40:43], v[180:183], v[216:219], v[40:43]
	v_mfma_f32_16x16x32_bf16 v[28:31], v[160:163], v[224:227], v[28:31]
	v_mfma_f32_16x16x32_bf16 v[24:27], v[180:183], v[224:227], v[24:27]
	v_mfma_f32_16x16x32_bf16 v[12:15], v[160:163], v[232:235], v[12:15]
	v_mfma_f32_16x16x32_bf16 v[8:11], v[180:183], v[232:235], v[8:11]
	s_setprio 0
	s_setprio 1
	v_mfma_f32_16x16x32_bf16 v[52:55], v[184:187], v[204:207], v[52:55]
	v_mfma_f32_16x16x32_bf16 v[48:51], v[192:195], v[204:207], v[48:51]
	v_mfma_f32_16x16x32_bf16 v[36:39], v[184:187], v[212:215], v[36:39]
	v_mfma_f32_16x16x32_bf16 v[32:35], v[192:195], v[212:215], v[32:35]
	v_mfma_f32_16x16x32_bf16 v[20:23], v[184:187], v[220:223], v[20:23]
	v_mfma_f32_16x16x32_bf16 v[16:19], v[192:195], v[220:223], v[16:19]
	v_mfma_f32_16x16x32_bf16 v[4:7], v[184:187], v[228:231], v[4:7]
	v_mfma_f32_16x16x32_bf16 v[0:3], v[192:195], v[228:231], v[0:3]
	v_mfma_f32_16x16x32_bf16 v[52:55], v[188:191], v[208:211], v[52:55]
	v_mfma_f32_16x16x32_bf16 v[48:51], v[196:199], v[208:211], v[48:51]
	v_mfma_f32_16x16x32_bf16 v[36:39], v[188:191], v[216:219], v[36:39]
	v_mfma_f32_16x16x32_bf16 v[32:35], v[196:199], v[216:219], v[32:35]
	v_mfma_f32_16x16x32_bf16 v[20:23], v[188:191], v[224:227], v[20:23]
	v_mfma_f32_16x16x32_bf16 v[16:19], v[196:199], v[224:227], v[16:19]
	v_mfma_f32_16x16x32_bf16 v[4:7], v[188:191], v[232:235], v[4:7]
	v_mfma_f32_16x16x32_bf16 v[0:3], v[196:199], v[232:235], v[0:3]
	s_setprio 0
	s_barrier
	s_add_i32 s36, 0, 0x18000
	v_add_u32_e32 v132, s36, v137
	s_add_i32 s72, 0, 0x1c000
	ds_read_b128 v[156:159], v132
	ds_read_b128 v[160:163], v132 offset:1024
	ds_read_b128 v[164:167], v132 offset:2048
	ds_read_b128 v[180:183], v132 offset:3072
	v_add_u32_e32 v132, s72, v137
	ds_read_b128 v[184:187], v132
	ds_read_b128 v[188:191], v132 offset:1024
	ds_read_b128 v[192:195], v132 offset:2048
	ds_read_b128 v[196:199], v132 offset:3072
	s_mov_b32 m0, s20
	v_lshl_add_u64 v[150:151], v[142:143], 0, s[54:55]
	ds_read_b128 v[204:207], v141 offset:32768
	ds_read_b128 v[208:211], v141 offset:33792
	ds_read_b128 v[212:215], v141 offset:34816
	ds_read_b128 v[216:219], v141 offset:35840
	ds_read_b128 v[220:223], v141 offset:36864
	ds_read_b128 v[224:227], v141 offset:37888
	ds_read_b128 v[228:231], v141 offset:38912
	ds_read_b128 v[232:235], v141 offset:39936
	global_load_lds_dwordx4 v[150:151], off
	v_lshl_add_u64 v[150:151], v[142:143], 0, s[58:59]
	s_mov_b32 m0, s21
	s_nop 0
	global_load_lds_dwordx4 v[150:151], off
	s_waitcnt vmcnt(8)
	s_waitcnt lgkmcnt(0)
	s_barrier
	s_setprio 1
	v_mfma_f32_16x16x32_bf16 v[124:127], v[156:159], v[204:207], v[124:127]
	v_mfma_f32_16x16x32_bf16 v[120:123], v[164:167], v[204:207], v[120:123]
	v_mfma_f32_16x16x32_bf16 v[108:111], v[156:159], v[212:215], v[108:111]
	v_mfma_f32_16x16x32_bf16 v[104:107], v[164:167], v[212:215], v[104:107]
	v_mfma_f32_16x16x32_bf16 v[92:95], v[156:159], v[220:223], v[92:95]
	v_mfma_f32_16x16x32_bf16 v[88:91], v[164:167], v[220:223], v[88:91]
	v_mfma_f32_16x16x32_bf16 v[76:79], v[156:159], v[228:231], v[76:79]
	v_mfma_f32_16x16x32_bf16 v[72:75], v[164:167], v[228:231], v[72:75]
	v_mfma_f32_16x16x32_bf16 v[124:127], v[160:163], v[208:211], v[124:127]
	v_mfma_f32_16x16x32_bf16 v[120:123], v[180:183], v[208:211], v[120:123]
	v_mfma_f32_16x16x32_bf16 v[108:111], v[160:163], v[216:219], v[108:111]
	v_mfma_f32_16x16x32_bf16 v[104:107], v[180:183], v[216:219], v[104:107]
	v_mfma_f32_16x16x32_bf16 v[92:95], v[160:163], v[224:227], v[92:95]
	v_mfma_f32_16x16x32_bf16 v[88:91], v[180:183], v[224:227], v[88:91]
	v_mfma_f32_16x16x32_bf16 v[76:79], v[160:163], v[232:235], v[76:79]
	v_mfma_f32_16x16x32_bf16 v[72:75], v[180:183], v[232:235], v[72:75]
	s_setprio 0
	s_setprio 1
	v_mfma_f32_16x16x32_bf16 v[116:119], v[184:187], v[204:207], v[116:119]
	v_mfma_f32_16x16x32_bf16 v[112:115], v[192:195], v[204:207], v[112:115]
	v_mfma_f32_16x16x32_bf16 v[100:103], v[184:187], v[212:215], v[100:103]
	v_mfma_f32_16x16x32_bf16 v[96:99], v[192:195], v[212:215], v[96:99]
	v_mfma_f32_16x16x32_bf16 v[84:87], v[184:187], v[220:223], v[84:87]
	v_mfma_f32_16x16x32_bf16 v[80:83], v[192:195], v[220:223], v[80:83]
	v_mfma_f32_16x16x32_bf16 v[68:71], v[184:187], v[228:231], v[68:71]
	v_mfma_f32_16x16x32_bf16 v[64:67], v[192:195], v[228:231], v[64:67]
	v_mfma_f32_16x16x32_bf16 v[116:119], v[188:191], v[208:211], v[116:119]
	v_mfma_f32_16x16x32_bf16 v[112:115], v[196:199], v[208:211], v[112:115]
	v_mfma_f32_16x16x32_bf16 v[100:103], v[188:191], v[216:219], v[100:103]
	v_mfma_f32_16x16x32_bf16 v[96:99], v[196:199], v[216:219], v[96:99]
	v_mfma_f32_16x16x32_bf16 v[84:87], v[188:191], v[224:227], v[84:87]
	v_mfma_f32_16x16x32_bf16 v[80:83], v[196:199], v[224:227], v[80:83]
	v_mfma_f32_16x16x32_bf16 v[68:71], v[188:191], v[232:235], v[68:71]
	v_mfma_f32_16x16x32_bf16 v[64:67], v[196:199], v[232:235], v[64:67]
	s_setprio 0
	s_barrier
	s_add_i32 s36, s36, s17
	v_lshl_add_u64 v[150:151], v[134:135], 0, s[60:61]
	s_mov_b32 m0, s36
	ds_read_b128 v[204:207], v141 offset:49152
	ds_read_b128 v[208:211], v141 offset:50176
	ds_read_b128 v[212:215], v141 offset:51200
	ds_read_b128 v[216:219], v141 offset:52224
	ds_read_b128 v[220:223], v141 offset:53248
	ds_read_b128 v[224:227], v141 offset:54272
	ds_read_b128 v[228:231], v141 offset:55296
	ds_read_b128 v[232:235], v141 offset:56320
	global_load_lds_dwordx4 v[150:151], off
	v_lshl_add_u64 v[150:151], v[134:135], 0, s[62:63]
	s_add_i32 m0, s36, 0x2000
	s_add_i32 s36, s72, s17
	global_load_lds_dwordx4 v[150:151], off
	v_lshl_add_u64 v[150:151], v[134:135], 0, s[64:65]
	s_mov_b32 m0, s36
	v_lshl_add_u64 v[134:135], v[134:135], 0, s[66:67]
	global_load_lds_dwordx4 v[150:151], off
	s_add_i32 m0, s36, 0x2000
	s_nop 0
	global_load_lds_dwordx4 v[134:135], off
	v_lshl_add_u64 v[134:135], v[142:143], 0, s[60:61]
	s_mov_b32 m0, s22
	s_nop 0
	global_load_lds_dwordx4 v[134:135], off
	v_lshl_add_u64 v[134:135], v[142:143], 0, s[62:63]
	s_mov_b32 m0, s23
	s_nop 0
	global_load_lds_dwordx4 v[134:135], off
	s_waitcnt vmcnt(8)
	s_waitcnt lgkmcnt(0)
	s_barrier
	s_setprio 1
	v_mfma_f32_16x16x32_bf16 v[60:63], v[156:159], v[204:207], v[60:63]
	v_mfma_f32_16x16x32_bf16 v[56:59], v[164:167], v[204:207], v[56:59]
	v_mfma_f32_16x16x32_bf16 v[44:47], v[156:159], v[212:215], v[44:47]
	v_mfma_f32_16x16x32_bf16 v[40:43], v[164:167], v[212:215], v[40:43]
	v_mfma_f32_16x16x32_bf16 v[28:31], v[156:159], v[220:223], v[28:31]
	v_mfma_f32_16x16x32_bf16 v[24:27], v[164:167], v[220:223], v[24:27]
	v_mfma_f32_16x16x32_bf16 v[12:15], v[156:159], v[228:231], v[12:15]
	v_mfma_f32_16x16x32_bf16 v[8:11], v[164:167], v[228:231], v[8:11]
	v_mfma_f32_16x16x32_bf16 v[60:63], v[160:163], v[208:211], v[60:63]
	v_mfma_f32_16x16x32_bf16 v[56:59], v[180:183], v[208:211], v[56:59]
	v_mfma_f32_16x16x32_bf16 v[44:47], v[160:163], v[216:219], v[44:47]
	v_mfma_f32_16x16x32_bf16 v[40:43], v[180:183], v[216:219], v[40:43]
	v_mfma_f32_16x16x32_bf16 v[28:31], v[160:163], v[224:227], v[28:31]
	v_mfma_f32_16x16x32_bf16 v[24:27], v[180:183], v[224:227], v[24:27]
	v_mfma_f32_16x16x32_bf16 v[12:15], v[160:163], v[232:235], v[12:15]
	v_mfma_f32_16x16x32_bf16 v[8:11], v[180:183], v[232:235], v[8:11]
	s_setprio 0
	s_setprio 1
	v_mfma_f32_16x16x32_bf16 v[52:55], v[184:187], v[204:207], v[52:55]
	v_mfma_f32_16x16x32_bf16 v[48:51], v[192:195], v[204:207], v[48:51]
	v_mfma_f32_16x16x32_bf16 v[36:39], v[184:187], v[212:215], v[36:39]
	v_mfma_f32_16x16x32_bf16 v[32:35], v[192:195], v[212:215], v[32:35]
	v_mfma_f32_16x16x32_bf16 v[20:23], v[184:187], v[220:223], v[20:23]
	v_mfma_f32_16x16x32_bf16 v[16:19], v[192:195], v[220:223], v[16:19]
	v_mfma_f32_16x16x32_bf16 v[4:7], v[184:187], v[228:231], v[4:7]
	v_mfma_f32_16x16x32_bf16 v[0:3], v[192:195], v[228:231], v[0:3]
	v_mfma_f32_16x16x32_bf16 v[52:55], v[188:191], v[208:211], v[52:55]
	v_mfma_f32_16x16x32_bf16 v[48:51], v[196:199], v[208:211], v[48:51]
	v_mfma_f32_16x16x32_bf16 v[36:39], v[188:191], v[216:219], v[36:39]
	v_mfma_f32_16x16x32_bf16 v[32:35], v[196:199], v[216:219], v[32:35]
	v_mfma_f32_16x16x32_bf16 v[20:23], v[188:191], v[224:227], v[20:23]
	v_mfma_f32_16x16x32_bf16 v[16:19], v[196:199], v[224:227], v[16:19]
	v_mfma_f32_16x16x32_bf16 v[4:7], v[188:191], v[232:235], v[4:7]
	v_mfma_f32_16x16x32_bf16 v[0:3], v[196:199], v[232:235], v[0:3]
	s_setprio 0
	s_barrier
	s_add_i32 s84, s84, 2
	s_add_u32 s70, s70, 0x100
	s_addc_u32 s71, s71, 0
	s_add_u32 s77, s77, 0x100
	s_addc_u32 s81, s81, 0
	s_cmp_gt_u32 s84, 61
	s_cbranch_scc0 .LBB0_170
	s_and_b64 vcc, exec, s[4:5]
	s_movk_i32 s77, 0x7fff
	s_cbranch_vccz .LBB0_173
	s_barrier

.LBB0_333:
	s_add_u32 s36, s70, 0xfff00080
	s_addc_u32 s72, s71, -1
	s_add_i32 s85, 0, 0x10000
	s_cmp_eq_u32 s81, 60
	s_cselect_b32 s73, s42, s72
	s_cselect_b32 s72, s47, s36
	v_add_u32_e32 v132, s85, v137
	s_cselect_b32 s87, s7, s77
	s_cselect_b32 s86, s74, s75
	s_add_i32 s36, 0, 0x14000
	ds_read_b128 v[156:159], v132
	ds_read_b128 v[160:163], v132 offset:1024
	ds_read_b128 v[164:167], v132 offset:2048
	ds_read_b128 v[180:183], v132 offset:3072
	v_add_u32_e32 v132, s36, v137
	ds_read_b128 v[184:187], v132
	ds_read_b128 v[188:191], v132 offset:1024
	ds_read_b128 v[192:195], v132 offset:2048
	ds_read_b128 v[196:199], v132 offset:3072
	v_lshl_add_u64 v[134:135], s[70:71], 0, v[130:131]
	s_add_i32 m0, s18, 0xc000
	ds_read_b128 v[204:207], v141
	ds_read_b128 v[208:211], v141 offset:1024
	ds_read_b128 v[212:215], v141 offset:2048
	ds_read_b128 v[216:219], v141 offset:3072
	ds_read_b128 v[220:223], v141 offset:4096
	ds_read_b128 v[224:227], v141 offset:5120
	ds_read_b128 v[228:231], v141 offset:6144
	ds_read_b128 v[232:235], v141 offset:7168
	global_load_lds_dwordx4 v[134:135], off
	v_lshl_add_u64 v[134:135], v[134:135], 0, s[56:57]
	s_add_i32 m0, s18, 0xe000
	s_nop 0
	global_load_lds_dwordx4 v[134:135], off
	s_waitcnt vmcnt(8)
	s_waitcnt lgkmcnt(0)
	s_barrier
	s_setprio 1
	v_mfma_f32_16x16x32_bf16 v[124:127], v[156:159], v[204:207], v[124:127]
	v_mfma_f32_16x16x32_bf16 v[120:123], v[164:167], v[204:207], v[120:123]
	v_mfma_f32_16x16x32_bf16 v[108:111], v[156:159], v[212:215], v[108:111]
	v_mfma_f32_16x16x32_bf16 v[104:107], v[164:167], v[212:215], v[104:107]
	v_mfma_f32_16x16x32_bf16 v[92:95], v[156:159], v[220:223], v[92:95]
	v_mfma_f32_16x16x32_bf16 v[88:91], v[164:167], v[220:223], v[88:91]
	v_mfma_f32_16x16x32_bf16 v[76:79], v[156:159], v[228:231], v[76:79]
	v_mfma_f32_16x16x32_bf16 v[72:75], v[164:167], v[228:231], v[72:75]
	v_mfma_f32_16x16x32_bf16 v[124:127], v[160:163], v[208:211], v[124:127]
	v_mfma_f32_16x16x32_bf16 v[120:123], v[180:183], v[208:211], v[120:123]
	v_mfma_f32_16x16x32_bf16 v[108:111], v[160:163], v[216:219], v[108:111]
	v_mfma_f32_16x16x32_bf16 v[104:107], v[180:183], v[216:219], v[104:107]
	v_mfma_f32_16x16x32_bf16 v[92:95], v[160:163], v[224:227], v[92:95]
	v_mfma_f32_16x16x32_bf16 v[88:91], v[180:183], v[224:227], v[88:91]
	v_mfma_f32_16x16x32_bf16 v[76:79], v[160:163], v[232:235], v[76:79]
	v_mfma_f32_16x16x32_bf16 v[72:75], v[180:183], v[232:235], v[72:75]
	s_setprio 0
	s_setprio 1
	v_mfma_f32_16x16x32_bf16 v[116:119], v[184:187], v[204:207], v[116:119]
	v_mfma_f32_16x16x32_bf16 v[112:115], v[192:195], v[204:207], v[112:115]
	v_mfma_f32_16x16x32_bf16 v[100:103], v[184:187], v[212:215], v[100:103]
	v_mfma_f32_16x16x32_bf16 v[96:99], v[192:195], v[212:215], v[96:99]
	v_mfma_f32_16x16x32_bf16 v[84:87], v[184:187], v[220:223], v[84:87]
	v_mfma_f32_16x16x32_bf16 v[80:83], v[192:195], v[220:223], v[80:83]
	v_mfma_f32_16x16x32_bf16 v[68:71], v[184:187], v[228:231], v[68:71]
	v_mfma_f32_16x16x32_bf16 v[64:67], v[192:195], v[228:231], v[64:67]
	v_mfma_f32_16x16x32_bf16 v[116:119], v[188:191], v[208:211], v[116:119]
	v_mfma_f32_16x16x32_bf16 v[112:115], v[196:199], v[208:211], v[112:115]
	v_mfma_f32_16x16x32_bf16 v[100:103], v[188:191], v[216:219], v[100:103]
	v_mfma_f32_16x16x32_bf16 v[96:99], v[196:199], v[216:219], v[96:99]
	v_mfma_f32_16x16x32_bf16 v[84:87], v[188:191], v[224:227], v[84:87]
	v_mfma_f32_16x16x32_bf16 v[80:83], v[196:199], v[224:227], v[80:83]
	v_mfma_f32_16x16x32_bf16 v[68:71], v[188:191], v[232:235], v[68:71]
	v_mfma_f32_16x16x32_bf16 v[64:67], v[196:199], v[232:235], v[64:67]
	s_setprio 0
	s_barrier
	s_add_i32 s85, s85, s17
	v_lshl_add_u64 v[134:135], s[86:87], 0, v[144:145]
	s_mov_b32 m0, s85
	ds_read_b128 v[204:207], v141 offset:16384
	ds_read_b128 v[208:211], v141 offset:17408
	ds_read_b128 v[212:215], v141 offset:18432
	ds_read_b128 v[216:219], v141 offset:19456
	ds_read_b128 v[220:223], v141 offset:20480
	ds_read_b128 v[224:227], v141 offset:21504
	ds_read_b128 v[228:231], v141 offset:22528
	ds_read_b128 v[232:235], v141 offset:23552
	global_load_lds_dwordx4 v[134:135], off
	v_lshl_add_u64 v[142:143], v[134:135], 0, s[56:57]
	s_add_i32 m0, s85, 0x2000
	s_add_i32 s36, s36, s17
	global_load_lds_dwordx4 v[142:143], off
	v_lshl_add_u64 v[142:143], v[134:135], 0, s[54:55]
	s_mov_b32 m0, s36
	s_nop 0
	global_load_lds_dwordx4 v[142:143], off
	v_lshl_add_u64 v[142:143], v[134:135], 0, s[58:59]
	s_add_i32 m0, s36, 0x2000
	s_nop 0
	global_load_lds_dwordx4 v[142:143], off
	v_lshl_add_u64 v[142:143], s[72:73], 0, v[128:129]
	s_mov_b32 m0, s18
	v_lshl_add_u64 v[150:151], v[142:143], 0, s[56:57]
	global_load_lds_dwordx4 v[142:143], off
	s_mov_b32 m0, s19
	s_nop 0
	global_load_lds_dwordx4 v[150:151], off
	s_waitcnt vmcnt(8)
	s_waitcnt lgkmcnt(0)
	s_barrier
	s_setprio 1
	v_mfma_f32_16x16x32_bf16 v[60:63], v[156:159], v[204:207], v[60:63]
	v_mfma_f32_16x16x32_bf16 v[56:59], v[164:167], v[204:207], v[56:59]
	v_mfma_f32_16x16x32_bf16 v[44:47], v[156:159], v[212:215], v[44:47]
	v_mfma_f32_16x16x32_bf16 v[40:43], v[164:167], v[212:215], v[40:43]
	v_mfma_f32_16x16x32_bf16 v[28:31], v[156:159], v[220:223], v[28:31]
	v_mfma_f32_16x16x32_bf16 v[24:27], v[164:167], v[220:223], v[24:27]
	v_mfma_f32_16x16x32_bf16 v[12:15], v[156:159], v[228:231], v[12:15]
	v_mfma_f32_16x16x32_bf16 v[8:11], v[164:167], v[228:231], v[8:11]
	v_mfma_f32_16x16x32_bf16 v[60:63], v[160:163], v[208:211], v[60:63]
	v_mfma_f32_16x16x32_bf16 v[56:59], v[180:183], v[208:211], v[56:59]
	v_mfma_f32_16x16x32_bf16 v[44:47], v[160:163], v[216:219], v[44:47]
	v_mfma_f32_16x16x32_bf16 v[40:43], v[180:183], v[216:219], v[40:43]
	v_mfma_f32_16x16x32_bf16 v[28:31], v[160:163], v[224:227], v[28:31]
	v_mfma_f32_16x16x32_bf16 v[24:27], v[180:183], v[224:227], v[24:27]
	v_mfma_f32_16x16x32_bf16 v[12:15], v[160:163], v[232:235], v[12:15]
	v_mfma_f32_16x16x32_bf16 v[8:11], v[180:183], v[232:235], v[8:11]
	s_setprio 0
	s_setprio 1
	v_mfma_f32_16x16x32_bf16 v[52:55], v[184:187], v[204:207], v[52:55]
	v_mfma_f32_16x16x32_bf16 v[48:51], v[192:195], v[204:207], v[48:51]
	v_mfma_f32_16x16x32_bf16 v[36:39], v[184:187], v[212:215], v[36:39]
	v_mfma_f32_16x16x32_bf16 v[32:35], v[192:195], v[212:215], v[32:35]
	v_mfma_f32_16x16x32_bf16 v[20:23], v[184:187], v[220:223], v[20:23]
	v_mfma_f32_16x16x32_bf16 v[16:19], v[192:195], v[220:223], v[16:19]
	v_mfma_f32_16x16x32_bf16 v[4:7], v[184:187], v[228:231], v[4:7]
	v_mfma_f32_16x16x32_bf16 v[0:3], v[192:195], v[228:231], v[0:3]
	v_mfma_f32_16x16x32_bf16 v[52:55], v[188:191], v[208:211], v[52:55]
	v_mfma_f32_16x16x32_bf16 v[48:51], v[196:199], v[208:211], v[48:51]
	v_mfma_f32_16x16x32_bf16 v[36:39], v[188:191], v[216:219], v[36:39]
	v_mfma_f32_16x16x32_bf16 v[32:35], v[196:199], v[216:219], v[32:35]
	v_mfma_f32_16x16x32_bf16 v[20:23], v[188:191], v[224:227], v[20:23]
	v_mfma_f32_16x16x32_bf16 v[16:19], v[196:199], v[224:227], v[16:19]
	v_mfma_f32_16x16x32_bf16 v[4:7], v[188:191], v[232:235], v[4:7]
	v_mfma_f32_16x16x32_bf16 v[0:3], v[196:199], v[232:235], v[0:3]
	s_setprio 0
	s_barrier
	s_add_i32 s36, 0, 0x18000
	v_add_u32_e32 v132, s36, v137
	s_add_i32 s72, 0, 0x1c000
	ds_read_b128 v[156:159], v132
	ds_read_b128 v[160:163], v132 offset:1024
	ds_read_b128 v[164:167], v132 offset:2048
	ds_read_b128 v[180:183], v132 offset:3072
	v_add_u32_e32 v132, s72, v137
	ds_read_b128 v[184:187], v132
	ds_read_b128 v[188:191], v132 offset:1024
	ds_read_b128 v[192:195], v132 offset:2048
	ds_read_b128 v[196:199], v132 offset:3072
	s_mov_b32 m0, s20
	v_lshl_add_u64 v[150:151], v[142:143], 0, s[54:55]
	ds_read_b128 v[204:207], v141 offset:32768
	ds_read_b128 v[208:211], v141 offset:33792
	ds_read_b128 v[212:215], v141 offset:34816
	ds_read_b128 v[216:219], v141 offset:35840
	ds_read_b128 v[220:223], v141 offset:36864
	ds_read_b128 v[224:227], v141 offset:37888
	ds_read_b128 v[228:231], v141 offset:38912
	ds_read_b128 v[232:235], v141 offset:39936
	global_load_lds_dwordx4 v[150:151], off
	v_lshl_add_u64 v[150:151], v[142:143], 0, s[58:59]
	s_mov_b32 m0, s21
	s_nop 0
	global_load_lds_dwordx4 v[150:151], off
	s_waitcnt vmcnt(8)
	s_waitcnt lgkmcnt(0)
	s_barrier
	s_setprio 1
	v_mfma_f32_16x16x32_bf16 v[124:127], v[156:159], v[204:207], v[124:127]
	v_mfma_f32_16x16x32_bf16 v[120:123], v[164:167], v[204:207], v[120:123]
	v_mfma_f32_16x16x32_bf16 v[108:111], v[156:159], v[212:215], v[108:111]
	v_mfma_f32_16x16x32_bf16 v[104:107], v[164:167], v[212:215], v[104:107]
	v_mfma_f32_16x16x32_bf16 v[92:95], v[156:159], v[220:223], v[92:95]
	v_mfma_f32_16x16x32_bf16 v[88:91], v[164:167], v[220:223], v[88:91]
	v_mfma_f32_16x16x32_bf16 v[76:79], v[156:159], v[228:231], v[76:79]
	v_mfma_f32_16x16x32_bf16 v[72:75], v[164:167], v[228:231], v[72:75]
	v_mfma_f32_16x16x32_bf16 v[124:127], v[160:163], v[208:211], v[124:127]
	v_mfma_f32_16x16x32_bf16 v[120:123], v[180:183], v[208:211], v[120:123]
	v_mfma_f32_16x16x32_bf16 v[108:111], v[160:163], v[216:219], v[108:111]
	v_mfma_f32_16x16x32_bf16 v[104:107], v[180:183], v[216:219], v[104:107]
	v_mfma_f32_16x16x32_bf16 v[92:95], v[160:163], v[224:227], v[92:95]
	v_mfma_f32_16x16x32_bf16 v[88:91], v[180:183], v[224:227], v[88:91]
	v_mfma_f32_16x16x32_bf16 v[76:79], v[160:163], v[232:235], v[76:79]
	v_mfma_f32_16x16x32_bf16 v[72:75], v[180:183], v[232:235], v[72:75]
	s_setprio 0
	s_setprio 1
	v_mfma_f32_16x16x32_bf16 v[116:119], v[184:187], v[204:207], v[116:119]
	v_mfma_f32_16x16x32_bf16 v[112:115], v[192:195], v[204:207], v[112:115]
	v_mfma_f32_16x16x32_bf16 v[100:103], v[184:187], v[212:215], v[100:103]
	v_mfma_f32_16x16x32_bf16 v[96:99], v[192:195], v[212:215], v[96:99]
	v_mfma_f32_16x16x32_bf16 v[84:87], v[184:187], v[220:223], v[84:87]
	v_mfma_f32_16x16x32_bf16 v[80:83], v[192:195], v[220:223], v[80:83]
	v_mfma_f32_16x16x32_bf16 v[68:71], v[184:187], v[228:231], v[68:71]
	v_mfma_f32_16x16x32_bf16 v[64:67], v[192:195], v[228:231], v[64:67]
	v_mfma_f32_16x16x32_bf16 v[116:119], v[188:191], v[208:211], v[116:119]
	v_mfma_f32_16x16x32_bf16 v[112:115], v[196:199], v[208:211], v[112:115]
	v_mfma_f32_16x16x32_bf16 v[100:103], v[188:191], v[216:219], v[100:103]
	v_mfma_f32_16x16x32_bf16 v[96:99], v[196:199], v[216:219], v[96:99]
	v_mfma_f32_16x16x32_bf16 v[84:87], v[188:191], v[224:227], v[84:87]
	v_mfma_f32_16x16x32_bf16 v[80:83], v[196:199], v[224:227], v[80:83]
	v_mfma_f32_16x16x32_bf16 v[68:71], v[188:191], v[232:235], v[68:71]
	v_mfma_f32_16x16x32_bf16 v[64:67], v[196:199], v[232:235], v[64:67]
	s_setprio 0
	s_barrier
	s_add_i32 s36, s36, s17
	v_lshl_add_u64 v[150:151], v[134:135], 0, s[60:61]
	s_mov_b32 m0, s36
	ds_read_b128 v[204:207], v141 offset:49152
	ds_read_b128 v[208:211], v141 offset:50176
	ds_read_b128 v[212:215], v141 offset:51200
	ds_read_b128 v[216:219], v141 offset:52224
	ds_read_b128 v[220:223], v141 offset:53248
	ds_read_b128 v[224:227], v141 offset:54272
	ds_read_b128 v[228:231], v141 offset:55296
	ds_read_b128 v[232:235], v141 offset:56320
	global_load_lds_dwordx4 v[150:151], off
	v_lshl_add_u64 v[150:151], v[134:135], 0, s[62:63]
	s_add_i32 m0, s36, 0x2000
	s_add_i32 s36, s72, s17
	global_load_lds_dwordx4 v[150:151], off
	v_lshl_add_u64 v[150:151], v[134:135], 0, s[64:65]
	s_mov_b32 m0, s36
	v_lshl_add_u64 v[134:135], v[134:135], 0, s[66:67]
	global_load_lds_dwordx4 v[150:151], off
	s_add_i32 m0, s36, 0x2000
	s_nop 0
	global_load_lds_dwordx4 v[134:135], off
	v_lshl_add_u64 v[134:135], v[142:143], 0, s[60:61]
	s_mov_b32 m0, s22
	s_nop 0
	global_load_lds_dwordx4 v[134:135], off
	v_lshl_add_u64 v[134:135], v[142:143], 0, s[62:63]
	s_mov_b32 m0, s23
	s_nop 0
	global_load_lds_dwordx4 v[134:135], off
	s_waitcnt vmcnt(8)
	s_waitcnt lgkmcnt(0)
	s_barrier
	s_setprio 1
	v_mfma_f32_16x16x32_bf16 v[60:63], v[156:159], v[204:207], v[60:63]
	v_mfma_f32_16x16x32_bf16 v[56:59], v[164:167], v[204:207], v[56:59]
	v_mfma_f32_16x16x32_bf16 v[44:47], v[156:159], v[212:215], v[44:47]
	v_mfma_f32_16x16x32_bf16 v[40:43], v[164:167], v[212:215], v[40:43]
	v_mfma_f32_16x16x32_bf16 v[28:31], v[156:159], v[220:223], v[28:31]
	v_mfma_f32_16x16x32_bf16 v[24:27], v[164:167], v[220:223], v[24:27]
	v_mfma_f32_16x16x32_bf16 v[12:15], v[156:159], v[228:231], v[12:15]
	v_mfma_f32_16x16x32_bf16 v[8:11], v[164:167], v[228:231], v[8:11]
	v_mfma_f32_16x16x32_bf16 v[60:63], v[160:163], v[208:211], v[60:63]
	v_mfma_f32_16x16x32_bf16 v[56:59], v[180:183], v[208:211], v[56:59]
	v_mfma_f32_16x16x32_bf16 v[44:47], v[160:163], v[216:219], v[44:47]
	v_mfma_f32_16x16x32_bf16 v[40:43], v[180:183], v[216:219], v[40:43]
	v_mfma_f32_16x16x32_bf16 v[28:31], v[160:163], v[224:227], v[28:31]
	v_mfma_f32_16x16x32_bf16 v[24:27], v[180:183], v[224:227], v[24:27]
	v_mfma_f32_16x16x32_bf16 v[12:15], v[160:163], v[232:235], v[12:15]
	v_mfma_f32_16x16x32_bf16 v[8:11], v[180:183], v[232:235], v[8:11]
	s_setprio 0
	s_setprio 1
	v_mfma_f32_16x16x32_bf16 v[52:55], v[184:187], v[204:207], v[52:55]
	v_mfma_f32_16x16x32_bf16 v[48:51], v[192:195], v[204:207], v[48:51]
	v_mfma_f32_16x16x32_bf16 v[36:39], v[184:187], v[212:215], v[36:39]
	v_mfma_f32_16x16x32_bf16 v[32:35], v[192:195], v[212:215], v[32:35]
	v_mfma_f32_16x16x32_bf16 v[20:23], v[184:187], v[220:223], v[20:23]
	v_mfma_f32_16x16x32_bf16 v[16:19], v[192:195], v[220:223], v[16:19]
	v_mfma_f32_16x16x32_bf16 v[4:7], v[184:187], v[228:231], v[4:7]
	v_mfma_f32_16x16x32_bf16 v[0:3], v[192:195], v[228:231], v[0:3]
	v_mfma_f32_16x16x32_bf16 v[52:55], v[188:191], v[208:211], v[52:55]
	v_mfma_f32_16x16x32_bf16 v[48:51], v[196:199], v[208:211], v[48:51]
	v_mfma_f32_16x16x32_bf16 v[36:39], v[188:191], v[216:219], v[36:39]
	v_mfma_f32_16x16x32_bf16 v[32:35], v[196:199], v[216:219], v[32:35]
	v_mfma_f32_16x16x32_bf16 v[20:23], v[188:191], v[224:227], v[20:23]
	v_mfma_f32_16x16x32_bf16 v[16:19], v[196:199], v[224:227], v[16:19]
	v_mfma_f32_16x16x32_bf16 v[4:7], v[188:191], v[232:235], v[4:7]
	v_mfma_f32_16x16x32_bf16 v[0:3], v[196:199], v[232:235], v[0:3]
	s_setprio 0
	s_barrier
	s_add_i32 s81, s81, 2
	s_add_u32 s70, s70, 0x100
	s_addc_u32 s71, s71, 0
	s_add_u32 s75, s75, 0x100
	s_addc_u32 s77, s77, 0
	s_cmp_gt_u32 s81, 61
	s_cbranch_scc0 .LBB0_333
	s_and_b64 vcc, exec, s[4:5]
	s_movk_i32 s77, 0x7fff
	s_cbranch_vccz .LBB0_336
	s_barrier

.LBB0_486:
	s_lshl_b32 s18, s92, 7
	s_and_b32 s18, s18, 0xffffff00
	s_ashr_i32 s71, s70, 31
	s_ashr_i32 s19, s18, 31
	s_lshl_b64 s[20:21], s[70:71], 21
	s_add_u32 s20, s4, s20
	s_addc_u32 s21, s5, s21
	s_lshl_b64 s[18:19], s[18:19], 1
	s_add_u32 s74, s20, s18
	s_addc_u32 s75, s21, s19
	s_and_b64 s[18:19], s[2:3], exec
	s_cselect_b32 vcc_hi, s75, s7
	s_cselect_b32 vcc_lo, s74, s6
	s_ashr_i32 s93, s92, 31
	s_lshl_b64 s[18:19], s[92:93], 17
	s_add_u32 s72, s37, s18
	s_addc_u32 s73, s38, s19
	s_and_b64 s[18:19], s[2:3], exec
	s_cselect_b32 s77, s73, s69
	s_cselect_b32 s76, s72, s68
	s_add_i32 s21, 0, 0x10000
	s_add_i32 s22, 0, 0x14000
	v_add_u32_e32 v152, s21, v179
	v_add_u32_e32 v153, s22, v179
	ds_read_b128 v[2:5], v152
	ds_read_b128 v[6:9], v152 offset:1024
	ds_read_b128 v[10:13], v152 offset:2048
	ds_read_b128 v[14:17], v152 offset:3072
	ds_read_b128 v[18:21], v153
	ds_read_b128 v[22:25], v153 offset:1024
	ds_read_b128 v[26:29], v153 offset:2048
	ds_read_b128 v[30:33], v153 offset:3072
	v_lshl_add_u64 v[0:1], s[6:7], 0, v[156:157]
	s_add_i32 s20, s79, 0xc000
	v_lshl_add_u64 v[66:67], v[0:1], 0, s[64:65]
	s_mov_b32 m0, s20
	s_add_i32 s6, s79, 0xe000
	ds_read_b128 v[34:37], v181
	ds_read_b128 v[38:41], v181 offset:1024
	ds_read_b128 v[42:45], v181 offset:2048
	ds_read_b128 v[46:49], v181 offset:3072
	ds_read_b128 v[50:53], v181 offset:4096
	ds_read_b128 v[54:57], v181 offset:5120
	ds_read_b128 v[58:61], v181 offset:6144
	ds_read_b128 v[62:65], v181 offset:7168
	global_load_lds_dwordx4 v[66:67], off
	v_lshl_add_u64 v[66:67], v[0:1], 0, s[66:67]
	s_mov_b32 m0, s6
	s_nop 0
	global_load_lds_dwordx4 v[66:67], off
	s_waitcnt vmcnt(8)
	s_waitcnt lgkmcnt(0)
	s_barrier
	s_setprio 1
	v_mfma_f32_16x16x32_bf16 v[66:69], v[2:5], v[34:37], 0
	v_mfma_f32_16x16x32_bf16 v[70:73], v[10:13], v[34:37], 0
	v_mfma_f32_16x16x32_bf16 v[74:77], v[2:5], v[42:45], 0
	v_mfma_f32_16x16x32_bf16 v[78:81], v[10:13], v[42:45], 0
	s_waitcnt vmcnt(0)
	v_mfma_f32_16x16x32_bf16 v[82:85], v[2:5], v[50:53], 0
	v_mfma_f32_16x16x32_bf16 v[86:89], v[10:13], v[50:53], 0
	v_mfma_f32_16x16x32_bf16 v[90:93], v[2:5], v[58:61], 0
	v_mfma_f32_16x16x32_bf16 v[94:97], v[10:13], v[58:61], 0
	v_mfma_f32_16x16x32_bf16 v[66:69], v[6:9], v[38:41], v[66:69]
	v_mfma_f32_16x16x32_bf16 v[70:73], v[14:17], v[38:41], v[70:73]
	v_mfma_f32_16x16x32_bf16 v[74:77], v[6:9], v[46:49], v[74:77]
	v_mfma_f32_16x16x32_bf16 v[78:81], v[14:17], v[46:49], v[78:81]
	v_mfma_f32_16x16x32_bf16 v[82:85], v[6:9], v[54:57], v[82:85]
	v_mfma_f32_16x16x32_bf16 v[86:89], v[14:17], v[54:57], v[86:89]
	v_mfma_f32_16x16x32_bf16 v[90:93], v[6:9], v[62:65], v[90:93]
	v_mfma_f32_16x16x32_bf16 v[94:97], v[14:17], v[62:65], v[94:97]
	s_setprio 0
	s_setprio 1
	v_mfma_f32_16x16x32_bf16 v[98:101], v[18:21], v[34:37], 0
	v_mfma_f32_16x16x32_bf16 v[34:37], v[26:29], v[34:37], 0
	v_mfma_f32_16x16x32_bf16 v[98:101], v[22:25], v[38:41], v[98:101]
	v_mfma_f32_16x16x32_bf16 v[34:37], v[30:33], v[38:41], v[34:37]
	v_mfma_f32_16x16x32_bf16 v[38:41], v[18:21], v[42:45], 0
	v_mfma_f32_16x16x32_bf16 v[42:45], v[26:29], v[42:45], 0
	v_mfma_f32_16x16x32_bf16 v[38:41], v[22:25], v[46:49], v[38:41]
	v_mfma_f32_16x16x32_bf16 v[42:45], v[30:33], v[46:49], v[42:45]
	v_mfma_f32_16x16x32_bf16 v[46:49], v[18:21], v[50:53], 0
	v_mfma_f32_16x16x32_bf16 v[50:53], v[26:29], v[50:53], 0
	v_mfma_f32_16x16x32_bf16 v[46:49], v[22:25], v[54:57], v[46:49]
	v_mfma_f32_16x16x32_bf16 v[50:53], v[30:33], v[54:57], v[50:53]
	v_mfma_f32_16x16x32_bf16 v[54:57], v[18:21], v[58:61], 0
	v_mfma_f32_16x16x32_bf16 v[58:61], v[26:29], v[58:61], 0
	v_mfma_f32_16x16x32_bf16 v[54:57], v[22:25], v[62:65], v[54:57]
	v_mfma_f32_16x16x32_bf16 v[58:61], v[30:33], v[62:65], v[58:61]
	s_setprio 0
	s_barrier
	v_lshl_add_u64 v[142:143], s[68:69], 0, v[144:145]
	s_mov_b64 s[44:45], 0x100
	s_add_i32 s21, s21, s39
	v_lshl_add_u64 v[130:131], v[142:143], 0, s[44:45]
	s_mov_b32 m0, s21
	s_mov_b64 s[18:19], 0x8100
	s_add_i32 s7, s21, 0x2000
	ds_read_b128 v[62:65], v181 offset:16384
	ds_read_b128 v[102:105], v181 offset:17408
	ds_read_b128 v[106:109], v181 offset:18432
	ds_read_b128 v[110:113], v181 offset:19456
	ds_read_b128 v[114:117], v181 offset:20480
	ds_read_b128 v[118:121], v181 offset:21504
	ds_read_b128 v[122:125], v181 offset:22528
	ds_read_b128 v[126:129], v181 offset:23552
	global_load_lds_dwordx4 v[130:131], off
	v_lshl_add_u64 v[130:131], v[142:143], 0, s[18:19]
	s_mov_b32 m0, s7
	s_mov_b64 s[18:19], 0x10100
	global_load_lds_dwordx4 v[130:131], off
	v_lshl_add_u64 v[130:131], v[142:143], 0, s[18:19]
	s_add_i32 s18, s22, s39
	s_mov_b32 m0, s18
	s_mov_b64 s[22:23], 0x18100
	s_add_i32 s19, s18, 0x2000
	global_load_lds_dwordx4 v[130:131], off
	v_lshl_add_u64 v[130:131], v[142:143], 0, s[22:23]
	s_mov_b32 m0, s19
	s_mov_b64 s[22:23], 0x80100
	global_load_lds_dwordx4 v[130:131], off
	v_lshl_add_u64 v[130:131], v[0:1], 0, s[44:45]
	s_mov_b32 m0, s79
	s_nop 0
	global_load_lds_dwordx4 v[130:131], off
	v_lshl_add_u64 v[130:131], v[0:1], 0, s[22:23]
	s_mov_b32 m0, s42
	s_nop 0
	global_load_lds_dwordx4 v[130:131], off
	s_waitcnt vmcnt(8)
	s_waitcnt lgkmcnt(0)
	s_barrier
	s_setprio 1
	v_mfma_f32_16x16x32_bf16 v[130:133], v[2:5], v[62:65], 0
	v_mfma_f32_16x16x32_bf16 v[138:141], v[2:5], v[106:109], 0
	v_mfma_f32_16x16x32_bf16 v[162:165], v[2:5], v[114:117], 0
	v_mfma_f32_16x16x32_bf16 v[2:5], v[2:5], v[122:125], 0
	v_mfma_f32_16x16x32_bf16 v[130:133], v[6:9], v[102:105], v[130:133]
	v_mfma_f32_16x16x32_bf16 v[134:137], v[10:13], v[62:65], 0
	v_mfma_f32_16x16x32_bf16 v[138:141], v[6:9], v[110:113], v[138:141]
	v_mfma_f32_16x16x32_bf16 v[162:165], v[6:9], v[118:121], v[162:165]
	v_mfma_f32_16x16x32_bf16 v[2:5], v[6:9], v[126:129], v[2:5]
	v_mfma_f32_16x16x32_bf16 v[6:9], v[10:13], v[122:125], 0
	v_mfma_f32_16x16x32_bf16 v[134:137], v[14:17], v[102:105], v[134:137]
	v_mfma_f32_16x16x32_bf16 v[158:161], v[10:13], v[106:109], 0
	v_mfma_f32_16x16x32_bf16 v[166:169], v[10:13], v[114:117], 0
	v_mfma_f32_16x16x32_bf16 v[6:9], v[14:17], v[126:129], v[6:9]
	v_mfma_f32_16x16x32_bf16 v[158:161], v[14:17], v[110:113], v[158:161]
	v_mfma_f32_16x16x32_bf16 v[166:169], v[14:17], v[118:121], v[166:169]
	s_setprio 0
	s_setprio 1
	v_mfma_f32_16x16x32_bf16 v[10:13], v[18:21], v[62:65], 0
	v_mfma_f32_16x16x32_bf16 v[14:17], v[26:29], v[62:65], 0
	v_mfma_f32_16x16x32_bf16 v[10:13], v[22:25], v[102:105], v[10:13]
	v_mfma_f32_16x16x32_bf16 v[14:17], v[30:33], v[102:105], v[14:17]
	v_mfma_f32_16x16x32_bf16 v[62:65], v[18:21], v[106:109], 0
	v_mfma_f32_16x16x32_bf16 v[102:105], v[26:29], v[106:109], 0
	v_mfma_f32_16x16x32_bf16 v[106:109], v[18:21], v[114:117], 0
	v_mfma_f32_16x16x32_bf16 v[18:21], v[18:21], v[122:125], 0
	v_mfma_f32_16x16x32_bf16 v[62:65], v[22:25], v[110:113], v[62:65]
	v_mfma_f32_16x16x32_bf16 v[102:105], v[30:33], v[110:113], v[102:105]
	v_mfma_f32_16x16x32_bf16 v[106:109], v[22:25], v[118:121], v[106:109]
	v_mfma_f32_16x16x32_bf16 v[110:113], v[26:29], v[114:117], 0
	v_mfma_f32_16x16x32_bf16 v[18:21], v[22:25], v[126:129], v[18:21]
	v_mfma_f32_16x16x32_bf16 v[22:25], v[26:29], v[122:125], 0
	v_mfma_f32_16x16x32_bf16 v[110:113], v[30:33], v[118:121], v[110:113]
	v_mfma_f32_16x16x32_bf16 v[22:25], v[30:33], v[126:129], v[22:25]
	s_setprio 0
	s_barrier
	s_add_i32 s69, 0, 0x18000
	s_add_i32 s36, 0, 0x1c000
	v_add_u32_e32 v174, s69, v179
	v_add_u32_e32 v175, s36, v179
	ds_read_b128 v[26:29], v174
	ds_read_b128 v[30:33], v174 offset:1024
	ds_read_b128 v[114:117], v174 offset:2048
	ds_read_b128 v[118:121], v174 offset:3072
	ds_read_b128 v[122:125], v175
	ds_read_b128 v[126:129], v175 offset:1024
	ds_read_b128 v[182:185], v175 offset:2048
	ds_read_b128 v[186:189], v175 offset:3072
	s_mov_b64 s[22:23], 0x100100
	s_mov_b32 m0, s43
	v_lshl_add_u64 v[150:151], v[0:1], 0, s[22:23]
	s_mov_b64 s[22:23], 0x180100
	ds_read_b128 v[190:193], v181 offset:32768
	ds_read_b128 v[194:197], v181 offset:33792
	ds_read_b128 v[204:207], v181 offset:34816
	ds_read_b128 v[208:211], v181 offset:35840
	ds_read_b128 v[212:215], v181 offset:36864
	ds_read_b128 v[216:219], v181 offset:37888
	ds_read_b128 v[220:223], v181 offset:38912
	ds_read_b128 v[224:227], v181 offset:39936
	global_load_lds_dwordx4 v[150:151], off
	v_lshl_add_u64 v[150:151], v[0:1], 0, s[22:23]
	s_mov_b32 m0, s96
	s_nop 0
	global_load_lds_dwordx4 v[150:151], off
	s_waitcnt vmcnt(8)
	s_waitcnt lgkmcnt(0)
	s_barrier
	s_setprio 1
	v_mfma_f32_16x16x32_bf16 v[66:69], v[26:29], v[190:193], v[66:69]
	v_mfma_f32_16x16x32_bf16 v[70:73], v[114:117], v[190:193], v[70:73]
	v_mfma_f32_16x16x32_bf16 v[74:77], v[26:29], v[204:207], v[74:77]
	v_mfma_f32_16x16x32_bf16 v[78:81], v[114:117], v[204:207], v[78:81]
	v_mfma_f32_16x16x32_bf16 v[82:85], v[26:29], v[212:215], v[82:85]
	v_mfma_f32_16x16x32_bf16 v[86:89], v[114:117], v[212:215], v[86:89]
	v_mfma_f32_16x16x32_bf16 v[90:93], v[26:29], v[220:223], v[90:93]
	v_mfma_f32_16x16x32_bf16 v[94:97], v[114:117], v[220:223], v[94:97]
	v_mfma_f32_16x16x32_bf16 v[66:69], v[30:33], v[194:197], v[66:69]
	v_mfma_f32_16x16x32_bf16 v[70:73], v[118:121], v[194:197], v[70:73]
	v_mfma_f32_16x16x32_bf16 v[74:77], v[30:33], v[208:211], v[74:77]
	v_mfma_f32_16x16x32_bf16 v[78:81], v[118:121], v[208:211], v[78:81]
	v_mfma_f32_16x16x32_bf16 v[82:85], v[30:33], v[216:219], v[82:85]
	v_mfma_f32_16x16x32_bf16 v[86:89], v[118:121], v[216:219], v[86:89]
	v_mfma_f32_16x16x32_bf16 v[90:93], v[30:33], v[224:227], v[90:93]
	v_mfma_f32_16x16x32_bf16 v[94:97], v[118:121], v[224:227], v[94:97]
	s_setprio 0
	s_setprio 1
	v_mfma_f32_16x16x32_bf16 v[98:101], v[122:125], v[190:193], v[98:101]
	v_mfma_f32_16x16x32_bf16 v[34:37], v[182:185], v[190:193], v[34:37]
	v_mfma_f32_16x16x32_bf16 v[38:41], v[122:125], v[204:207], v[38:41]
	v_mfma_f32_16x16x32_bf16 v[42:45], v[182:185], v[204:207], v[42:45]
	v_mfma_f32_16x16x32_bf16 v[46:49], v[122:125], v[212:215], v[46:49]
	v_mfma_f32_16x16x32_bf16 v[50:53], v[182:185], v[212:215], v[50:53]
	v_mfma_f32_16x16x32_bf16 v[54:57], v[122:125], v[220:223], v[54:57]
	v_mfma_f32_16x16x32_bf16 v[58:61], v[182:185], v[220:223], v[58:61]
	v_mfma_f32_16x16x32_bf16 v[98:101], v[126:129], v[194:197], v[98:101]
	v_mfma_f32_16x16x32_bf16 v[34:37], v[186:189], v[194:197], v[34:37]
	v_mfma_f32_16x16x32_bf16 v[38:41], v[126:129], v[208:211], v[38:41]
	v_mfma_f32_16x16x32_bf16 v[42:45], v[186:189], v[208:211], v[42:45]
	v_mfma_f32_16x16x32_bf16 v[46:49], v[126:129], v[216:219], v[46:49]
	v_mfma_f32_16x16x32_bf16 v[50:53], v[186:189], v[216:219], v[50:53]
	v_mfma_f32_16x16x32_bf16 v[54:57], v[126:129], v[224:227], v[54:57]
	v_mfma_f32_16x16x32_bf16 v[58:61], v[186:189], v[224:227], v[58:61]
	s_setprio 0
	s_barrier
	s_mov_b64 s[30:31], 0x180
	s_add_i32 s69, s69, s39
	v_lshl_add_u64 v[150:151], v[142:143], 0, s[30:31]
	s_mov_b32 m0, s69
	s_mov_b64 s[22:23], 0x8180
	ds_read_b128 v[190:193], v181 offset:49152
	ds_read_b128 v[194:197], v181 offset:50176
	ds_read_b128 v[204:207], v181 offset:51200
	ds_read_b128 v[208:211], v181 offset:52224
	ds_read_b128 v[212:215], v181 offset:53248
	ds_read_b128 v[216:219], v181 offset:54272
	ds_read_b128 v[220:223], v181 offset:55296
	ds_read_b128 v[224:227], v181 offset:56320
	global_load_lds_dwordx4 v[150:151], off
	v_lshl_add_u64 v[150:151], v[142:143], 0, s[22:23]
	s_add_i32 s22, s69, 0x2000
	s_mov_b32 m0, s22
	s_mov_b64 s[44:45], 0x10180
	s_add_i32 s23, s36, s39
	global_load_lds_dwordx4 v[150:151], off
	v_lshl_add_u64 v[150:151], v[142:143], 0, s[44:45]
	s_mov_b32 m0, s23
	s_mov_b64 s[44:45], 0x18180
	s_add_i32 s68, s23, 0x2000
	global_load_lds_dwordx4 v[150:151], off
	v_lshl_add_u64 v[142:143], v[142:143], 0, s[44:45]
	s_mov_b32 m0, s68
	s_mov_b64 s[44:45], 0x80180
	global_load_lds_dwordx4 v[142:143], off
	v_lshl_add_u64 v[142:143], v[0:1], 0, s[30:31]
	s_mov_b32 m0, s40
	s_nop 0
	global_load_lds_dwordx4 v[142:143], off
	v_lshl_add_u64 v[142:143], v[0:1], 0, s[44:45]
	s_mov_b32 m0, s16
	s_nop 0
	global_load_lds_dwordx4 v[142:143], off
	s_waitcnt vmcnt(8)
	s_waitcnt lgkmcnt(0)
	s_barrier
	s_setprio 1
	v_mfma_f32_16x16x32_bf16 v[130:133], v[26:29], v[190:193], v[130:133]
	v_mfma_f32_16x16x32_bf16 v[134:137], v[114:117], v[190:193], v[134:137]
	v_mfma_f32_16x16x32_bf16 v[138:141], v[26:29], v[204:207], v[138:141]
	v_mfma_f32_16x16x32_bf16 v[2:5], v[26:29], v[220:223], v[2:5]
	v_mfma_f32_16x16x32_bf16 v[6:9], v[114:117], v[220:223], v[6:9]
	v_mfma_f32_16x16x32_bf16 v[130:133], v[30:33], v[194:197], v[130:133]
	v_mfma_f32_16x16x32_bf16 v[134:137], v[118:121], v[194:197], v[134:137]
	v_mfma_f32_16x16x32_bf16 v[138:141], v[30:33], v[208:211], v[138:141]
	v_mfma_f32_16x16x32_bf16 v[158:161], v[114:117], v[204:207], v[158:161]
	v_mfma_f32_16x16x32_bf16 v[162:165], v[26:29], v[212:215], v[162:165]
	v_mfma_f32_16x16x32_bf16 v[166:169], v[114:117], v[212:215], v[166:169]
	v_mfma_f32_16x16x32_bf16 v[2:5], v[30:33], v[224:227], v[2:5]
	v_mfma_f32_16x16x32_bf16 v[6:9], v[118:121], v[224:227], v[6:9]
	v_mfma_f32_16x16x32_bf16 v[158:161], v[118:121], v[208:211], v[158:161]
	v_mfma_f32_16x16x32_bf16 v[162:165], v[30:33], v[216:219], v[162:165]
	v_mfma_f32_16x16x32_bf16 v[166:169], v[118:121], v[216:219], v[166:169]
	s_setprio 0
	s_setprio 1
	v_mfma_f32_16x16x32_bf16 v[10:13], v[122:125], v[190:193], v[10:13]
	v_mfma_f32_16x16x32_bf16 v[14:17], v[182:185], v[190:193], v[14:17]
	v_mfma_f32_16x16x32_bf16 v[26:29], v[122:125], v[204:207], v[62:65]
	v_mfma_f32_16x16x32_bf16 v[30:33], v[182:185], v[204:207], v[102:105]
	v_mfma_f32_16x16x32_bf16 v[62:65], v[122:125], v[212:215], v[106:109]
	v_mfma_f32_16x16x32_bf16 v[102:105], v[182:185], v[212:215], v[110:113]
	v_mfma_f32_16x16x32_bf16 v[18:21], v[122:125], v[220:223], v[18:21]
	v_mfma_f32_16x16x32_bf16 v[22:25], v[182:185], v[220:223], v[22:25]
	v_mfma_f32_16x16x32_bf16 v[10:13], v[126:129], v[194:197], v[10:13]
	v_mfma_f32_16x16x32_bf16 v[14:17], v[186:189], v[194:197], v[14:17]
	v_mfma_f32_16x16x32_bf16 v[26:29], v[126:129], v[208:211], v[26:29]
	v_mfma_f32_16x16x32_bf16 v[30:33], v[186:189], v[208:211], v[30:33]
	v_mfma_f32_16x16x32_bf16 v[62:65], v[126:129], v[216:219], v[62:65]
	v_mfma_f32_16x16x32_bf16 v[102:105], v[186:189], v[216:219], v[102:105]
	v_mfma_f32_16x16x32_bf16 v[18:21], v[126:129], v[224:227], v[18:21]
	v_mfma_f32_16x16x32_bf16 v[22:25], v[186:189], v[224:227], v[22:25]
	s_setprio 0
	s_barrier
	ds_read_b128 v[106:109], v152
	ds_read_b128 v[110:113], v152 offset:1024
	ds_read_b128 v[114:117], v152 offset:2048
	ds_read_b128 v[118:121], v152 offset:3072
	ds_read_b128 v[122:125], v153
	ds_read_b128 v[126:129], v153 offset:1024
	ds_read_b128 v[182:185], v153 offset:2048
	ds_read_b128 v[186:189], v153 offset:3072
	s_mov_b64 s[44:45], 0x100180
	s_mov_b32 m0, s20
	v_lshl_add_u64 v[142:143], v[0:1], 0, s[44:45]
	s_mov_b64 s[44:45], 0x180180
	ds_read_b128 v[190:193], v181
	ds_read_b128 v[194:197], v181 offset:1024
	ds_read_b128 v[204:207], v181 offset:2048
	ds_read_b128 v[208:211], v181 offset:3072
	ds_read_b128 v[212:215], v181 offset:4096
	ds_read_b128 v[216:219], v181 offset:5120
	ds_read_b128 v[220:223], v181 offset:6144
	ds_read_b128 v[224:227], v181 offset:7168
	global_load_lds_dwordx4 v[142:143], off
	v_lshl_add_u64 v[0:1], v[0:1], 0, s[44:45]
	s_mov_b32 m0, s6
	s_nop 0
	global_load_lds_dwordx4 v[0:1], off
	s_waitcnt vmcnt(8)
	s_waitcnt lgkmcnt(0)
	s_barrier
	s_setprio 1
	v_mfma_f32_16x16x32_bf16 v[90:93], v[106:109], v[220:223], v[90:93]
	v_mfma_f32_16x16x32_bf16 v[66:69], v[106:109], v[190:193], v[66:69]
	v_mfma_f32_16x16x32_bf16 v[70:73], v[114:117], v[190:193], v[70:73]
	v_mfma_f32_16x16x32_bf16 v[74:77], v[106:109], v[204:207], v[74:77]
	v_mfma_f32_16x16x32_bf16 v[78:81], v[114:117], v[204:207], v[78:81]
	v_mfma_f32_16x16x32_bf16 v[82:85], v[106:109], v[212:215], v[82:85]
	v_mfma_f32_16x16x32_bf16 v[86:89], v[114:117], v[212:215], v[86:89]
	v_mfma_f32_16x16x32_bf16 v[228:231], v[110:113], v[224:227], v[90:93]
	v_mfma_f32_16x16x32_bf16 v[90:93], v[114:117], v[220:223], v[94:97]
	v_mfma_f32_16x16x32_bf16 v[66:69], v[110:113], v[194:197], v[66:69]
	v_mfma_f32_16x16x32_bf16 v[70:73], v[118:121], v[194:197], v[70:73]
	v_mfma_f32_16x16x32_bf16 v[74:77], v[110:113], v[208:211], v[74:77]
	v_mfma_f32_16x16x32_bf16 v[78:81], v[118:121], v[208:211], v[78:81]
	v_mfma_f32_16x16x32_bf16 v[82:85], v[110:113], v[216:219], v[82:85]
	v_mfma_f32_16x16x32_bf16 v[86:89], v[118:121], v[216:219], v[86:89]
	v_mfma_f32_16x16x32_bf16 v[92:95], v[118:121], v[224:227], v[90:93]
	s_setprio 0
	s_setprio 1
	v_mfma_f32_16x16x32_bf16 v[34:37], v[182:185], v[190:193], v[34:37]
	v_mfma_f32_16x16x32_bf16 v[38:41], v[122:125], v[204:207], v[38:41]
	v_mfma_f32_16x16x32_bf16 v[42:45], v[182:185], v[204:207], v[42:45]
	v_mfma_f32_16x16x32_bf16 v[46:49], v[122:125], v[212:215], v[46:49]
	v_mfma_f32_16x16x32_bf16 v[50:53], v[182:185], v[212:215], v[50:53]
	v_mfma_f32_16x16x32_bf16 v[54:57], v[122:125], v[220:223], v[54:57]
	v_mfma_f32_16x16x32_bf16 v[58:61], v[182:185], v[220:223], v[58:61]
	v_mfma_f32_16x16x32_bf16 v[96:99], v[122:125], v[190:193], v[98:101]
	v_mfma_f32_16x16x32_bf16 v[34:37], v[186:189], v[194:197], v[34:37]
	v_mfma_f32_16x16x32_bf16 v[38:41], v[126:129], v[208:211], v[38:41]
	v_mfma_f32_16x16x32_bf16 v[42:45], v[186:189], v[208:211], v[42:45]
	v_mfma_f32_16x16x32_bf16 v[46:49], v[126:129], v[216:219], v[46:49]
	v_mfma_f32_16x16x32_bf16 v[50:53], v[186:189], v[216:219], v[50:53]
	v_mfma_f32_16x16x32_bf16 v[54:57], v[126:129], v[224:227], v[54:57]
	v_mfma_f32_16x16x32_bf16 v[58:61], v[186:189], v[224:227], v[58:61]
	v_mfma_f32_16x16x32_bf16 v[232:235], v[126:129], v[194:197], v[96:99]
	s_setprio 0
	s_barrier
	s_mov_b32 m0, s21
	v_lshl_add_u64 v[198:199], s[76:77], 0, v[144:145]
	s_mov_b64 s[20:21], 0x8000
	ds_read_b128 v[96:99], v181 offset:16384
	ds_read_b128 v[190:193], v181 offset:17408
	ds_read_b128 v[194:197], v181 offset:18432
	ds_read_b128 v[204:207], v181 offset:19456
	ds_read_b128 v[208:211], v181 offset:20480
	ds_read_b128 v[212:215], v181 offset:21504
	ds_read_b128 v[216:219], v181 offset:22528
	ds_read_b128 v[220:223], v181 offset:23552
	global_load_lds_dwordx4 v[198:199], off
	v_lshl_add_u64 v[0:1], v[198:199], 0, s[20:21]
	s_mov_b32 m0, s7
	s_mov_b64 s[6:7], 0x10000
	global_load_lds_dwordx4 v[0:1], off
	v_lshl_add_u64 v[0:1], v[198:199], 0, s[6:7]
	s_mov_b32 m0, s18
	s_mov_b64 s[6:7], 0x18000
	global_load_lds_dwordx4 v[0:1], off
	v_lshl_add_u64 v[0:1], v[198:199], 0, s[6:7]
	s_mov_b32 m0, s19
	v_lshl_add_u64 v[154:155], vcc, 0, v[156:157]
	global_load_lds_dwordx4 v[0:1], off
	s_mov_b32 m0, s79
	v_lshl_add_u64 v[0:1], v[154:155], 0, s[56:57]
	global_load_lds_dwordx4 v[154:155], off
	s_mov_b32 m0, s42
	s_nop 0
	global_load_lds_dwordx4 v[0:1], off
	s_waitcnt vmcnt(8)
	s_waitcnt lgkmcnt(0)
	s_barrier
	s_setprio 1
	v_mfma_f32_16x16x32_bf16 v[130:133], v[106:109], v[96:99], v[130:133]
	v_mfma_f32_16x16x32_bf16 v[224:227], v[110:113], v[190:193], v[130:133]
	v_mfma_f32_16x16x32_bf16 v[130:133], v[114:117], v[96:99], v[134:137]
	v_mfma_f32_16x16x32_bf16 v[136:139], v[106:109], v[194:197], v[138:141]
	v_mfma_f32_16x16x32_bf16 v[236:239], v[110:113], v[204:207], v[136:139]
	v_mfma_f32_16x16x32_bf16 v[136:139], v[114:117], v[194:197], v[158:161]
	v_mfma_f32_16x16x32_bf16 v[158:161], v[118:121], v[204:207], v[136:139]
	v_mfma_f32_16x16x32_bf16 v[136:139], v[106:109], v[208:211], v[162:165]
	v_mfma_f32_16x16x32_bf16 v[0:3], v[106:109], v[216:219], v[2:5]
	v_mfma_f32_16x16x32_bf16 v[4:7], v[114:117], v[216:219], v[6:9]
	v_mfma_f32_16x16x32_bf16 v[162:165], v[110:113], v[212:215], v[136:139]
	v_mfma_f32_16x16x32_bf16 v[136:139], v[114:117], v[208:211], v[166:169]
	v_mfma_f32_16x16x32_bf16 v[0:3], v[110:113], v[220:223], v[0:3]
	v_mfma_f32_16x16x32_bf16 v[4:7], v[118:121], v[220:223], v[4:7]
	v_mfma_f32_16x16x32_bf16 v[132:135], v[118:121], v[190:193], v[130:133]
	v_mfma_f32_16x16x32_bf16 v[166:169], v[118:121], v[212:215], v[136:139]
	s_setprio 0
	s_setprio 1
	v_mfma_f32_16x16x32_bf16 v[8:11], v[122:125], v[96:99], v[10:13]
	v_mfma_f32_16x16x32_bf16 v[12:15], v[182:185], v[96:99], v[14:17]
	v_mfma_f32_16x16x32_bf16 v[112:115], v[186:189], v[190:193], v[12:15]
	v_mfma_f32_16x16x32_bf16 v[12:15], v[122:125], v[194:197], v[26:29]
	v_mfma_f32_16x16x32_bf16 v[8:11], v[126:129], v[190:193], v[8:11]
	v_mfma_f32_16x16x32_bf16 v[190:193], v[126:129], v[204:207], v[12:15]
	v_mfma_f32_16x16x32_bf16 v[12:15], v[182:185], v[194:197], v[30:33]
	v_mfma_f32_16x16x32_bf16 v[28:31], v[186:189], v[204:207], v[12:15]
	v_mfma_f32_16x16x32_bf16 v[12:15], v[122:125], v[208:211], v[62:65]
	v_mfma_f32_16x16x32_bf16 v[194:197], v[126:129], v[212:215], v[12:15]
	v_mfma_f32_16x16x32_bf16 v[12:15], v[182:185], v[208:211], v[102:105]
	v_mfma_f32_16x16x32_bf16 v[204:207], v[186:189], v[212:215], v[12:15]
	v_mfma_f32_16x16x32_bf16 v[12:15], v[122:125], v[216:219], v[18:21]
	v_mfma_f32_16x16x32_bf16 v[16:19], v[126:129], v[220:223], v[12:15]
	v_mfma_f32_16x16x32_bf16 v[12:15], v[182:185], v[216:219], v[22:25]
	v_mfma_f32_16x16x32_bf16 v[20:23], v[186:189], v[220:223], v[12:15]
	s_setprio 0
	s_barrier
	s_nop 4
	ds_read_b128 v[12:15], v174
	ds_read_b128 v[182:185], v174 offset:1024
	ds_read_b128 v[186:189], v174 offset:2048
	ds_read_b128 v[208:211], v174 offset:3072
	ds_read_b128 v[212:215], v175
	ds_read_b128 v[216:219], v175 offset:1024
	ds_read_b128 v[220:223], v175 offset:2048
	ds_read_b128 v[240:243], v175 offset:3072
	s_mov_b32 m0, s43
	v_lshl_add_u64 v[32:33], v[154:155], 0, s[54:55]
	ds_read_b128 v[24:27], v181 offset:32768
	ds_read_b128 v[62:65], v181 offset:33792
	ds_read_b128 v[100:103], v181 offset:34816
	ds_read_b128 v[108:111], v181 offset:35840
	ds_read_b128 v[244:247], v181 offset:36864
	ds_read_b128 v[248:251], v181 offset:37888
	ds_read_b128 v[174:177], v181 offset:38912
	ds_read_b128 v[150:153], v181 offset:39936
	global_load_lds_dwordx4 v[32:33], off
	v_lshl_add_u64 v[32:33], v[154:155], 0, s[58:59]
	s_mov_b32 m0, s96
	s_nop 0
	global_load_lds_dwordx4 v[32:33], off
	s_waitcnt vmcnt(8)
	s_waitcnt lgkmcnt(0)
	s_barrier
	s_setprio 1
	v_mfma_f32_16x16x32_bf16 v[66:69], v[12:15], v[24:27], v[66:69]
	v_mfma_f32_16x16x32_bf16 v[136:139], v[182:185], v[62:65], v[66:69]
	v_mfma_f32_16x16x32_bf16 v[66:69], v[186:189], v[24:27], v[70:73]
	v_mfma_f32_16x16x32_bf16 v[124:127], v[208:211], v[62:65], v[66:69]
	v_mfma_f32_16x16x32_bf16 v[66:69], v[12:15], v[100:103], v[74:77]
	v_mfma_f32_16x16x32_bf16 v[116:119], v[182:185], v[108:111], v[66:69]
	v_mfma_f32_16x16x32_bf16 v[66:69], v[186:189], v[100:103], v[78:81]
	v_mfma_f32_16x16x32_bf16 v[104:107], v[208:211], v[108:111], v[66:69]
	v_mfma_f32_16x16x32_bf16 v[66:69], v[12:15], v[244:247], v[82:85]
	v_mfma_f32_16x16x32_bf16 v[96:99], v[182:185], v[248:251], v[66:69]
	v_mfma_f32_16x16x32_bf16 v[66:69], v[186:189], v[244:247], v[86:89]
	v_mfma_f32_16x16x32_bf16 v[88:91], v[208:211], v[248:251], v[66:69]
	v_mfma_f32_16x16x32_bf16 v[66:69], v[12:15], v[174:177], v[228:231]
	v_mfma_f32_16x16x32_bf16 v[80:83], v[182:185], v[150:153], v[66:69]
	v_mfma_f32_16x16x32_bf16 v[66:69], v[186:189], v[174:177], v[92:95]
	v_mfma_f32_16x16x32_bf16 v[72:75], v[208:211], v[150:153], v[66:69]
	s_setprio 0
	s_setprio 1
	v_mfma_f32_16x16x32_bf16 v[66:69], v[212:215], v[24:27], v[232:235]
	v_mfma_f32_16x16x32_bf16 v[24:27], v[220:223], v[24:27], v[34:37]
	v_mfma_f32_16x16x32_bf16 v[128:131], v[240:243], v[62:65], v[24:27]
	v_mfma_f32_16x16x32_bf16 v[24:27], v[212:215], v[100:103], v[38:41]
	v_mfma_f32_16x16x32_bf16 v[120:123], v[216:219], v[108:111], v[24:27]
	v_mfma_f32_16x16x32_bf16 v[24:27], v[220:223], v[100:103], v[42:45]
	v_mfma_f32_16x16x32_bf16 v[108:111], v[240:243], v[108:111], v[24:27]
	v_mfma_f32_16x16x32_bf16 v[24:27], v[212:215], v[244:247], v[46:49]
	v_mfma_f32_16x16x32_bf16 v[100:103], v[216:219], v[248:251], v[24:27]
	v_mfma_f32_16x16x32_bf16 v[24:27], v[220:223], v[244:247], v[50:53]
	v_mfma_f32_16x16x32_bf16 v[92:95], v[240:243], v[248:251], v[24:27]
	v_mfma_f32_16x16x32_bf16 v[24:27], v[212:215], v[174:177], v[54:57]
	v_mfma_f32_16x16x32_bf16 v[84:87], v[216:219], v[150:153], v[24:27]
	v_mfma_f32_16x16x32_bf16 v[24:27], v[220:223], v[174:177], v[58:61]
	v_mfma_f32_16x16x32_bf16 v[140:143], v[216:219], v[62:65], v[66:69]
	v_mfma_f32_16x16x32_bf16 v[76:79], v[240:243], v[150:153], v[24:27]
	s_setprio 0
	s_barrier
	s_mov_b32 m0, s69
	s_nop 2
	v_lshl_add_u64 v[24:25], v[198:199], 0, s[60:61]
	s_mov_b64 s[6:7], 0x8080
	ds_read_b128 v[36:39], v181 offset:49152
	ds_read_b128 v[44:47], v181 offset:50176
	ds_read_b128 v[150:153], v181 offset:51200
	ds_read_b128 v[174:177], v181 offset:52224
	ds_read_b128 v[228:231], v181 offset:53248
	ds_read_b128 v[232:235], v181 offset:54272
	ds_read_b128 v[244:247], v181 offset:55296
	ds_read_b128 v[248:251], v181 offset:56320
	global_load_lds_dwordx4 v[24:25], off
	v_lshl_add_u64 v[24:25], v[198:199], 0, s[6:7]
	s_mov_b32 m0, s22
	s_mov_b64 s[6:7], 0x10080
	global_load_lds_dwordx4 v[24:25], off
	v_lshl_add_u64 v[24:25], v[198:199], 0, s[6:7]
	s_mov_b32 m0, s23
	s_mov_b64 s[6:7], 0x18080
	global_load_lds_dwordx4 v[24:25], off
	v_lshl_add_u64 v[24:25], v[198:199], 0, s[6:7]
	s_mov_b32 m0, s68
	s_nop 0
	global_load_lds_dwordx4 v[24:25], off
	v_lshl_add_u64 v[24:25], v[154:155], 0, s[60:61]
	s_mov_b32 m0, s40
	s_nop 0
	global_load_lds_dwordx4 v[24:25], off
	v_lshl_add_u64 v[24:25], v[154:155], 0, s[62:63]
	s_mov_b32 m0, s16
	s_nop 0
	global_load_lds_dwordx4 v[24:25], off
	s_waitcnt vmcnt(8)
	s_waitcnt lgkmcnt(0)
	s_barrier
	s_setprio 1
	v_mfma_f32_16x16x32_bf16 v[24:27], v[12:15], v[36:39], v[224:227]
	v_mfma_f32_16x16x32_bf16 v[64:67], v[182:185], v[44:47], v[24:27]
	v_mfma_f32_16x16x32_bf16 v[24:27], v[186:189], v[36:39], v[132:135]
	v_mfma_f32_16x16x32_bf16 v[56:59], v[208:211], v[44:47], v[24:27]
	v_mfma_f32_16x16x32_bf16 v[24:27], v[12:15], v[150:153], v[236:239]
	v_mfma_f32_16x16x32_bf16 v[48:51], v[182:185], v[174:177], v[24:27]
	v_mfma_f32_16x16x32_bf16 v[24:27], v[186:189], v[150:153], v[158:161]
	v_mfma_f32_16x16x32_bf16 v[40:43], v[208:211], v[174:177], v[24:27]
	v_mfma_f32_16x16x32_bf16 v[24:27], v[12:15], v[228:231], v[162:165]
	v_mfma_f32_16x16x32_bf16 v[0:3], v[12:15], v[244:247], v[0:3]
	v_mfma_f32_16x16x32_bf16 v[32:35], v[182:185], v[232:235], v[24:27]
	v_mfma_f32_16x16x32_bf16 v[24:27], v[186:189], v[228:231], v[166:169]
	v_mfma_f32_16x16x32_bf16 v[12:15], v[182:185], v[248:251], v[0:3]
	v_mfma_f32_16x16x32_bf16 v[0:3], v[186:189], v[244:247], v[4:7]
	v_mfma_f32_16x16x32_bf16 v[24:27], v[208:211], v[232:235], v[24:27]
	v_mfma_f32_16x16x32_bf16 v[0:3], v[208:211], v[248:251], v[0:3]
	s_setprio 0
	s_setprio 1
	v_mfma_f32_16x16x32_bf16 v[4:7], v[212:215], v[36:39], v[8:11]
	v_mfma_f32_16x16x32_bf16 v[68:71], v[216:219], v[44:47], v[4:7]
	v_mfma_f32_16x16x32_bf16 v[4:7], v[220:223], v[36:39], v[112:115]
	v_mfma_f32_16x16x32_bf16 v[60:63], v[240:243], v[44:47], v[4:7]
	v_mfma_f32_16x16x32_bf16 v[4:7], v[212:215], v[150:153], v[190:193]
	v_mfma_f32_16x16x32_bf16 v[52:55], v[216:219], v[174:177], v[4:7]
	v_mfma_f32_16x16x32_bf16 v[4:7], v[220:223], v[150:153], v[28:31]
	v_mfma_f32_16x16x32_bf16 v[44:47], v[240:243], v[174:177], v[4:7]
	v_mfma_f32_16x16x32_bf16 v[4:7], v[212:215], v[228:231], v[194:197]
	v_mfma_f32_16x16x32_bf16 v[36:39], v[216:219], v[232:235], v[4:7]
	v_mfma_f32_16x16x32_bf16 v[4:7], v[220:223], v[228:231], v[204:207]
	v_mfma_f32_16x16x32_bf16 v[28:31], v[240:243], v[232:235], v[4:7]
	v_mfma_f32_16x16x32_bf16 v[4:7], v[212:215], v[244:247], v[16:19]
	v_mfma_f32_16x16x32_bf16 v[16:19], v[216:219], v[248:251], v[4:7]
	v_mfma_f32_16x16x32_bf16 v[4:7], v[220:223], v[244:247], v[20:23]
	v_mfma_f32_16x16x32_bf16 v[4:7], v[240:243], v[248:251], v[4:7]
	s_setprio 0
	s_barrier
	s_andn2_b64 vcc, exec, s[88:89]
	s_cbranch_vccnz .LBB0_488
	s_barrier

.LBB0_836:
	s_add_u32 s36, s70, 0xfff00080
	s_addc_u32 s44, s71, -1
	s_add_i32 s45, 0, 0x10000
	s_cmp_eq_u32 s92, 60
	s_cselect_b32 s73, s37, s44
	s_cselect_b32 s72, s38, s36
	s_cselect_b32 s47, s69, s79
	s_cselect_b32 s46, s74, s75
	s_add_i32 s36, 0, 0x14000
	v_add_u32_e32 v150, s45, v160
	v_add_u32_e32 v154, s36, v160
	ds_read_b128 v[128:131], v150
	ds_read_b128 v[132:135], v150 offset:1024
	ds_read_b128 v[140:143], v150 offset:2048
	ds_read_b128 v[150:153], v150 offset:3072
	ds_read_b128 v[156:159], v154
	ds_read_b128 v[164:167], v154 offset:1024
	ds_read_b128 v[174:177], v154 offset:2048
	ds_read_b128 v[180:183], v154 offset:3072
	v_lshl_add_u64 v[154:155], s[70:71], 0, v[138:139]
	s_add_i32 m0, s20, 0xc000
	ds_read_b128 v[184:187], v162
	ds_read_b128 v[188:191], v162 offset:1024
	ds_read_b128 v[192:195], v162 offset:2048
	ds_read_b128 v[196:199], v162 offset:3072
	ds_read_b128 v[204:207], v162 offset:4096
	ds_read_b128 v[208:211], v162 offset:5120
	ds_read_b128 v[212:215], v162 offset:6144
	ds_read_b128 v[216:219], v162 offset:7168
	global_load_lds_dwordx4 v[154:155], off
	v_lshl_add_u64 v[154:155], v[154:155], 0, s[56:57]
	s_add_i32 m0, s20, 0xe000
	s_nop 0
	global_load_lds_dwordx4 v[154:155], off
	s_waitcnt vmcnt(8)
	s_waitcnt lgkmcnt(0)
	s_barrier
	s_setprio 1
	v_mfma_f32_16x16x32_bf16 v[124:127], v[128:131], v[184:187], v[124:127]
	v_mfma_f32_16x16x32_bf16 v[120:123], v[140:143], v[184:187], v[120:123]
	v_mfma_f32_16x16x32_bf16 v[108:111], v[128:131], v[192:195], v[108:111]
	v_mfma_f32_16x16x32_bf16 v[104:107], v[140:143], v[192:195], v[104:107]
	v_mfma_f32_16x16x32_bf16 v[92:95], v[128:131], v[204:207], v[92:95]
	v_mfma_f32_16x16x32_bf16 v[88:91], v[140:143], v[204:207], v[88:91]
	v_mfma_f32_16x16x32_bf16 v[76:79], v[128:131], v[212:215], v[76:79]
	v_mfma_f32_16x16x32_bf16 v[72:75], v[140:143], v[212:215], v[72:75]
	v_mfma_f32_16x16x32_bf16 v[124:127], v[132:135], v[188:191], v[124:127]
	v_mfma_f32_16x16x32_bf16 v[120:123], v[150:153], v[188:191], v[120:123]
	v_mfma_f32_16x16x32_bf16 v[108:111], v[132:135], v[196:199], v[108:111]
	v_mfma_f32_16x16x32_bf16 v[104:107], v[150:153], v[196:199], v[104:107]
	v_mfma_f32_16x16x32_bf16 v[92:95], v[132:135], v[208:211], v[92:95]
	v_mfma_f32_16x16x32_bf16 v[88:91], v[150:153], v[208:211], v[88:91]
	v_mfma_f32_16x16x32_bf16 v[76:79], v[132:135], v[216:219], v[76:79]
	v_mfma_f32_16x16x32_bf16 v[72:75], v[150:153], v[216:219], v[72:75]
	s_setprio 0
	s_setprio 1
	v_mfma_f32_16x16x32_bf16 v[116:119], v[156:159], v[184:187], v[116:119]
	v_mfma_f32_16x16x32_bf16 v[112:115], v[174:177], v[184:187], v[112:115]
	v_mfma_f32_16x16x32_bf16 v[100:103], v[156:159], v[192:195], v[100:103]
	v_mfma_f32_16x16x32_bf16 v[96:99], v[174:177], v[192:195], v[96:99]
	v_mfma_f32_16x16x32_bf16 v[84:87], v[156:159], v[204:207], v[84:87]
	v_mfma_f32_16x16x32_bf16 v[80:83], v[174:177], v[204:207], v[80:83]
	v_mfma_f32_16x16x32_bf16 v[68:71], v[156:159], v[212:215], v[68:71]
	v_mfma_f32_16x16x32_bf16 v[64:67], v[174:177], v[212:215], v[64:67]
	v_mfma_f32_16x16x32_bf16 v[116:119], v[164:167], v[188:191], v[116:119]
	v_mfma_f32_16x16x32_bf16 v[112:115], v[180:183], v[188:191], v[112:115]
	v_mfma_f32_16x16x32_bf16 v[100:103], v[164:167], v[196:199], v[100:103]
	v_mfma_f32_16x16x32_bf16 v[96:99], v[180:183], v[196:199], v[96:99]
	v_mfma_f32_16x16x32_bf16 v[84:87], v[164:167], v[208:211], v[84:87]
	v_mfma_f32_16x16x32_bf16 v[80:83], v[180:183], v[208:211], v[80:83]
	v_mfma_f32_16x16x32_bf16 v[68:71], v[164:167], v[216:219], v[68:71]
	v_mfma_f32_16x16x32_bf16 v[64:67], v[180:183], v[216:219], v[64:67]
	s_setprio 0
	s_barrier
	s_add_i32 s44, s45, s17
	v_lshl_add_u64 v[154:155], s[46:47], 0, v[144:145]
	s_mov_b32 m0, s44
	ds_read_b128 v[184:187], v162 offset:16384
	ds_read_b128 v[188:191], v162 offset:17408
	ds_read_b128 v[192:195], v162 offset:18432
	ds_read_b128 v[196:199], v162 offset:19456
	ds_read_b128 v[204:207], v162 offset:20480
	ds_read_b128 v[208:211], v162 offset:21504
	ds_read_b128 v[212:215], v162 offset:22528
	ds_read_b128 v[216:219], v162 offset:23552
	global_load_lds_dwordx4 v[154:155], off
	v_lshl_add_u64 v[168:169], v[154:155], 0, s[56:57]
	s_add_i32 m0, s44, 0x2000
	s_add_i32 s36, s36, s17
	global_load_lds_dwordx4 v[168:169], off
	v_lshl_add_u64 v[168:169], v[154:155], 0, s[54:55]
	s_mov_b32 m0, s36
	s_nop 0
	global_load_lds_dwordx4 v[168:169], off
	v_lshl_add_u64 v[168:169], v[154:155], 0, s[58:59]
	s_add_i32 m0, s36, 0x2000
	s_nop 0
	global_load_lds_dwordx4 v[168:169], off
	v_lshl_add_u64 v[168:169], s[72:73], 0, v[136:137]
	s_mov_b32 m0, s20
	v_lshl_add_u64 v[220:221], v[168:169], 0, s[56:57]
	global_load_lds_dwordx4 v[168:169], off
	s_mov_b32 m0, s21
	s_nop 0
	global_load_lds_dwordx4 v[220:221], off
	s_waitcnt vmcnt(8)
	s_waitcnt lgkmcnt(0)
	s_barrier
	s_setprio 1
	v_mfma_f32_16x16x32_bf16 v[60:63], v[128:131], v[184:187], v[60:63]
	v_mfma_f32_16x16x32_bf16 v[56:59], v[140:143], v[184:187], v[56:59]
	v_mfma_f32_16x16x32_bf16 v[44:47], v[128:131], v[192:195], v[44:47]
	v_mfma_f32_16x16x32_bf16 v[40:43], v[140:143], v[192:195], v[40:43]
	v_mfma_f32_16x16x32_bf16 v[28:31], v[128:131], v[204:207], v[28:31]
	v_mfma_f32_16x16x32_bf16 v[24:27], v[140:143], v[204:207], v[24:27]
	v_mfma_f32_16x16x32_bf16 v[12:15], v[128:131], v[212:215], v[12:15]
	v_mfma_f32_16x16x32_bf16 v[8:11], v[140:143], v[212:215], v[8:11]
	v_mfma_f32_16x16x32_bf16 v[60:63], v[132:135], v[188:191], v[60:63]
	v_mfma_f32_16x16x32_bf16 v[56:59], v[150:153], v[188:191], v[56:59]
	v_mfma_f32_16x16x32_bf16 v[44:47], v[132:135], v[196:199], v[44:47]
	v_mfma_f32_16x16x32_bf16 v[40:43], v[150:153], v[196:199], v[40:43]
	v_mfma_f32_16x16x32_bf16 v[28:31], v[132:135], v[208:211], v[28:31]
	v_mfma_f32_16x16x32_bf16 v[24:27], v[150:153], v[208:211], v[24:27]
	v_mfma_f32_16x16x32_bf16 v[12:15], v[132:135], v[216:219], v[12:15]
	v_mfma_f32_16x16x32_bf16 v[8:11], v[150:153], v[216:219], v[8:11]
	s_setprio 0
	s_setprio 1
	v_mfma_f32_16x16x32_bf16 v[52:55], v[156:159], v[184:187], v[52:55]
	v_mfma_f32_16x16x32_bf16 v[48:51], v[174:177], v[184:187], v[48:51]
	v_mfma_f32_16x16x32_bf16 v[36:39], v[156:159], v[192:195], v[36:39]
	v_mfma_f32_16x16x32_bf16 v[32:35], v[174:177], v[192:195], v[32:35]
	v_mfma_f32_16x16x32_bf16 v[20:23], v[156:159], v[204:207], v[20:23]
	v_mfma_f32_16x16x32_bf16 v[16:19], v[174:177], v[204:207], v[16:19]
	v_mfma_f32_16x16x32_bf16 v[4:7], v[156:159], v[212:215], v[4:7]
	v_mfma_f32_16x16x32_bf16 v[0:3], v[174:177], v[212:215], v[0:3]
	v_mfma_f32_16x16x32_bf16 v[52:55], v[164:167], v[188:191], v[52:55]
	v_mfma_f32_16x16x32_bf16 v[48:51], v[180:183], v[188:191], v[48:51]
	v_mfma_f32_16x16x32_bf16 v[36:39], v[164:167], v[196:199], v[36:39]
	v_mfma_f32_16x16x32_bf16 v[32:35], v[180:183], v[196:199], v[32:35]
	v_mfma_f32_16x16x32_bf16 v[20:23], v[164:167], v[208:211], v[20:23]
	v_mfma_f32_16x16x32_bf16 v[16:19], v[180:183], v[208:211], v[16:19]
	v_mfma_f32_16x16x32_bf16 v[4:7], v[164:167], v[216:219], v[4:7]
	v_mfma_f32_16x16x32_bf16 v[0:3], v[180:183], v[216:219], v[0:3]
	s_setprio 0
	s_barrier
	s_add_i32 s36, 0, 0x18000
	s_add_i32 s44, 0, 0x1c000
	v_add_u32_e32 v150, s36, v160
	v_add_u32_e32 v163, s44, v160
	ds_read_b128 v[128:131], v150
	ds_read_b128 v[132:135], v150 offset:1024
	ds_read_b128 v[140:143], v150 offset:2048
	ds_read_b128 v[150:153], v150 offset:3072
	ds_read_b128 v[156:159], v163
	ds_read_b128 v[164:167], v163 offset:1024
	ds_read_b128 v[174:177], v163 offset:2048
	ds_read_b128 v[180:183], v163 offset:3072
	s_mov_b32 m0, s22
	v_lshl_add_u64 v[220:221], v[168:169], 0, s[54:55]
	ds_read_b128 v[184:187], v162 offset:32768
	ds_read_b128 v[188:191], v162 offset:33792
	ds_read_b128 v[192:195], v162 offset:34816
	ds_read_b128 v[196:199], v162 offset:35840
	ds_read_b128 v[204:207], v162 offset:36864
	ds_read_b128 v[208:211], v162 offset:37888
	ds_read_b128 v[212:215], v162 offset:38912
	ds_read_b128 v[216:219], v162 offset:39936
	global_load_lds_dwordx4 v[220:221], off
	v_lshl_add_u64 v[220:221], v[168:169], 0, s[58:59]
	s_mov_b32 m0, s23
	s_nop 0
	global_load_lds_dwordx4 v[220:221], off
	s_waitcnt vmcnt(8)
	s_waitcnt lgkmcnt(0)
	s_barrier
	s_setprio 1
	v_mfma_f32_16x16x32_bf16 v[124:127], v[128:131], v[184:187], v[124:127]
	v_mfma_f32_16x16x32_bf16 v[120:123], v[140:143], v[184:187], v[120:123]
	v_mfma_f32_16x16x32_bf16 v[108:111], v[128:131], v[192:195], v[108:111]
	v_mfma_f32_16x16x32_bf16 v[104:107], v[140:143], v[192:195], v[104:107]
	v_mfma_f32_16x16x32_bf16 v[92:95], v[128:131], v[204:207], v[92:95]
	v_mfma_f32_16x16x32_bf16 v[88:91], v[140:143], v[204:207], v[88:91]
	v_mfma_f32_16x16x32_bf16 v[76:79], v[128:131], v[212:215], v[76:79]
	v_mfma_f32_16x16x32_bf16 v[72:75], v[140:143], v[212:215], v[72:75]
	v_mfma_f32_16x16x32_bf16 v[124:127], v[132:135], v[188:191], v[124:127]
	v_mfma_f32_16x16x32_bf16 v[120:123], v[150:153], v[188:191], v[120:123]
	v_mfma_f32_16x16x32_bf16 v[108:111], v[132:135], v[196:199], v[108:111]
	v_mfma_f32_16x16x32_bf16 v[104:107], v[150:153], v[196:199], v[104:107]
	v_mfma_f32_16x16x32_bf16 v[92:95], v[132:135], v[208:211], v[92:95]
	v_mfma_f32_16x16x32_bf16 v[88:91], v[150:153], v[208:211], v[88:91]
	v_mfma_f32_16x16x32_bf16 v[76:79], v[132:135], v[216:219], v[76:79]
	v_mfma_f32_16x16x32_bf16 v[72:75], v[150:153], v[216:219], v[72:75]
	s_setprio 0
	s_setprio 1
	v_mfma_f32_16x16x32_bf16 v[116:119], v[156:159], v[184:187], v[116:119]
	v_mfma_f32_16x16x32_bf16 v[112:115], v[174:177], v[184:187], v[112:115]
	v_mfma_f32_16x16x32_bf16 v[100:103], v[156:159], v[192:195], v[100:103]
	v_mfma_f32_16x16x32_bf16 v[96:99], v[174:177], v[192:195], v[96:99]
	v_mfma_f32_16x16x32_bf16 v[84:87], v[156:159], v[204:207], v[84:87]
	v_mfma_f32_16x16x32_bf16 v[80:83], v[174:177], v[204:207], v[80:83]
	v_mfma_f32_16x16x32_bf16 v[68:71], v[156:159], v[212:215], v[68:71]
	v_mfma_f32_16x16x32_bf16 v[64:67], v[174:177], v[212:215], v[64:67]
	v_mfma_f32_16x16x32_bf16 v[116:119], v[164:167], v[188:191], v[116:119]
	v_mfma_f32_16x16x32_bf16 v[112:115], v[180:183], v[188:191], v[112:115]
	v_mfma_f32_16x16x32_bf16 v[100:103], v[164:167], v[196:199], v[100:103]
	v_mfma_f32_16x16x32_bf16 v[96:99], v[180:183], v[196:199], v[96:99]
	v_mfma_f32_16x16x32_bf16 v[84:87], v[164:167], v[208:211], v[84:87]
	v_mfma_f32_16x16x32_bf16 v[80:83], v[180:183], v[208:211], v[80:83]
	v_mfma_f32_16x16x32_bf16 v[68:71], v[164:167], v[216:219], v[68:71]
	v_mfma_f32_16x16x32_bf16 v[64:67], v[180:183], v[216:219], v[64:67]
	s_setprio 0
	s_barrier
	s_add_i32 s36, s36, s17
	v_lshl_add_u64 v[220:221], v[154:155], 0, s[60:61]
	s_mov_b32 m0, s36
	ds_read_b128 v[184:187], v162 offset:49152
	ds_read_b128 v[188:191], v162 offset:50176
	ds_read_b128 v[192:195], v162 offset:51200
	ds_read_b128 v[196:199], v162 offset:52224
	ds_read_b128 v[204:207], v162 offset:53248
	ds_read_b128 v[208:211], v162 offset:54272
	ds_read_b128 v[212:215], v162 offset:55296
	ds_read_b128 v[216:219], v162 offset:56320
	global_load_lds_dwordx4 v[220:221], off
	v_lshl_add_u64 v[220:221], v[154:155], 0, s[62:63]
	s_add_i32 m0, s36, 0x2000
	s_add_i32 s36, s44, s17
	global_load_lds_dwordx4 v[220:221], off
	v_lshl_add_u64 v[220:221], v[154:155], 0, s[64:65]
	s_mov_b32 m0, s36
	v_lshl_add_u64 v[154:155], v[154:155], 0, s[66:67]
	global_load_lds_dwordx4 v[220:221], off
	s_add_i32 m0, s36, 0x2000
	s_nop 0
	global_load_lds_dwordx4 v[154:155], off
	v_lshl_add_u64 v[154:155], v[168:169], 0, s[60:61]
	s_mov_b32 m0, s89
	s_nop 0
	global_load_lds_dwordx4 v[154:155], off
	v_lshl_add_u64 v[154:155], v[168:169], 0, s[62:63]
	s_mov_b32 m0, s90
	s_nop 0
	global_load_lds_dwordx4 v[154:155], off
	s_waitcnt vmcnt(8)
	s_waitcnt lgkmcnt(0)
	s_barrier
	s_setprio 1
	v_mfma_f32_16x16x32_bf16 v[60:63], v[128:131], v[184:187], v[60:63]
	v_mfma_f32_16x16x32_bf16 v[56:59], v[140:143], v[184:187], v[56:59]
	v_mfma_f32_16x16x32_bf16 v[44:47], v[128:131], v[192:195], v[44:47]
	v_mfma_f32_16x16x32_bf16 v[40:43], v[140:143], v[192:195], v[40:43]
	v_mfma_f32_16x16x32_bf16 v[28:31], v[128:131], v[204:207], v[28:31]
	v_mfma_f32_16x16x32_bf16 v[24:27], v[140:143], v[204:207], v[24:27]
	v_mfma_f32_16x16x32_bf16 v[12:15], v[128:131], v[212:215], v[12:15]
	v_mfma_f32_16x16x32_bf16 v[8:11], v[140:143], v[212:215], v[8:11]
	v_mfma_f32_16x16x32_bf16 v[60:63], v[132:135], v[188:191], v[60:63]
	v_mfma_f32_16x16x32_bf16 v[56:59], v[150:153], v[188:191], v[56:59]
	v_mfma_f32_16x16x32_bf16 v[44:47], v[132:135], v[196:199], v[44:47]
	v_mfma_f32_16x16x32_bf16 v[40:43], v[150:153], v[196:199], v[40:43]
	v_mfma_f32_16x16x32_bf16 v[28:31], v[132:135], v[208:211], v[28:31]
	v_mfma_f32_16x16x32_bf16 v[24:27], v[150:153], v[208:211], v[24:27]
	v_mfma_f32_16x16x32_bf16 v[12:15], v[132:135], v[216:219], v[12:15]
	v_mfma_f32_16x16x32_bf16 v[8:11], v[150:153], v[216:219], v[8:11]
	s_setprio 0
	s_setprio 1
	v_mfma_f32_16x16x32_bf16 v[52:55], v[156:159], v[184:187], v[52:55]
	v_mfma_f32_16x16x32_bf16 v[48:51], v[174:177], v[184:187], v[48:51]
	v_mfma_f32_16x16x32_bf16 v[36:39], v[156:159], v[192:195], v[36:39]
	v_mfma_f32_16x16x32_bf16 v[32:35], v[174:177], v[192:195], v[32:35]
	v_mfma_f32_16x16x32_bf16 v[20:23], v[156:159], v[204:207], v[20:23]
	v_mfma_f32_16x16x32_bf16 v[16:19], v[174:177], v[204:207], v[16:19]
	v_mfma_f32_16x16x32_bf16 v[4:7], v[156:159], v[212:215], v[4:7]
	v_mfma_f32_16x16x32_bf16 v[0:3], v[174:177], v[212:215], v[0:3]
	v_mfma_f32_16x16x32_bf16 v[52:55], v[164:167], v[188:191], v[52:55]
	v_mfma_f32_16x16x32_bf16 v[48:51], v[180:183], v[188:191], v[48:51]
	v_mfma_f32_16x16x32_bf16 v[36:39], v[164:167], v[196:199], v[36:39]
	v_mfma_f32_16x16x32_bf16 v[32:35], v[180:183], v[196:199], v[32:35]
	v_mfma_f32_16x16x32_bf16 v[20:23], v[164:167], v[208:211], v[20:23]
	v_mfma_f32_16x16x32_bf16 v[16:19], v[180:183], v[208:211], v[16:19]
	v_mfma_f32_16x16x32_bf16 v[4:7], v[164:167], v[216:219], v[4:7]
	v_mfma_f32_16x16x32_bf16 v[0:3], v[180:183], v[216:219], v[0:3]
	s_setprio 0
	s_barrier
	s_add_i32 s92, s92, 2
	s_add_u32 s70, s70, 0x100
	s_addc_u32 s71, s71, 0
	s_add_u32 s75, s75, 0x100
	s_addc_u32 s79, s79, 0
	s_cmp_gt_u32 s92, 61
	s_cbranch_scc0 .LBB0_836
	s_and_b64 vcc, exec, s[52:53]
	s_cbranch_vccz .LBB0_839
	s_barrier

.LBB0_1157:
	ds_read_b128 v[146:149], v142
	ds_read_b128 v[150:153], v142 offset:1024
	ds_read_b128 v[154:157], v142 offset:2048
	ds_read_b128 v[158:161], v142 offset:3072
	ds_read_b128 v[162:165], v143
	ds_read_b128 v[166:169], v143 offset:1024
	ds_read_b128 v[170:173], v143 offset:2048
	ds_read_b128 v[174:177], v143 offset:3072
	s_add_u32 s64, s44, 0xfff00080
	s_addc_u32 s65, s45, -1
	s_cmp_eq_u32 s63, 60
	s_cselect_b32 s65, s29, s65
	s_cselect_b32 s64, s43, s64
	s_cselect_b32 s67, s27, s47
	s_cselect_b32 s66, s62, s46
	v_lshl_add_u64 v[210:211], s[44:45], 0, v[132:133]
	s_add_i32 m0, s48, 0xc000
	ds_read_b128 v[178:181], v144
	ds_read_b128 v[182:185], v144 offset:1024
	ds_read_b128 v[186:189], v144 offset:2048
	ds_read_b128 v[190:193], v144 offset:3072
	ds_read_b128 v[194:197], v144 offset:4096
	ds_read_b128 v[198:201], v144 offset:5120
	ds_read_b128 v[202:205], v144 offset:6144
	ds_read_b128 v[206:209], v144 offset:7168
	global_load_lds_dwordx4 v[210:211], off
	v_lshl_add_u64 v[210:211], v[210:211], 0, s[4:5]
	s_add_i32 m0, s48, 0xe000
	s_nop 0
	global_load_lds_dwordx4 v[210:211], off
	s_waitcnt vmcnt(8)
	s_waitcnt lgkmcnt(0)
	s_barrier
	s_setprio 1
	v_mfma_f32_16x16x32_bf16 v[124:127], v[146:149], v[178:181], v[124:127]
	v_mfma_f32_16x16x32_bf16 v[120:123], v[154:157], v[178:181], v[120:123]
	v_mfma_f32_16x16x32_bf16 v[116:119], v[146:149], v[186:189], v[116:119]
	v_mfma_f32_16x16x32_bf16 v[112:115], v[154:157], v[186:189], v[112:115]
	v_mfma_f32_16x16x32_bf16 v[108:111], v[146:149], v[194:197], v[108:111]
	v_mfma_f32_16x16x32_bf16 v[100:103], v[154:157], v[194:197], v[100:103]
	v_mfma_f32_16x16x32_bf16 v[92:95], v[146:149], v[202:205], v[92:95]
	v_mfma_f32_16x16x32_bf16 v[80:83], v[154:157], v[202:205], v[80:83]
	v_mfma_f32_16x16x32_bf16 v[124:127], v[150:153], v[182:185], v[124:127]
	v_mfma_f32_16x16x32_bf16 v[120:123], v[158:161], v[182:185], v[120:123]
	v_mfma_f32_16x16x32_bf16 v[116:119], v[150:153], v[190:193], v[116:119]
	v_mfma_f32_16x16x32_bf16 v[112:115], v[158:161], v[190:193], v[112:115]
	v_mfma_f32_16x16x32_bf16 v[108:111], v[150:153], v[198:201], v[108:111]
	v_mfma_f32_16x16x32_bf16 v[100:103], v[158:161], v[198:201], v[100:103]
	v_mfma_f32_16x16x32_bf16 v[92:95], v[150:153], v[206:209], v[92:95]
	v_mfma_f32_16x16x32_bf16 v[80:83], v[158:161], v[206:209], v[80:83]
	s_setprio 0
	s_setprio 1
	v_mfma_f32_16x16x32_bf16 v[104:107], v[162:165], v[178:181], v[104:107]
	v_mfma_f32_16x16x32_bf16 v[96:99], v[170:173], v[178:181], v[96:99]
	v_mfma_f32_16x16x32_bf16 v[88:91], v[162:165], v[186:189], v[88:91]
	v_mfma_f32_16x16x32_bf16 v[84:87], v[170:173], v[186:189], v[84:87]
	v_mfma_f32_16x16x32_bf16 v[76:79], v[162:165], v[194:197], v[76:79]
	v_mfma_f32_16x16x32_bf16 v[72:75], v[170:173], v[194:197], v[72:75]
	v_mfma_f32_16x16x32_bf16 v[68:71], v[162:165], v[202:205], v[68:71]
	v_mfma_f32_16x16x32_bf16 v[64:67], v[170:173], v[202:205], v[64:67]
	v_mfma_f32_16x16x32_bf16 v[104:107], v[166:169], v[182:185], v[104:107]
	v_mfma_f32_16x16x32_bf16 v[96:99], v[174:177], v[182:185], v[96:99]
	v_mfma_f32_16x16x32_bf16 v[88:91], v[166:169], v[190:193], v[88:91]
	v_mfma_f32_16x16x32_bf16 v[84:87], v[174:177], v[190:193], v[84:87]
	v_mfma_f32_16x16x32_bf16 v[76:79], v[166:169], v[198:201], v[76:79]
	v_mfma_f32_16x16x32_bf16 v[72:75], v[174:177], v[198:201], v[72:75]
	v_mfma_f32_16x16x32_bf16 v[68:71], v[166:169], v[206:209], v[68:71]
	v_mfma_f32_16x16x32_bf16 v[64:67], v[174:177], v[206:209], v[64:67]
	s_setprio 0
	s_barrier
	v_lshl_add_u64 v[210:211], s[66:67], 0, v[128:129]
	s_add_i32 s66, s59, s34
	s_mov_b32 m0, s66
	ds_read_b128 v[178:181], v144 offset:16384
	ds_read_b128 v[182:185], v144 offset:17408
	ds_read_b128 v[186:189], v144 offset:18432
	ds_read_b128 v[190:193], v144 offset:19456
	ds_read_b128 v[194:197], v144 offset:20480
	ds_read_b128 v[198:201], v144 offset:21504
	ds_read_b128 v[202:205], v144 offset:22528
	ds_read_b128 v[206:209], v144 offset:23552
	global_load_lds_dwordx4 v[210:211], off
	v_lshl_add_u64 v[212:213], v[210:211], 0, s[4:5]
	s_add_i32 m0, s66, 0x2000
	s_add_i32 s66, s60, s34
	global_load_lds_dwordx4 v[212:213], off
	v_lshl_add_u64 v[212:213], v[210:211], 0, s[6:7]
	s_mov_b32 m0, s66
	s_nop 0
	global_load_lds_dwordx4 v[212:213], off
	v_lshl_add_u64 v[212:213], v[210:211], 0, s[8:9]
	s_add_i32 m0, s66, 0x2000
	s_nop 0
	global_load_lds_dwordx4 v[212:213], off
	v_lshl_add_u64 v[212:213], s[64:65], 0, v[128:129]
	s_mov_b32 m0, s48
	v_lshl_add_u64 v[214:215], v[212:213], 0, s[4:5]
	global_load_lds_dwordx4 v[212:213], off
	s_mov_b32 m0, s49
	s_nop 0
	global_load_lds_dwordx4 v[214:215], off
	s_waitcnt vmcnt(8)
	s_waitcnt lgkmcnt(0)
	s_barrier
	s_setprio 1
	v_mfma_f32_16x16x32_bf16 v[60:63], v[146:149], v[178:181], v[60:63]
	v_mfma_f32_16x16x32_bf16 v[56:59], v[154:157], v[178:181], v[56:59]
	v_mfma_f32_16x16x32_bf16 v[52:55], v[146:149], v[186:189], v[52:55]
	v_mfma_f32_16x16x32_bf16 v[40:43], v[154:157], v[186:189], v[40:43]
	v_mfma_f32_16x16x32_bf16 v[36:39], v[146:149], v[194:197], v[36:39]
	v_mfma_f32_16x16x32_bf16 v[24:27], v[154:157], v[194:197], v[24:27]
	v_mfma_f32_16x16x32_bf16 v[20:23], v[146:149], v[202:205], v[20:23]
	v_mfma_f32_16x16x32_bf16 v[8:11], v[154:157], v[202:205], v[8:11]
	v_mfma_f32_16x16x32_bf16 v[60:63], v[150:153], v[182:185], v[60:63]
	v_mfma_f32_16x16x32_bf16 v[56:59], v[158:161], v[182:185], v[56:59]
	v_mfma_f32_16x16x32_bf16 v[52:55], v[150:153], v[190:193], v[52:55]
	v_mfma_f32_16x16x32_bf16 v[40:43], v[158:161], v[190:193], v[40:43]
	v_mfma_f32_16x16x32_bf16 v[36:39], v[150:153], v[198:201], v[36:39]
	v_mfma_f32_16x16x32_bf16 v[24:27], v[158:161], v[198:201], v[24:27]
	v_mfma_f32_16x16x32_bf16 v[20:23], v[150:153], v[206:209], v[20:23]
	v_mfma_f32_16x16x32_bf16 v[8:11], v[158:161], v[206:209], v[8:11]
	s_setprio 0
	s_setprio 1
	v_mfma_f32_16x16x32_bf16 v[48:51], v[162:165], v[178:181], v[48:51]
	v_mfma_f32_16x16x32_bf16 v[44:47], v[170:173], v[178:181], v[44:47]
	v_mfma_f32_16x16x32_bf16 v[32:35], v[162:165], v[186:189], v[32:35]
	v_mfma_f32_16x16x32_bf16 v[28:31], v[170:173], v[186:189], v[28:31]
	v_mfma_f32_16x16x32_bf16 v[16:19], v[162:165], v[194:197], v[16:19]
	v_mfma_f32_16x16x32_bf16 v[12:15], v[170:173], v[194:197], v[12:15]
	v_mfma_f32_16x16x32_bf16 v[4:7], v[162:165], v[202:205], v[4:7]
	v_mfma_f32_16x16x32_bf16 v[0:3], v[170:173], v[202:205], v[0:3]
	v_mfma_f32_16x16x32_bf16 v[48:51], v[166:169], v[182:185], v[48:51]
	v_mfma_f32_16x16x32_bf16 v[44:47], v[174:177], v[182:185], v[44:47]
	v_mfma_f32_16x16x32_bf16 v[32:35], v[166:169], v[190:193], v[32:35]
	v_mfma_f32_16x16x32_bf16 v[28:31], v[174:177], v[190:193], v[28:31]
	v_mfma_f32_16x16x32_bf16 v[16:19], v[166:169], v[198:201], v[16:19]
	v_mfma_f32_16x16x32_bf16 v[12:15], v[174:177], v[198:201], v[12:15]
	v_mfma_f32_16x16x32_bf16 v[4:7], v[166:169], v[206:209], v[4:7]
	v_mfma_f32_16x16x32_bf16 v[0:3], v[174:177], v[206:209], v[0:3]
	s_setprio 0
	s_barrier
	s_add_i32 s64, 0, 0x18000
	v_add_u32_e32 v130, s64, v140
	s_add_i32 s65, 0, 0x1c000
	ds_read_b128 v[146:149], v130
	ds_read_b128 v[150:153], v130 offset:1024
	ds_read_b128 v[154:157], v130 offset:2048
	ds_read_b128 v[158:161], v130 offset:3072
	v_add_u32_e32 v130, s65, v140
	ds_read_b128 v[162:165], v130
	ds_read_b128 v[166:169], v130 offset:1024
	ds_read_b128 v[170:173], v130 offset:2048
	ds_read_b128 v[174:177], v130 offset:3072
	s_mov_b32 m0, s50
	v_lshl_add_u64 v[214:215], v[212:213], 0, s[6:7]
	ds_read_b128 v[178:181], v144 offset:32768
	ds_read_b128 v[182:185], v144 offset:33792
	ds_read_b128 v[186:189], v144 offset:34816
	ds_read_b128 v[190:193], v144 offset:35840
	ds_read_b128 v[194:197], v144 offset:36864
	ds_read_b128 v[198:201], v144 offset:37888
	ds_read_b128 v[202:205], v144 offset:38912
	ds_read_b128 v[206:209], v144 offset:39936
	global_load_lds_dwordx4 v[214:215], off
	v_lshl_add_u64 v[214:215], v[212:213], 0, s[8:9]
	s_mov_b32 m0, s51
	s_nop 0
	global_load_lds_dwordx4 v[214:215], off
	s_waitcnt vmcnt(8)
	s_waitcnt lgkmcnt(0)
	s_barrier
	s_setprio 1
	v_mfma_f32_16x16x32_bf16 v[124:127], v[146:149], v[178:181], v[124:127]
	v_mfma_f32_16x16x32_bf16 v[120:123], v[154:157], v[178:181], v[120:123]
	v_mfma_f32_16x16x32_bf16 v[116:119], v[146:149], v[186:189], v[116:119]
	v_mfma_f32_16x16x32_bf16 v[112:115], v[154:157], v[186:189], v[112:115]
	v_mfma_f32_16x16x32_bf16 v[108:111], v[146:149], v[194:197], v[108:111]
	v_mfma_f32_16x16x32_bf16 v[100:103], v[154:157], v[194:197], v[100:103]
	v_mfma_f32_16x16x32_bf16 v[92:95], v[146:149], v[202:205], v[92:95]
	v_mfma_f32_16x16x32_bf16 v[80:83], v[154:157], v[202:205], v[80:83]
	v_mfma_f32_16x16x32_bf16 v[124:127], v[150:153], v[182:185], v[124:127]
	v_mfma_f32_16x16x32_bf16 v[120:123], v[158:161], v[182:185], v[120:123]
	v_mfma_f32_16x16x32_bf16 v[116:119], v[150:153], v[190:193], v[116:119]
	v_mfma_f32_16x16x32_bf16 v[112:115], v[158:161], v[190:193], v[112:115]
	v_mfma_f32_16x16x32_bf16 v[108:111], v[150:153], v[198:201], v[108:111]
	v_mfma_f32_16x16x32_bf16 v[100:103], v[158:161], v[198:201], v[100:103]
	v_mfma_f32_16x16x32_bf16 v[92:95], v[150:153], v[206:209], v[92:95]
	v_mfma_f32_16x16x32_bf16 v[80:83], v[158:161], v[206:209], v[80:83]
	s_setprio 0
	s_setprio 1
	v_mfma_f32_16x16x32_bf16 v[104:107], v[162:165], v[178:181], v[104:107]
	v_mfma_f32_16x16x32_bf16 v[96:99], v[170:173], v[178:181], v[96:99]
	v_mfma_f32_16x16x32_bf16 v[88:91], v[162:165], v[186:189], v[88:91]
	v_mfma_f32_16x16x32_bf16 v[84:87], v[170:173], v[186:189], v[84:87]
	v_mfma_f32_16x16x32_bf16 v[76:79], v[162:165], v[194:197], v[76:79]
	v_mfma_f32_16x16x32_bf16 v[72:75], v[170:173], v[194:197], v[72:75]
	v_mfma_f32_16x16x32_bf16 v[68:71], v[162:165], v[202:205], v[68:71]
	v_mfma_f32_16x16x32_bf16 v[64:67], v[170:173], v[202:205], v[64:67]
	v_mfma_f32_16x16x32_bf16 v[104:107], v[166:169], v[182:185], v[104:107]
	v_mfma_f32_16x16x32_bf16 v[96:99], v[174:177], v[182:185], v[96:99]
	v_mfma_f32_16x16x32_bf16 v[88:91], v[166:169], v[190:193], v[88:91]
	v_mfma_f32_16x16x32_bf16 v[84:87], v[174:177], v[190:193], v[84:87]
	v_mfma_f32_16x16x32_bf16 v[76:79], v[166:169], v[198:201], v[76:79]
	v_mfma_f32_16x16x32_bf16 v[72:75], v[174:177], v[198:201], v[72:75]
	v_mfma_f32_16x16x32_bf16 v[68:71], v[166:169], v[206:209], v[68:71]
	v_mfma_f32_16x16x32_bf16 v[64:67], v[174:177], v[206:209], v[64:67]
	s_setprio 0
	s_barrier
	s_add_i32 s64, s64, s34
	v_lshl_add_u64 v[214:215], v[210:211], 0, s[16:17]
	s_mov_b32 m0, s64
	ds_read_b128 v[178:181], v144 offset:49152
	ds_read_b128 v[182:185], v144 offset:50176
	ds_read_b128 v[186:189], v144 offset:51200
	ds_read_b128 v[190:193], v144 offset:52224
	ds_read_b128 v[194:197], v144 offset:53248
	ds_read_b128 v[198:201], v144 offset:54272
	ds_read_b128 v[202:205], v144 offset:55296
	ds_read_b128 v[206:209], v144 offset:56320
	global_load_lds_dwordx4 v[214:215], off
	v_lshl_add_u64 v[214:215], v[210:211], 0, s[18:19]
	s_add_i32 m0, s64, 0x2000
	s_add_i32 s64, s65, s34
	global_load_lds_dwordx4 v[214:215], off
	v_lshl_add_u64 v[214:215], v[210:211], 0, s[20:21]
	s_mov_b32 m0, s64
	v_lshl_add_u64 v[210:211], v[210:211], 0, s[22:23]
	global_load_lds_dwordx4 v[214:215], off
	s_add_i32 m0, s64, 0x2000
	s_nop 0
	global_load_lds_dwordx4 v[210:211], off
	v_lshl_add_u64 v[210:211], v[212:213], 0, s[16:17]
	s_mov_b32 m0, s57
	s_nop 0
	global_load_lds_dwordx4 v[210:211], off
	v_lshl_add_u64 v[210:211], v[212:213], 0, s[18:19]
	s_mov_b32 m0, s58
	s_nop 0
	global_load_lds_dwordx4 v[210:211], off
	s_waitcnt vmcnt(8)
	s_waitcnt lgkmcnt(0)
	s_barrier
	s_setprio 1
	v_mfma_f32_16x16x32_bf16 v[60:63], v[146:149], v[178:181], v[60:63]
	v_mfma_f32_16x16x32_bf16 v[56:59], v[154:157], v[178:181], v[56:59]
	v_mfma_f32_16x16x32_bf16 v[52:55], v[146:149], v[186:189], v[52:55]
	v_mfma_f32_16x16x32_bf16 v[40:43], v[154:157], v[186:189], v[40:43]
	v_mfma_f32_16x16x32_bf16 v[36:39], v[146:149], v[194:197], v[36:39]
	v_mfma_f32_16x16x32_bf16 v[24:27], v[154:157], v[194:197], v[24:27]
	v_mfma_f32_16x16x32_bf16 v[20:23], v[146:149], v[202:205], v[20:23]
	v_mfma_f32_16x16x32_bf16 v[8:11], v[154:157], v[202:205], v[8:11]
	v_mfma_f32_16x16x32_bf16 v[60:63], v[150:153], v[182:185], v[60:63]
	v_mfma_f32_16x16x32_bf16 v[56:59], v[158:161], v[182:185], v[56:59]
	v_mfma_f32_16x16x32_bf16 v[52:55], v[150:153], v[190:193], v[52:55]
	v_mfma_f32_16x16x32_bf16 v[40:43], v[158:161], v[190:193], v[40:43]
	v_mfma_f32_16x16x32_bf16 v[36:39], v[150:153], v[198:201], v[36:39]
	v_mfma_f32_16x16x32_bf16 v[24:27], v[158:161], v[198:201], v[24:27]
	v_mfma_f32_16x16x32_bf16 v[20:23], v[150:153], v[206:209], v[20:23]
	v_mfma_f32_16x16x32_bf16 v[8:11], v[158:161], v[206:209], v[8:11]
	s_setprio 0
	s_setprio 1
	v_mfma_f32_16x16x32_bf16 v[48:51], v[162:165], v[178:181], v[48:51]
	v_mfma_f32_16x16x32_bf16 v[44:47], v[170:173], v[178:181], v[44:47]
	v_mfma_f32_16x16x32_bf16 v[32:35], v[162:165], v[186:189], v[32:35]
	v_mfma_f32_16x16x32_bf16 v[28:31], v[170:173], v[186:189], v[28:31]
	v_mfma_f32_16x16x32_bf16 v[16:19], v[162:165], v[194:197], v[16:19]
	v_mfma_f32_16x16x32_bf16 v[12:15], v[170:173], v[194:197], v[12:15]
	v_mfma_f32_16x16x32_bf16 v[4:7], v[162:165], v[202:205], v[4:7]
	v_mfma_f32_16x16x32_bf16 v[0:3], v[170:173], v[202:205], v[0:3]
	v_mfma_f32_16x16x32_bf16 v[48:51], v[166:169], v[182:185], v[48:51]
	v_mfma_f32_16x16x32_bf16 v[44:47], v[174:177], v[182:185], v[44:47]
	v_mfma_f32_16x16x32_bf16 v[32:35], v[166:169], v[190:193], v[32:35]
	v_mfma_f32_16x16x32_bf16 v[28:31], v[174:177], v[190:193], v[28:31]
	v_mfma_f32_16x16x32_bf16 v[16:19], v[166:169], v[198:201], v[16:19]
	v_mfma_f32_16x16x32_bf16 v[12:15], v[174:177], v[198:201], v[12:15]
	v_mfma_f32_16x16x32_bf16 v[4:7], v[166:169], v[206:209], v[4:7]
	v_mfma_f32_16x16x32_bf16 v[0:3], v[174:177], v[206:209], v[0:3]
	s_setprio 0
	s_barrier
	s_add_i32 s63, s63, 2
	s_add_u32 s44, s44, 0x100
	s_addc_u32 s45, s45, 0
	s_add_u32 s46, s46, 0x100
	s_addc_u32 s47, s47, 0
	s_cmp_gt_u32 s63, 61
	s_cbranch_scc0 .LBB0_1157
	s_and_b64 vcc, exec, s[24:25]
	s_cbranch_vccz .LBB0_1160
	s_barrier

.LBB0_1212:
	ds_read_b128 v[40:43], v160
	ds_read_b128 v[44:47], v160 offset:1024
	ds_read_b128 v[56:59], v160 offset:2048
	ds_read_b128 v[60:63], v160 offset:3072
	ds_read_b128 v[154:157], v161
	ds_read_b128 v[164:167], v161 offset:1024
	ds_read_b128 v[168:171], v161 offset:2048
	ds_read_b128 v[172:175], v161 offset:3072
	s_add_u32 s66, s36, 0xfff80080
	s_addc_u32 s67, s37, -1
	s_cmp_eq_u32 s65, 60
	s_cselect_b32 s67, s59, s67
	s_cselect_b32 s66, s60, s66
	s_cselect_b32 s69, s61, s64
	s_cselect_b32 s68, s62, s63
	v_lshl_add_u64 v[208:209], s[36:37], 0, v[152:153]
	s_add_i32 m0, s47, 0xc000
	ds_read_b128 v[176:179], v162
	ds_read_b128 v[180:183], v162 offset:1024
	ds_read_b128 v[184:187], v162 offset:2048
	ds_read_b128 v[188:191], v162 offset:3072
	ds_read_b128 v[192:195], v162 offset:4096
	ds_read_b128 v[196:199], v162 offset:5120
	ds_read_b128 v[200:203], v162 offset:6144
	ds_read_b128 v[204:207], v162 offset:7168
	global_load_lds_dwordx4 v[208:209], off
	v_lshl_add_u64 v[208:209], v[208:209], 0, s[14:15]
	s_add_i32 m0, s47, 0xe000
	s_nop 0
	global_load_lds_dwordx4 v[208:209], off
	s_waitcnt vmcnt(8)
	s_waitcnt lgkmcnt(0)
	s_barrier
	s_setprio 1
	v_mfma_f32_16x16x32_bf16 v[140:143], v[40:43], v[176:179], v[140:143]
	v_mfma_f32_16x16x32_bf16 v[136:139], v[56:59], v[176:179], v[136:139]
	v_mfma_f32_16x16x32_bf16 v[124:127], v[40:43], v[184:187], v[124:127]
	v_mfma_f32_16x16x32_bf16 v[120:123], v[56:59], v[184:187], v[120:123]
	v_mfma_f32_16x16x32_bf16 v[108:111], v[40:43], v[192:195], v[108:111]
	v_mfma_f32_16x16x32_bf16 v[104:107], v[56:59], v[192:195], v[104:107]
	v_mfma_f32_16x16x32_bf16 v[92:95], v[40:43], v[200:203], v[92:95]
	v_mfma_f32_16x16x32_bf16 v[88:91], v[56:59], v[200:203], v[88:91]
	v_mfma_f32_16x16x32_bf16 v[140:143], v[44:47], v[180:183], v[140:143]
	v_mfma_f32_16x16x32_bf16 v[136:139], v[60:63], v[180:183], v[136:139]
	v_mfma_f32_16x16x32_bf16 v[124:127], v[44:47], v[188:191], v[124:127]
	v_mfma_f32_16x16x32_bf16 v[120:123], v[60:63], v[188:191], v[120:123]
	v_mfma_f32_16x16x32_bf16 v[108:111], v[44:47], v[196:199], v[108:111]
	v_mfma_f32_16x16x32_bf16 v[104:107], v[60:63], v[196:199], v[104:107]
	v_mfma_f32_16x16x32_bf16 v[92:95], v[44:47], v[204:207], v[92:95]
	v_mfma_f32_16x16x32_bf16 v[88:91], v[60:63], v[204:207], v[88:91]
	s_setprio 0
	s_setprio 1
	v_mfma_f32_16x16x32_bf16 v[132:135], v[154:157], v[176:179], v[132:135]
	v_mfma_f32_16x16x32_bf16 v[128:131], v[168:171], v[176:179], v[128:131]
	v_mfma_f32_16x16x32_bf16 v[116:119], v[154:157], v[184:187], v[116:119]
	v_mfma_f32_16x16x32_bf16 v[112:115], v[168:171], v[184:187], v[112:115]
	v_mfma_f32_16x16x32_bf16 v[100:103], v[154:157], v[192:195], v[100:103]
	v_mfma_f32_16x16x32_bf16 v[96:99], v[168:171], v[192:195], v[96:99]
	v_mfma_f32_16x16x32_bf16 v[84:87], v[154:157], v[200:203], v[84:87]
	v_mfma_f32_16x16x32_bf16 v[80:83], v[168:171], v[200:203], v[80:83]
	v_mfma_f32_16x16x32_bf16 v[132:135], v[164:167], v[180:183], v[132:135]
	v_mfma_f32_16x16x32_bf16 v[128:131], v[172:175], v[180:183], v[128:131]
	v_mfma_f32_16x16x32_bf16 v[116:119], v[164:167], v[188:191], v[116:119]
	v_mfma_f32_16x16x32_bf16 v[112:115], v[172:175], v[188:191], v[112:115]
	v_mfma_f32_16x16x32_bf16 v[100:103], v[164:167], v[196:199], v[100:103]
	v_mfma_f32_16x16x32_bf16 v[96:99], v[172:175], v[196:199], v[96:99]
	v_mfma_f32_16x16x32_bf16 v[84:87], v[164:167], v[204:207], v[84:87]
	v_mfma_f32_16x16x32_bf16 v[80:83], v[172:175], v[204:207], v[80:83]
	s_setprio 0
	s_barrier
	v_lshl_add_u64 v[208:209], s[68:69], 0, v[144:145]
	s_add_i32 s68, s54, s45
	s_mov_b32 m0, s68
	ds_read_b128 v[176:179], v162 offset:16384
	ds_read_b128 v[180:183], v162 offset:17408
	ds_read_b128 v[184:187], v162 offset:18432
	ds_read_b128 v[188:191], v162 offset:19456
	ds_read_b128 v[192:195], v162 offset:20480
	ds_read_b128 v[196:199], v162 offset:21504
	ds_read_b128 v[200:203], v162 offset:22528
	ds_read_b128 v[204:207], v162 offset:23552
	global_load_lds_dwordx4 v[208:209], off
	v_lshl_add_u64 v[210:211], v[208:209], 0, s[2:3]
	s_add_i32 m0, s68, 0x2000
	s_add_i32 s68, s55, s45
	global_load_lds_dwordx4 v[210:211], off
	v_lshl_add_u64 v[210:211], v[208:209], 0, s[4:5]
	s_mov_b32 m0, s68
	s_nop 0
	global_load_lds_dwordx4 v[210:211], off
	v_lshl_add_u64 v[210:211], v[208:209], 0, s[6:7]
	s_add_i32 m0, s68, 0x2000
	s_nop 0
	global_load_lds_dwordx4 v[210:211], off
	v_lshl_add_u64 v[210:211], s[66:67], 0, v[146:147]
	s_mov_b32 m0, s47
	v_lshl_add_u64 v[212:213], v[210:211], 0, s[14:15]
	global_load_lds_dwordx4 v[210:211], off
	s_mov_b32 m0, s48
	s_nop 0
	global_load_lds_dwordx4 v[212:213], off
	s_waitcnt vmcnt(8)
	s_waitcnt lgkmcnt(0)
	s_barrier
	s_setprio 1
	v_mfma_f32_16x16x32_bf16 v[76:79], v[40:43], v[176:179], v[76:79]
	v_mfma_f32_16x16x32_bf16 v[72:75], v[56:59], v[176:179], v[72:75]
	v_mfma_f32_16x16x32_bf16 v[52:55], v[40:43], v[184:187], v[52:55]
	v_mfma_f32_16x16x32_bf16 v[48:51], v[56:59], v[184:187], v[48:51]
	v_mfma_f32_16x16x32_bf16 v[28:31], v[40:43], v[192:195], v[28:31]
	v_mfma_f32_16x16x32_bf16 v[24:27], v[56:59], v[192:195], v[24:27]
	v_mfma_f32_16x16x32_bf16 v[12:15], v[40:43], v[200:203], v[12:15]
	v_mfma_f32_16x16x32_bf16 v[8:11], v[56:59], v[200:203], v[8:11]
	v_mfma_f32_16x16x32_bf16 v[76:79], v[44:47], v[180:183], v[76:79]
	v_mfma_f32_16x16x32_bf16 v[72:75], v[60:63], v[180:183], v[72:75]
	v_mfma_f32_16x16x32_bf16 v[52:55], v[44:47], v[188:191], v[52:55]
	v_mfma_f32_16x16x32_bf16 v[48:51], v[60:63], v[188:191], v[48:51]
	v_mfma_f32_16x16x32_bf16 v[28:31], v[44:47], v[196:199], v[28:31]
	v_mfma_f32_16x16x32_bf16 v[24:27], v[60:63], v[196:199], v[24:27]
	v_mfma_f32_16x16x32_bf16 v[12:15], v[44:47], v[204:207], v[12:15]
	v_mfma_f32_16x16x32_bf16 v[8:11], v[60:63], v[204:207], v[8:11]
	s_setprio 0
	s_setprio 1
	v_mfma_f32_16x16x32_bf16 v[36:39], v[154:157], v[184:187], v[36:39]
	v_mfma_f32_16x16x32_bf16 v[32:35], v[168:171], v[184:187], v[32:35]
	v_mfma_f32_16x16x32_bf16 v[20:23], v[154:157], v[192:195], v[20:23]
	v_mfma_f32_16x16x32_bf16 v[16:19], v[168:171], v[192:195], v[16:19]
	v_mfma_f32_16x16x32_bf16 v[4:7], v[154:157], v[200:203], v[4:7]
	v_mfma_f32_16x16x32_bf16 v[0:3], v[168:171], v[200:203], v[0:3]
	v_mfma_f32_16x16x32_bf16 v[40:43], v[154:157], v[176:179], v[68:71]
	v_mfma_f32_16x16x32_bf16 v[44:47], v[168:171], v[176:179], v[64:67]
	v_mfma_f32_16x16x32_bf16 v[36:39], v[164:167], v[188:191], v[36:39]
	v_mfma_f32_16x16x32_bf16 v[32:35], v[172:175], v[188:191], v[32:35]
	v_mfma_f32_16x16x32_bf16 v[20:23], v[164:167], v[196:199], v[20:23]
	v_mfma_f32_16x16x32_bf16 v[16:19], v[172:175], v[196:199], v[16:19]
	v_mfma_f32_16x16x32_bf16 v[4:7], v[164:167], v[204:207], v[4:7]
	v_mfma_f32_16x16x32_bf16 v[0:3], v[172:175], v[204:207], v[0:3]
	v_mfma_f32_16x16x32_bf16 v[40:43], v[164:167], v[180:183], v[40:43]
	v_mfma_f32_16x16x32_bf16 v[44:47], v[172:175], v[180:183], v[44:47]
	s_setprio 0
	s_barrier
	s_add_i32 s66, 0, 0x18000
	s_add_i32 s67, 0, 0x1c000
	v_add_u32_e32 v68, s66, v159
	v_add_u32_e32 v163, s67, v159
	ds_read_b128 v[56:59], v68
	ds_read_b128 v[60:63], v68 offset:1024
	ds_read_b128 v[64:67], v68 offset:2048
	ds_read_b128 v[68:71], v68 offset:3072
	ds_read_b128 v[154:157], v163
	ds_read_b128 v[164:167], v163 offset:1024
	ds_read_b128 v[168:171], v163 offset:2048
	ds_read_b128 v[172:175], v163 offset:3072
	s_mov_b32 m0, s49
	v_lshl_add_u64 v[212:213], v[210:211], 0, s[2:3]
	ds_read_b128 v[176:179], v162 offset:32768
	ds_read_b128 v[180:183], v162 offset:33792
	ds_read_b128 v[184:187], v162 offset:34816
	ds_read_b128 v[188:191], v162 offset:35840
	ds_read_b128 v[192:195], v162 offset:36864
	ds_read_b128 v[196:199], v162 offset:37888
	ds_read_b128 v[200:203], v162 offset:38912
	ds_read_b128 v[204:207], v162 offset:39936
	global_load_lds_dwordx4 v[212:213], off
	v_lshl_add_u64 v[212:213], v[210:211], 0, s[16:17]
	s_mov_b32 m0, s50
	s_nop 0
	global_load_lds_dwordx4 v[212:213], off
	s_waitcnt vmcnt(8)
	s_waitcnt lgkmcnt(0)
	s_barrier
	s_setprio 1
	v_mfma_f32_16x16x32_bf16 v[140:143], v[56:59], v[176:179], v[140:143]
	v_mfma_f32_16x16x32_bf16 v[136:139], v[64:67], v[176:179], v[136:139]
	v_mfma_f32_16x16x32_bf16 v[124:127], v[56:59], v[184:187], v[124:127]
	v_mfma_f32_16x16x32_bf16 v[120:123], v[64:67], v[184:187], v[120:123]
	v_mfma_f32_16x16x32_bf16 v[108:111], v[56:59], v[192:195], v[108:111]
	v_mfma_f32_16x16x32_bf16 v[104:107], v[64:67], v[192:195], v[104:107]
	v_mfma_f32_16x16x32_bf16 v[92:95], v[56:59], v[200:203], v[92:95]
	v_mfma_f32_16x16x32_bf16 v[88:91], v[64:67], v[200:203], v[88:91]
	v_mfma_f32_16x16x32_bf16 v[140:143], v[60:63], v[180:183], v[140:143]
	v_mfma_f32_16x16x32_bf16 v[136:139], v[68:71], v[180:183], v[136:139]
	v_mfma_f32_16x16x32_bf16 v[124:127], v[60:63], v[188:191], v[124:127]
	v_mfma_f32_16x16x32_bf16 v[120:123], v[68:71], v[188:191], v[120:123]
	v_mfma_f32_16x16x32_bf16 v[108:111], v[60:63], v[196:199], v[108:111]
	v_mfma_f32_16x16x32_bf16 v[104:107], v[68:71], v[196:199], v[104:107]
	v_mfma_f32_16x16x32_bf16 v[92:95], v[60:63], v[204:207], v[92:95]
	v_mfma_f32_16x16x32_bf16 v[88:91], v[68:71], v[204:207], v[88:91]
	s_setprio 0
	s_setprio 1
	v_mfma_f32_16x16x32_bf16 v[132:135], v[154:157], v[176:179], v[132:135]
	v_mfma_f32_16x16x32_bf16 v[128:131], v[168:171], v[176:179], v[128:131]
	v_mfma_f32_16x16x32_bf16 v[116:119], v[154:157], v[184:187], v[116:119]
	v_mfma_f32_16x16x32_bf16 v[112:115], v[168:171], v[184:187], v[112:115]
	v_mfma_f32_16x16x32_bf16 v[100:103], v[154:157], v[192:195], v[100:103]
	v_mfma_f32_16x16x32_bf16 v[96:99], v[168:171], v[192:195], v[96:99]
	v_mfma_f32_16x16x32_bf16 v[84:87], v[154:157], v[200:203], v[84:87]
	v_mfma_f32_16x16x32_bf16 v[80:83], v[168:171], v[200:203], v[80:83]
	v_mfma_f32_16x16x32_bf16 v[132:135], v[164:167], v[180:183], v[132:135]
	v_mfma_f32_16x16x32_bf16 v[128:131], v[172:175], v[180:183], v[128:131]
	v_mfma_f32_16x16x32_bf16 v[116:119], v[164:167], v[188:191], v[116:119]
	v_mfma_f32_16x16x32_bf16 v[112:115], v[172:175], v[188:191], v[112:115]
	v_mfma_f32_16x16x32_bf16 v[100:103], v[164:167], v[196:199], v[100:103]
	v_mfma_f32_16x16x32_bf16 v[96:99], v[172:175], v[196:199], v[96:99]
	v_mfma_f32_16x16x32_bf16 v[84:87], v[164:167], v[204:207], v[84:87]
	v_mfma_f32_16x16x32_bf16 v[80:83], v[172:175], v[204:207], v[80:83]
	s_setprio 0
	s_barrier
	s_add_i32 s66, s66, s45
	v_lshl_add_u64 v[212:213], v[208:209], 0, s[20:21]
	s_mov_b32 m0, s66
	ds_read_b128 v[176:179], v162 offset:49152
	ds_read_b128 v[180:183], v162 offset:50176
	ds_read_b128 v[184:187], v162 offset:51200
	ds_read_b128 v[188:191], v162 offset:52224
	ds_read_b128 v[192:195], v162 offset:53248
	ds_read_b128 v[196:199], v162 offset:54272
	ds_read_b128 v[200:203], v162 offset:55296
	ds_read_b128 v[204:207], v162 offset:56320
	global_load_lds_dwordx4 v[212:213], off
	v_lshl_add_u64 v[212:213], v[208:209], 0, s[22:23]
	s_add_i32 m0, s66, 0x2000
	s_add_i32 s66, s67, s45
	global_load_lds_dwordx4 v[212:213], off
	v_lshl_add_u64 v[212:213], v[208:209], 0, s[26:27]
	s_mov_b32 m0, s66
	v_lshl_add_u64 v[208:209], v[208:209], 0, s[28:29]
	global_load_lds_dwordx4 v[212:213], off
	s_add_i32 m0, s66, 0x2000
	s_nop 0
	global_load_lds_dwordx4 v[208:209], off
	v_lshl_add_u64 v[208:209], v[210:211], 0, s[20:21]
	s_mov_b32 m0, s51
	s_nop 0
	global_load_lds_dwordx4 v[208:209], off
	v_lshl_add_u64 v[208:209], v[210:211], 0, s[24:25]
	s_mov_b32 m0, s52
	s_nop 0
	global_load_lds_dwordx4 v[208:209], off
	s_waitcnt vmcnt(8)
	s_waitcnt lgkmcnt(0)
	s_barrier
	s_setprio 1
	v_mfma_f32_16x16x32_bf16 v[76:79], v[56:59], v[176:179], v[76:79]
	v_mfma_f32_16x16x32_bf16 v[72:75], v[64:67], v[176:179], v[72:75]
	v_mfma_f32_16x16x32_bf16 v[52:55], v[56:59], v[184:187], v[52:55]
	v_mfma_f32_16x16x32_bf16 v[48:51], v[64:67], v[184:187], v[48:51]
	v_mfma_f32_16x16x32_bf16 v[28:31], v[56:59], v[192:195], v[28:31]
	v_mfma_f32_16x16x32_bf16 v[24:27], v[64:67], v[192:195], v[24:27]
	v_mfma_f32_16x16x32_bf16 v[12:15], v[56:59], v[200:203], v[12:15]
	v_mfma_f32_16x16x32_bf16 v[8:11], v[64:67], v[200:203], v[8:11]
	v_mfma_f32_16x16x32_bf16 v[76:79], v[60:63], v[180:183], v[76:79]
	v_mfma_f32_16x16x32_bf16 v[72:75], v[68:71], v[180:183], v[72:75]
	v_mfma_f32_16x16x32_bf16 v[52:55], v[60:63], v[188:191], v[52:55]
	v_mfma_f32_16x16x32_bf16 v[48:51], v[68:71], v[188:191], v[48:51]
	v_mfma_f32_16x16x32_bf16 v[28:31], v[60:63], v[196:199], v[28:31]
	v_mfma_f32_16x16x32_bf16 v[24:27], v[68:71], v[196:199], v[24:27]
	v_mfma_f32_16x16x32_bf16 v[12:15], v[60:63], v[204:207], v[12:15]
	v_mfma_f32_16x16x32_bf16 v[8:11], v[68:71], v[204:207], v[8:11]
	s_setprio 0
	s_setprio 1
	v_mfma_f32_16x16x32_bf16 v[40:43], v[154:157], v[176:179], v[40:43]
	v_mfma_f32_16x16x32_bf16 v[68:71], v[164:167], v[180:183], v[40:43]
	v_mfma_f32_16x16x32_bf16 v[40:43], v[168:171], v[176:179], v[44:47]
	v_mfma_f32_16x16x32_bf16 v[36:39], v[154:157], v[184:187], v[36:39]
	v_mfma_f32_16x16x32_bf16 v[32:35], v[168:171], v[184:187], v[32:35]
	v_mfma_f32_16x16x32_bf16 v[20:23], v[154:157], v[192:195], v[20:23]
	v_mfma_f32_16x16x32_bf16 v[16:19], v[168:171], v[192:195], v[16:19]
	v_mfma_f32_16x16x32_bf16 v[4:7], v[154:157], v[200:203], v[4:7]
	v_mfma_f32_16x16x32_bf16 v[0:3], v[168:171], v[200:203], v[0:3]
	v_mfma_f32_16x16x32_bf16 v[64:67], v[172:175], v[180:183], v[40:43]
	v_mfma_f32_16x16x32_bf16 v[36:39], v[164:167], v[188:191], v[36:39]
	v_mfma_f32_16x16x32_bf16 v[32:35], v[172:175], v[188:191], v[32:35]
	v_mfma_f32_16x16x32_bf16 v[20:23], v[164:167], v[196:199], v[20:23]
	v_mfma_f32_16x16x32_bf16 v[16:19], v[172:175], v[196:199], v[16:19]
	v_mfma_f32_16x16x32_bf16 v[4:7], v[164:167], v[204:207], v[4:7]
	v_mfma_f32_16x16x32_bf16 v[0:3], v[172:175], v[204:207], v[0:3]
	s_setprio 0
	s_barrier
	s_add_i32 s65, s65, 2
	s_add_u32 s36, s36, 0x100
	s_addc_u32 s37, s37, 0
	s_add_u32 s63, s63, 0x100
	s_addc_u32 s64, s64, 0
	s_cmp_gt_u32 s65, 61
	s_cbranch_scc0 .LBB0_1212
	s_and_b64 vcc, exec, s[30:31]
	s_cbranch_vccz .LBB0_1215
	s_barrier

.LBB0_1403:
	s_add_u32 s38, s36, 0xfff00080
	s_addc_u32 s39, s37, -1
	s_add_i32 s61, 0, 0x10000
	s_cmp_eq_u32 s60, 60
	s_cselect_b32 s39, s5, s39
	s_cselect_b32 s38, s15, s38
	s_cselect_b32 s63, s13, s59
	s_cselect_b32 s62, s27, s58
	s_add_i32 s64, 0, 0x14000
	v_add_u32_e32 v146, s61, v157
	v_add_u32_e32 v154, s64, v157
	ds_read_b128 v[134:137], v146
	ds_read_b128 v[138:141], v146 offset:1024
	ds_read_b128 v[142:145], v146 offset:2048
	ds_read_b128 v[146:149], v146 offset:3072
	ds_read_b128 v[150:153], v154
	ds_read_b128 v[172:175], v154 offset:1024
	ds_read_b128 v[176:179], v154 offset:2048
	ds_read_b128 v[190:193], v154 offset:3072
	v_lshl_add_u64 v[154:155], s[36:37], 0, v[132:133]
	s_add_i32 m0, s45, 0xc000
	ds_read_b128 v[194:197], v160
	ds_read_b128 v[198:201], v160 offset:1024
	ds_read_b128 v[202:205], v160 offset:2048
	ds_read_b128 v[206:209], v160 offset:3072
	ds_read_b128 v[210:213], v160 offset:4096
	ds_read_b128 v[214:217], v160 offset:5120
	ds_read_b128 v[218:221], v160 offset:6144
	ds_read_b128 v[222:225], v160 offset:7168
	global_load_lds_dwordx4 v[154:155], off
	v_lshl_add_u64 v[154:155], v[154:155], 0, s[24:25]
	s_add_i32 m0, s45, 0xe000
	s_nop 0
	global_load_lds_dwordx4 v[154:155], off
	s_waitcnt vmcnt(8)
	s_waitcnt lgkmcnt(0)
	s_barrier
	s_setprio 1
	v_mfma_f32_16x16x32_bf16 v[126:129], v[134:137], v[194:197], v[126:129]
	v_mfma_f32_16x16x32_bf16 v[122:125], v[142:145], v[194:197], v[122:125]
	v_mfma_f32_16x16x32_bf16 v[110:113], v[134:137], v[202:205], v[110:113]
	v_mfma_f32_16x16x32_bf16 v[106:109], v[142:145], v[202:205], v[106:109]
	v_mfma_f32_16x16x32_bf16 v[94:97], v[134:137], v[210:213], v[94:97]
	v_mfma_f32_16x16x32_bf16 v[90:93], v[142:145], v[210:213], v[90:93]
	v_mfma_f32_16x16x32_bf16 v[78:81], v[134:137], v[218:221], v[78:81]
	v_mfma_f32_16x16x32_bf16 v[74:77], v[142:145], v[218:221], v[74:77]
	v_mfma_f32_16x16x32_bf16 v[126:129], v[138:141], v[198:201], v[126:129]
	v_mfma_f32_16x16x32_bf16 v[122:125], v[146:149], v[198:201], v[122:125]
	v_mfma_f32_16x16x32_bf16 v[110:113], v[138:141], v[206:209], v[110:113]
	v_mfma_f32_16x16x32_bf16 v[106:109], v[146:149], v[206:209], v[106:109]
	v_mfma_f32_16x16x32_bf16 v[94:97], v[138:141], v[214:217], v[94:97]
	v_mfma_f32_16x16x32_bf16 v[90:93], v[146:149], v[214:217], v[90:93]
	v_mfma_f32_16x16x32_bf16 v[78:81], v[138:141], v[222:225], v[78:81]
	v_mfma_f32_16x16x32_bf16 v[74:77], v[146:149], v[222:225], v[74:77]
	s_setprio 0
	s_setprio 1
	v_mfma_f32_16x16x32_bf16 v[118:121], v[150:153], v[194:197], v[118:121]
	v_mfma_f32_16x16x32_bf16 v[114:117], v[176:179], v[194:197], v[114:117]
	v_mfma_f32_16x16x32_bf16 v[102:105], v[150:153], v[202:205], v[102:105]
	v_mfma_f32_16x16x32_bf16 v[98:101], v[176:179], v[202:205], v[98:101]
	v_mfma_f32_16x16x32_bf16 v[86:89], v[150:153], v[210:213], v[86:89]
	v_mfma_f32_16x16x32_bf16 v[82:85], v[176:179], v[210:213], v[82:85]
	v_mfma_f32_16x16x32_bf16 v[70:73], v[150:153], v[218:221], v[70:73]
	v_mfma_f32_16x16x32_bf16 v[66:69], v[176:179], v[218:221], v[66:69]
	v_mfma_f32_16x16x32_bf16 v[118:121], v[172:175], v[198:201], v[118:121]
	v_mfma_f32_16x16x32_bf16 v[114:117], v[190:193], v[198:201], v[114:117]
	v_mfma_f32_16x16x32_bf16 v[102:105], v[172:175], v[206:209], v[102:105]
	v_mfma_f32_16x16x32_bf16 v[98:101], v[190:193], v[206:209], v[98:101]
	v_mfma_f32_16x16x32_bf16 v[86:89], v[172:175], v[214:217], v[86:89]
	v_mfma_f32_16x16x32_bf16 v[82:85], v[190:193], v[214:217], v[82:85]
	v_mfma_f32_16x16x32_bf16 v[70:73], v[172:175], v[222:225], v[70:73]
	v_mfma_f32_16x16x32_bf16 v[66:69], v[190:193], v[222:225], v[66:69]
	s_setprio 0
	s_barrier
	s_add_i32 s61, s61, s20
	v_lshl_add_u64 v[154:155], s[62:63], 0, v[0:1]
	s_mov_b32 m0, s61
	ds_read_b128 v[194:197], v160 offset:16384
	ds_read_b128 v[198:201], v160 offset:17408
	ds_read_b128 v[202:205], v160 offset:18432
	ds_read_b128 v[206:209], v160 offset:19456
	ds_read_b128 v[210:213], v160 offset:20480
	ds_read_b128 v[214:217], v160 offset:21504
	ds_read_b128 v[218:221], v160 offset:22528
	ds_read_b128 v[222:225], v160 offset:23552
	global_load_lds_dwordx4 v[154:155], off
	v_lshl_add_u64 v[164:165], v[154:155], 0, s[24:25]
	s_add_i32 m0, s61, 0x2000
	s_add_i32 s61, s64, s20
	global_load_lds_dwordx4 v[164:165], off
	v_lshl_add_u64 v[164:165], v[154:155], 0, s[22:23]
	s_mov_b32 m0, s61
	s_nop 0
	global_load_lds_dwordx4 v[164:165], off
	v_lshl_add_u64 v[164:165], v[154:155], 0, s[28:29]
	s_add_i32 m0, s61, 0x2000
	s_nop 0
	global_load_lds_dwordx4 v[164:165], off
	v_lshl_add_u64 v[164:165], s[38:39], 0, v[130:131]
	s_mov_b32 m0, s45
	v_lshl_add_u64 v[166:167], v[164:165], 0, s[24:25]
	global_load_lds_dwordx4 v[164:165], off
	s_mov_b32 m0, s46
	s_nop 0
	global_load_lds_dwordx4 v[166:167], off
	s_waitcnt vmcnt(8)
	s_waitcnt lgkmcnt(0)
	s_barrier
	s_setprio 1
	v_mfma_f32_16x16x32_bf16 v[62:65], v[134:137], v[194:197], v[62:65]
	v_mfma_f32_16x16x32_bf16 v[58:61], v[142:145], v[194:197], v[58:61]
	v_mfma_f32_16x16x32_bf16 v[46:49], v[134:137], v[202:205], v[46:49]
	v_mfma_f32_16x16x32_bf16 v[42:45], v[142:145], v[202:205], v[42:45]
	v_mfma_f32_16x16x32_bf16 v[30:33], v[134:137], v[210:213], v[30:33]
	v_mfma_f32_16x16x32_bf16 v[26:29], v[142:145], v[210:213], v[26:29]
	v_mfma_f32_16x16x32_bf16 v[14:17], v[134:137], v[218:221], v[14:17]
	v_mfma_f32_16x16x32_bf16 v[10:13], v[142:145], v[218:221], v[10:13]
	v_mfma_f32_16x16x32_bf16 v[62:65], v[138:141], v[198:201], v[62:65]
	v_mfma_f32_16x16x32_bf16 v[58:61], v[146:149], v[198:201], v[58:61]
	v_mfma_f32_16x16x32_bf16 v[46:49], v[138:141], v[206:209], v[46:49]
	v_mfma_f32_16x16x32_bf16 v[42:45], v[146:149], v[206:209], v[42:45]
	v_mfma_f32_16x16x32_bf16 v[30:33], v[138:141], v[214:217], v[30:33]
	v_mfma_f32_16x16x32_bf16 v[26:29], v[146:149], v[214:217], v[26:29]
	v_mfma_f32_16x16x32_bf16 v[14:17], v[138:141], v[222:225], v[14:17]
	v_mfma_f32_16x16x32_bf16 v[10:13], v[146:149], v[222:225], v[10:13]
	s_setprio 0
	s_setprio 1
	v_mfma_f32_16x16x32_bf16 v[54:57], v[150:153], v[194:197], v[54:57]
	v_mfma_f32_16x16x32_bf16 v[50:53], v[176:179], v[194:197], v[50:53]
	v_mfma_f32_16x16x32_bf16 v[38:41], v[150:153], v[202:205], v[38:41]
	v_mfma_f32_16x16x32_bf16 v[34:37], v[176:179], v[202:205], v[34:37]
	v_mfma_f32_16x16x32_bf16 v[22:25], v[150:153], v[210:213], v[22:25]
	v_mfma_f32_16x16x32_bf16 v[18:21], v[176:179], v[210:213], v[18:21]
	v_mfma_f32_16x16x32_bf16 v[6:9], v[150:153], v[218:221], v[6:9]
	v_mfma_f32_16x16x32_bf16 v[2:5], v[176:179], v[218:221], v[2:5]
	v_mfma_f32_16x16x32_bf16 v[54:57], v[172:175], v[198:201], v[54:57]
	v_mfma_f32_16x16x32_bf16 v[50:53], v[190:193], v[198:201], v[50:53]
	v_mfma_f32_16x16x32_bf16 v[38:41], v[172:175], v[206:209], v[38:41]
	v_mfma_f32_16x16x32_bf16 v[34:37], v[190:193], v[206:209], v[34:37]
	v_mfma_f32_16x16x32_bf16 v[22:25], v[172:175], v[214:217], v[22:25]
	v_mfma_f32_16x16x32_bf16 v[18:21], v[190:193], v[214:217], v[18:21]
	v_mfma_f32_16x16x32_bf16 v[6:9], v[172:175], v[222:225], v[6:9]
	v_mfma_f32_16x16x32_bf16 v[2:5], v[190:193], v[222:225], v[2:5]
	s_setprio 0
	s_barrier
	s_add_i32 s38, 0, 0x18000
	s_add_i32 s39, 0, 0x1c000
	v_add_u32_e32 v146, s38, v157
	v_add_u32_e32 v159, s39, v157
	ds_read_b128 v[134:137], v146
	ds_read_b128 v[138:141], v146 offset:1024
	ds_read_b128 v[142:145], v146 offset:2048
	ds_read_b128 v[146:149], v146 offset:3072
	ds_read_b128 v[150:153], v159
	ds_read_b128 v[172:175], v159 offset:1024
	ds_read_b128 v[176:179], v159 offset:2048
	ds_read_b128 v[190:193], v159 offset:3072
	s_mov_b32 m0, s47
	v_lshl_add_u64 v[166:167], v[164:165], 0, s[22:23]
	ds_read_b128 v[194:197], v160 offset:32768
	ds_read_b128 v[198:201], v160 offset:33792
	ds_read_b128 v[202:205], v160 offset:34816
	ds_read_b128 v[206:209], v160 offset:35840
	ds_read_b128 v[210:213], v160 offset:36864
	ds_read_b128 v[214:217], v160 offset:37888
	ds_read_b128 v[218:221], v160 offset:38912
	ds_read_b128 v[222:225], v160 offset:39936
	global_load_lds_dwordx4 v[166:167], off
	v_lshl_add_u64 v[166:167], v[164:165], 0, s[28:29]
	s_mov_b32 m0, s52
	s_nop 0
	global_load_lds_dwordx4 v[166:167], off
	s_waitcnt vmcnt(8)
	s_waitcnt lgkmcnt(0)
	s_barrier
	s_setprio 1
	v_mfma_f32_16x16x32_bf16 v[126:129], v[134:137], v[194:197], v[126:129]
	v_mfma_f32_16x16x32_bf16 v[122:125], v[142:145], v[194:197], v[122:125]
	v_mfma_f32_16x16x32_bf16 v[110:113], v[134:137], v[202:205], v[110:113]
	v_mfma_f32_16x16x32_bf16 v[106:109], v[142:145], v[202:205], v[106:109]
	v_mfma_f32_16x16x32_bf16 v[94:97], v[134:137], v[210:213], v[94:97]
	v_mfma_f32_16x16x32_bf16 v[90:93], v[142:145], v[210:213], v[90:93]
	v_mfma_f32_16x16x32_bf16 v[78:81], v[134:137], v[218:221], v[78:81]
	v_mfma_f32_16x16x32_bf16 v[74:77], v[142:145], v[218:221], v[74:77]
	v_mfma_f32_16x16x32_bf16 v[126:129], v[138:141], v[198:201], v[126:129]
	v_mfma_f32_16x16x32_bf16 v[122:125], v[146:149], v[198:201], v[122:125]
	v_mfma_f32_16x16x32_bf16 v[110:113], v[138:141], v[206:209], v[110:113]
	v_mfma_f32_16x16x32_bf16 v[106:109], v[146:149], v[206:209], v[106:109]
	v_mfma_f32_16x16x32_bf16 v[94:97], v[138:141], v[214:217], v[94:97]
	v_mfma_f32_16x16x32_bf16 v[90:93], v[146:149], v[214:217], v[90:93]
	v_mfma_f32_16x16x32_bf16 v[78:81], v[138:141], v[222:225], v[78:81]
	v_mfma_f32_16x16x32_bf16 v[74:77], v[146:149], v[222:225], v[74:77]
	s_setprio 0
	s_setprio 1
	v_mfma_f32_16x16x32_bf16 v[118:121], v[150:153], v[194:197], v[118:121]
	v_mfma_f32_16x16x32_bf16 v[114:117], v[176:179], v[194:197], v[114:117]
	v_mfma_f32_16x16x32_bf16 v[102:105], v[150:153], v[202:205], v[102:105]
	v_mfma_f32_16x16x32_bf16 v[98:101], v[176:179], v[202:205], v[98:101]
	v_mfma_f32_16x16x32_bf16 v[86:89], v[150:153], v[210:213], v[86:89]
	v_mfma_f32_16x16x32_bf16 v[82:85], v[176:179], v[210:213], v[82:85]
	v_mfma_f32_16x16x32_bf16 v[70:73], v[150:153], v[218:221], v[70:73]
	v_mfma_f32_16x16x32_bf16 v[66:69], v[176:179], v[218:221], v[66:69]
	v_mfma_f32_16x16x32_bf16 v[118:121], v[172:175], v[198:201], v[118:121]
	v_mfma_f32_16x16x32_bf16 v[114:117], v[190:193], v[198:201], v[114:117]
	v_mfma_f32_16x16x32_bf16 v[102:105], v[172:175], v[206:209], v[102:105]
	v_mfma_f32_16x16x32_bf16 v[98:101], v[190:193], v[206:209], v[98:101]
	v_mfma_f32_16x16x32_bf16 v[86:89], v[172:175], v[214:217], v[86:89]
	v_mfma_f32_16x16x32_bf16 v[82:85], v[190:193], v[214:217], v[82:85]
	v_mfma_f32_16x16x32_bf16 v[70:73], v[172:175], v[222:225], v[70:73]
	v_mfma_f32_16x16x32_bf16 v[66:69], v[190:193], v[222:225], v[66:69]
	s_setprio 0
	s_barrier
	s_add_i32 s38, s38, s20
	v_lshl_add_u64 v[166:167], v[154:155], 0, s[30:31]
	s_mov_b32 m0, s38
	ds_read_b128 v[194:197], v160 offset:49152
	ds_read_b128 v[198:201], v160 offset:50176
	ds_read_b128 v[202:205], v160 offset:51200
	ds_read_b128 v[206:209], v160 offset:52224
	ds_read_b128 v[210:213], v160 offset:53248
	ds_read_b128 v[214:217], v160 offset:54272
	ds_read_b128 v[218:221], v160 offset:55296
	ds_read_b128 v[222:225], v160 offset:56320
	global_load_lds_dwordx4 v[166:167], off
	v_lshl_add_u64 v[166:167], v[154:155], 0, s[34:35]
	s_add_i32 m0, s38, 0x2000
	s_add_i32 s38, s39, s20
	global_load_lds_dwordx4 v[166:167], off
	v_lshl_add_u64 v[166:167], v[154:155], 0, s[88:89]
	s_mov_b32 m0, s38
	v_lshl_add_u64 v[154:155], v[154:155], 0, s[90:91]
	global_load_lds_dwordx4 v[166:167], off
	s_add_i32 m0, s38, 0x2000
	s_nop 0
	global_load_lds_dwordx4 v[154:155], off
	v_lshl_add_u64 v[154:155], v[164:165], 0, s[30:31]
	s_mov_b32 m0, s53
	s_nop 0
	global_load_lds_dwordx4 v[154:155], off
	v_lshl_add_u64 v[154:155], v[164:165], 0, s[34:35]
	s_mov_b32 m0, s54
	s_nop 0
	global_load_lds_dwordx4 v[154:155], off
	s_waitcnt vmcnt(8)
	s_waitcnt lgkmcnt(0)
	s_barrier
	s_setprio 1
	v_mfma_f32_16x16x32_bf16 v[62:65], v[134:137], v[194:197], v[62:65]
	v_mfma_f32_16x16x32_bf16 v[58:61], v[142:145], v[194:197], v[58:61]
	v_mfma_f32_16x16x32_bf16 v[46:49], v[134:137], v[202:205], v[46:49]
	v_mfma_f32_16x16x32_bf16 v[42:45], v[142:145], v[202:205], v[42:45]
	v_mfma_f32_16x16x32_bf16 v[30:33], v[134:137], v[210:213], v[30:33]
	v_mfma_f32_16x16x32_bf16 v[26:29], v[142:145], v[210:213], v[26:29]
	v_mfma_f32_16x16x32_bf16 v[14:17], v[134:137], v[218:221], v[14:17]
	v_mfma_f32_16x16x32_bf16 v[10:13], v[142:145], v[218:221], v[10:13]
	v_mfma_f32_16x16x32_bf16 v[62:65], v[138:141], v[198:201], v[62:65]
	v_mfma_f32_16x16x32_bf16 v[58:61], v[146:149], v[198:201], v[58:61]
	v_mfma_f32_16x16x32_bf16 v[46:49], v[138:141], v[206:209], v[46:49]
	v_mfma_f32_16x16x32_bf16 v[42:45], v[146:149], v[206:209], v[42:45]
	v_mfma_f32_16x16x32_bf16 v[30:33], v[138:141], v[214:217], v[30:33]
	v_mfma_f32_16x16x32_bf16 v[26:29], v[146:149], v[214:217], v[26:29]
	v_mfma_f32_16x16x32_bf16 v[14:17], v[138:141], v[222:225], v[14:17]
	v_mfma_f32_16x16x32_bf16 v[10:13], v[146:149], v[222:225], v[10:13]
	s_setprio 0
	s_setprio 1
	v_mfma_f32_16x16x32_bf16 v[54:57], v[150:153], v[194:197], v[54:57]
	v_mfma_f32_16x16x32_bf16 v[50:53], v[176:179], v[194:197], v[50:53]
	v_mfma_f32_16x16x32_bf16 v[38:41], v[150:153], v[202:205], v[38:41]
	v_mfma_f32_16x16x32_bf16 v[34:37], v[176:179], v[202:205], v[34:37]
	v_mfma_f32_16x16x32_bf16 v[22:25], v[150:153], v[210:213], v[22:25]
	v_mfma_f32_16x16x32_bf16 v[18:21], v[176:179], v[210:213], v[18:21]
	v_mfma_f32_16x16x32_bf16 v[6:9], v[150:153], v[218:221], v[6:9]
	v_mfma_f32_16x16x32_bf16 v[2:5], v[176:179], v[218:221], v[2:5]
	v_mfma_f32_16x16x32_bf16 v[54:57], v[172:175], v[198:201], v[54:57]
	v_mfma_f32_16x16x32_bf16 v[50:53], v[190:193], v[198:201], v[50:53]
	v_mfma_f32_16x16x32_bf16 v[38:41], v[172:175], v[206:209], v[38:41]
	v_mfma_f32_16x16x32_bf16 v[34:37], v[190:193], v[206:209], v[34:37]
	v_mfma_f32_16x16x32_bf16 v[22:25], v[172:175], v[214:217], v[22:25]
	v_mfma_f32_16x16x32_bf16 v[18:21], v[190:193], v[214:217], v[18:21]
	v_mfma_f32_16x16x32_bf16 v[6:9], v[172:175], v[222:225], v[6:9]
	v_mfma_f32_16x16x32_bf16 v[2:5], v[190:193], v[222:225], v[2:5]
	s_setprio 0
	s_barrier
	s_add_i32 s60, s60, 2
	s_add_u32 s36, s36, 0x100
	s_addc_u32 s37, s37, 0
	s_add_u32 s58, s58, 0x100
	s_addc_u32 s59, s59, 0
	s_cmp_gt_u32 s60, 61
	s_cbranch_scc0 .LBB0_1403
	s_and_b64 vcc, exec, s[10:11]
	s_cbranch_vccz .LBB0_1406
	s_barrier

.LBB0_1490:
	s_add_u32 s62, s16, 0xfff00080
	s_addc_u32 s63, s17, -1
	s_add_i32 s66, 0, 0x10000
	v_add_u32_e32 v73, s66, v71
	ds_read_b128 v[74:77], v73
	ds_read_b128 v[78:81], v73 offset:1024
	ds_read_b128 v[82:85], v73 offset:2048
	ds_read_b128 v[86:89], v73 offset:3072
	s_cmp_eq_u32 s20, 4
	s_cselect_b32 s63, s13, s63
	s_cselect_b32 s62, s12, s62
	s_cselect_b32 s65, s7, s19
	s_cselect_b32 s64, s11, s18
	v_lshl_add_u64 v[122:123], s[16:17], 0, v[68:69]
	s_add_i32 m0, s39, 0xc000
	ds_read_b128 v[90:93], v72
	ds_read_b128 v[94:97], v72 offset:1024
	ds_read_b128 v[98:101], v72 offset:2048
	ds_read_b128 v[102:105], v72 offset:3072
	ds_read_b128 v[106:109], v72 offset:4096
	ds_read_b128 v[110:113], v72 offset:5120
	ds_read_b128 v[114:117], v72 offset:6144
	ds_read_b128 v[118:121], v72 offset:7168
	global_load_lds_dwordx4 v[122:123], off
	v_lshl_add_u64 v[122:123], v[122:123], 0, s[24:25]
	s_add_i32 m0, s39, 0xe000
	s_nop 0
	global_load_lds_dwordx4 v[122:123], off
	s_waitcnt vmcnt(8)
	s_waitcnt lgkmcnt(0)
	s_barrier
	s_setprio 1
	v_mfma_f32_16x16x32_bf16 v[62:65], v[74:77], v[90:93], v[62:65]
	v_mfma_f32_16x16x32_bf16 v[58:61], v[82:85], v[90:93], v[58:61]
	v_mfma_f32_16x16x32_bf16 v[54:57], v[74:77], v[98:101], v[54:57]
	v_mfma_f32_16x16x32_bf16 v[50:53], v[82:85], v[98:101], v[50:53]
	v_mfma_f32_16x16x32_bf16 v[46:49], v[74:77], v[106:109], v[46:49]
	v_mfma_f32_16x16x32_bf16 v[42:45], v[82:85], v[106:109], v[42:45]
	v_mfma_f32_16x16x32_bf16 v[38:41], v[74:77], v[114:117], v[38:41]
	v_mfma_f32_16x16x32_bf16 v[34:37], v[82:85], v[114:117], v[34:37]
	v_mfma_f32_16x16x32_bf16 v[62:65], v[78:81], v[94:97], v[62:65]
	v_mfma_f32_16x16x32_bf16 v[58:61], v[86:89], v[94:97], v[58:61]
	v_mfma_f32_16x16x32_bf16 v[54:57], v[78:81], v[102:105], v[54:57]
	v_mfma_f32_16x16x32_bf16 v[50:53], v[86:89], v[102:105], v[50:53]
	v_mfma_f32_16x16x32_bf16 v[46:49], v[78:81], v[110:113], v[46:49]
	v_mfma_f32_16x16x32_bf16 v[42:45], v[86:89], v[110:113], v[42:45]
	v_mfma_f32_16x16x32_bf16 v[38:41], v[78:81], v[118:121], v[38:41]
	v_mfma_f32_16x16x32_bf16 v[34:37], v[86:89], v[118:121], v[34:37]
	s_setprio 0
	s_setprio 1
	s_setprio 0
	s_barrier
	v_lshl_add_u64 v[122:123], s[64:65], 0, v[0:1]
	s_add_i32 s64, s66, s36
	s_mov_b32 m0, s64
	ds_read_b128 v[90:93], v72 offset:16384
	ds_read_b128 v[94:97], v72 offset:17408
	ds_read_b128 v[98:101], v72 offset:18432
	ds_read_b128 v[102:105], v72 offset:19456
	ds_read_b128 v[106:109], v72 offset:20480
	ds_read_b128 v[110:113], v72 offset:21504
	ds_read_b128 v[114:117], v72 offset:22528
	ds_read_b128 v[118:121], v72 offset:23552
	global_load_lds_dwordx4 v[122:123], off
	v_lshl_add_u64 v[124:125], v[122:123], 0, s[24:25]
	s_add_i32 m0, s64, 0x2000
	s_nop 0
	global_load_lds_dwordx4 v[124:125], off
	v_lshl_add_u64 v[124:125], v[122:123], 0, s[22:23]
	s_mov_b32 m0, s45
	s_nop 0
	global_load_lds_dwordx4 v[124:125], off
	v_lshl_add_u64 v[124:125], v[122:123], 0, s[28:29]
	s_mov_b32 m0, s46
	s_nop 0
	global_load_lds_dwordx4 v[124:125], off
	v_lshl_add_u64 v[124:125], s[62:63], 0, v[0:1]
	s_mov_b32 m0, s39
	v_lshl_add_u64 v[126:127], v[124:125], 0, s[24:25]
	global_load_lds_dwordx4 v[124:125], off
	s_mov_b32 m0, s47
	s_nop 0
	global_load_lds_dwordx4 v[126:127], off
	s_waitcnt vmcnt(8)
	s_waitcnt lgkmcnt(0)
	s_barrier
	s_setprio 1
	v_mfma_f32_16x16x32_bf16 v[30:33], v[74:77], v[90:93], v[30:33]
	v_mfma_f32_16x16x32_bf16 v[26:29], v[82:85], v[90:93], v[26:29]
	v_mfma_f32_16x16x32_bf16 v[22:25], v[74:77], v[98:101], v[22:25]
	v_mfma_f32_16x16x32_bf16 v[18:21], v[82:85], v[98:101], v[18:21]
	v_mfma_f32_16x16x32_bf16 v[14:17], v[74:77], v[106:109], v[14:17]
	v_mfma_f32_16x16x32_bf16 v[10:13], v[82:85], v[106:109], v[10:13]
	v_mfma_f32_16x16x32_bf16 v[6:9], v[74:77], v[114:117], v[6:9]
	v_mfma_f32_16x16x32_bf16 v[2:5], v[82:85], v[114:117], v[2:5]
	v_mfma_f32_16x16x32_bf16 v[30:33], v[78:81], v[94:97], v[30:33]
	v_mfma_f32_16x16x32_bf16 v[26:29], v[86:89], v[94:97], v[26:29]
	v_mfma_f32_16x16x32_bf16 v[22:25], v[78:81], v[102:105], v[22:25]
	v_mfma_f32_16x16x32_bf16 v[18:21], v[86:89], v[102:105], v[18:21]
	v_mfma_f32_16x16x32_bf16 v[14:17], v[78:81], v[110:113], v[14:17]
	v_mfma_f32_16x16x32_bf16 v[10:13], v[86:89], v[110:113], v[10:13]
	v_mfma_f32_16x16x32_bf16 v[6:9], v[78:81], v[118:121], v[6:9]
	v_mfma_f32_16x16x32_bf16 v[2:5], v[86:89], v[118:121], v[2:5]
	s_setprio 0
	s_setprio 1
	s_setprio 0
	s_barrier
	s_add_i32 s62, 0, 0x18000
	v_add_u32_e32 v73, s62, v71
	ds_read_b128 v[74:77], v73
	ds_read_b128 v[78:81], v73 offset:1024
	ds_read_b128 v[82:85], v73 offset:2048
	ds_read_b128 v[86:89], v73 offset:3072
	s_mov_b32 m0, s52
	v_lshl_add_u64 v[126:127], v[124:125], 0, s[22:23]
	ds_read_b128 v[90:93], v72 offset:32768
	ds_read_b128 v[94:97], v72 offset:33792
	ds_read_b128 v[98:101], v72 offset:34816
	ds_read_b128 v[102:105], v72 offset:35840
	ds_read_b128 v[106:109], v72 offset:36864
	ds_read_b128 v[110:113], v72 offset:37888
	ds_read_b128 v[114:117], v72 offset:38912
	ds_read_b128 v[118:121], v72 offset:39936
	global_load_lds_dwordx4 v[126:127], off
	v_lshl_add_u64 v[126:127], v[124:125], 0, s[28:29]
	s_mov_b32 m0, s53
	s_nop 0
	global_load_lds_dwordx4 v[126:127], off
	s_waitcnt vmcnt(8)
	s_waitcnt lgkmcnt(0)
	s_barrier
	s_setprio 1
	v_mfma_f32_16x16x32_bf16 v[62:65], v[74:77], v[90:93], v[62:65]
	v_mfma_f32_16x16x32_bf16 v[58:61], v[82:85], v[90:93], v[58:61]
	v_mfma_f32_16x16x32_bf16 v[54:57], v[74:77], v[98:101], v[54:57]
	v_mfma_f32_16x16x32_bf16 v[50:53], v[82:85], v[98:101], v[50:53]
	v_mfma_f32_16x16x32_bf16 v[46:49], v[74:77], v[106:109], v[46:49]
	v_mfma_f32_16x16x32_bf16 v[42:45], v[82:85], v[106:109], v[42:45]
	v_mfma_f32_16x16x32_bf16 v[38:41], v[74:77], v[114:117], v[38:41]
	v_mfma_f32_16x16x32_bf16 v[34:37], v[82:85], v[114:117], v[34:37]
	v_mfma_f32_16x16x32_bf16 v[62:65], v[78:81], v[94:97], v[62:65]
	v_mfma_f32_16x16x32_bf16 v[58:61], v[86:89], v[94:97], v[58:61]
	v_mfma_f32_16x16x32_bf16 v[54:57], v[78:81], v[102:105], v[54:57]
	v_mfma_f32_16x16x32_bf16 v[50:53], v[86:89], v[102:105], v[50:53]
	v_mfma_f32_16x16x32_bf16 v[46:49], v[78:81], v[110:113], v[46:49]
	v_mfma_f32_16x16x32_bf16 v[42:45], v[86:89], v[110:113], v[42:45]
	v_mfma_f32_16x16x32_bf16 v[38:41], v[78:81], v[118:121], v[38:41]
	v_mfma_f32_16x16x32_bf16 v[34:37], v[86:89], v[118:121], v[34:37]
	s_setprio 0
	s_setprio 1
	s_setprio 0
	s_barrier
	s_add_i32 s62, s62, s36
	v_lshl_add_u64 v[126:127], v[122:123], 0, s[30:31]
	s_mov_b32 m0, s62
	ds_read_b128 v[90:93], v72 offset:49152
	ds_read_b128 v[94:97], v72 offset:50176
	ds_read_b128 v[98:101], v72 offset:51200
	ds_read_b128 v[102:105], v72 offset:52224
	ds_read_b128 v[106:109], v72 offset:53248
	ds_read_b128 v[110:113], v72 offset:54272
	ds_read_b128 v[114:117], v72 offset:55296
	ds_read_b128 v[118:121], v72 offset:56320
	global_load_lds_dwordx4 v[126:127], off
	v_lshl_add_u64 v[126:127], v[122:123], 0, s[34:35]
	s_add_i32 m0, s62, 0x2000
	s_nop 0
	global_load_lds_dwordx4 v[126:127], off
	v_lshl_add_u64 v[126:127], v[122:123], 0, s[88:89]
	s_mov_b32 m0, s57
	v_lshl_add_u64 v[122:123], v[122:123], 0, s[90:91]
	global_load_lds_dwordx4 v[126:127], off
	s_mov_b32 m0, s58
	s_nop 0
	global_load_lds_dwordx4 v[122:123], off
	v_lshl_add_u64 v[122:123], v[124:125], 0, s[30:31]
	s_mov_b32 m0, s54
	s_nop 0
	global_load_lds_dwordx4 v[122:123], off
	v_lshl_add_u64 v[122:123], v[124:125], 0, s[34:35]
	s_mov_b32 m0, s55
	s_nop 0
	global_load_lds_dwordx4 v[122:123], off
	s_waitcnt vmcnt(8)
	s_waitcnt lgkmcnt(0)
	s_barrier
	s_setprio 1
	v_mfma_f32_16x16x32_bf16 v[30:33], v[74:77], v[90:93], v[30:33]
	v_mfma_f32_16x16x32_bf16 v[26:29], v[82:85], v[90:93], v[26:29]
	v_mfma_f32_16x16x32_bf16 v[22:25], v[74:77], v[98:101], v[22:25]
	v_mfma_f32_16x16x32_bf16 v[18:21], v[82:85], v[98:101], v[18:21]
	v_mfma_f32_16x16x32_bf16 v[14:17], v[74:77], v[106:109], v[14:17]
	v_mfma_f32_16x16x32_bf16 v[10:13], v[82:85], v[106:109], v[10:13]
	v_mfma_f32_16x16x32_bf16 v[6:9], v[74:77], v[114:117], v[6:9]
	v_mfma_f32_16x16x32_bf16 v[2:5], v[82:85], v[114:117], v[2:5]
	v_mfma_f32_16x16x32_bf16 v[30:33], v[78:81], v[94:97], v[30:33]
	v_mfma_f32_16x16x32_bf16 v[26:29], v[86:89], v[94:97], v[26:29]
	v_mfma_f32_16x16x32_bf16 v[22:25], v[78:81], v[102:105], v[22:25]
	v_mfma_f32_16x16x32_bf16 v[18:21], v[86:89], v[102:105], v[18:21]
	v_mfma_f32_16x16x32_bf16 v[14:17], v[78:81], v[110:113], v[14:17]
	v_mfma_f32_16x16x32_bf16 v[10:13], v[86:89], v[110:113], v[10:13]
	v_mfma_f32_16x16x32_bf16 v[6:9], v[78:81], v[118:121], v[6:9]
	v_mfma_f32_16x16x32_bf16 v[2:5], v[86:89], v[118:121], v[2:5]
	s_setprio 0
	s_setprio 1
	s_setprio 0
	s_barrier
	s_add_i32 s20, s20, 2
	s_add_u32 s16, s16, 0x100
	s_addc_u32 s17, s17, 0
	s_add_u32 s18, s18, 0x100
	s_addc_u32 s19, s19, 0
	s_cmp_gt_u32 s20, 5
	s_cbranch_scc0 .LBB0_1490
	s_and_b64 vcc, exec, s[4:5]
	s_cbranch_vccz .LBB0_1493
	s_barrier

.LBB0_1509:
	s_add_u32 s18, s16, 0xfff80080
	s_addc_u32 s19, s17, -1
	s_add_i32 s59, 0, 0x10000
	s_cmp_eq_u32 s58, 4
	s_cselect_b32 s19, s13, s19
	s_cselect_b32 s18, s12, s18
	v_add_u32_e32 v139, s59, v137
	s_cselect_b32 s61, s11, s57
	s_cselect_b32 s60, s20, s55
	s_add_i32 s62, 0, 0x14000
	ds_read_b128 v[140:143], v139
	ds_read_b128 v[144:147], v139 offset:1024
	ds_read_b128 v[148:151], v139 offset:2048
	ds_read_b128 v[152:155], v139 offset:3072
	v_add_u32_e32 v139, s62, v137
	ds_read_b128 v[172:175], v139
	ds_read_b128 v[176:179], v139 offset:1024
	ds_read_b128 v[190:193], v139 offset:2048
	ds_read_b128 v[194:197], v139 offset:3072
	v_lshl_add_u64 v[156:157], s[16:17], 0, v[134:135]
	s_add_i32 m0, s44, 0xc000
	ds_read_b128 v[198:201], v138
	ds_read_b128 v[202:205], v138 offset:1024
	ds_read_b128 v[206:209], v138 offset:2048
	ds_read_b128 v[210:213], v138 offset:3072
	ds_read_b128 v[214:217], v138 offset:4096
	ds_read_b128 v[218:221], v138 offset:5120
	ds_read_b128 v[222:225], v138 offset:6144
	ds_read_b128 v[226:229], v138 offset:7168
	global_load_lds_dwordx4 v[156:157], off
	v_lshl_add_u64 v[156:157], v[156:157], 0, s[48:49]
	s_add_i32 m0, s44, 0xe000
	s_nop 0
	global_load_lds_dwordx4 v[156:157], off
	s_waitcnt vmcnt(8)
	s_waitcnt lgkmcnt(0)
	s_barrier
	s_setprio 1
	v_mfma_f32_16x16x32_bf16 v[126:129], v[140:143], v[198:201], v[126:129]
	v_mfma_f32_16x16x32_bf16 v[122:125], v[148:151], v[198:201], v[122:125]
	v_mfma_f32_16x16x32_bf16 v[118:121], v[140:143], v[206:209], v[118:121]
	v_mfma_f32_16x16x32_bf16 v[114:117], v[148:151], v[206:209], v[114:117]
	v_mfma_f32_16x16x32_bf16 v[106:109], v[140:143], v[214:217], v[106:109]
	v_mfma_f32_16x16x32_bf16 v[98:101], v[148:151], v[214:217], v[98:101]
	v_mfma_f32_16x16x32_bf16 v[90:93], v[140:143], v[222:225], v[90:93]
	v_mfma_f32_16x16x32_bf16 v[82:85], v[148:151], v[222:225], v[82:85]
	v_mfma_f32_16x16x32_bf16 v[126:129], v[144:147], v[202:205], v[126:129]
	v_mfma_f32_16x16x32_bf16 v[122:125], v[152:155], v[202:205], v[122:125]
	v_mfma_f32_16x16x32_bf16 v[118:121], v[144:147], v[210:213], v[118:121]
	v_mfma_f32_16x16x32_bf16 v[114:117], v[152:155], v[210:213], v[114:117]
	v_mfma_f32_16x16x32_bf16 v[106:109], v[144:147], v[218:221], v[106:109]
	v_mfma_f32_16x16x32_bf16 v[98:101], v[152:155], v[218:221], v[98:101]
	v_mfma_f32_16x16x32_bf16 v[90:93], v[144:147], v[226:229], v[90:93]
	v_mfma_f32_16x16x32_bf16 v[82:85], v[152:155], v[226:229], v[82:85]
	s_setprio 0
	s_setprio 1
	v_mfma_f32_16x16x32_bf16 v[110:113], v[172:175], v[198:201], v[110:113]
	v_mfma_f32_16x16x32_bf16 v[102:105], v[190:193], v[198:201], v[102:105]
	v_mfma_f32_16x16x32_bf16 v[94:97], v[172:175], v[206:209], v[94:97]
	v_mfma_f32_16x16x32_bf16 v[86:89], v[190:193], v[206:209], v[86:89]
	v_mfma_f32_16x16x32_bf16 v[78:81], v[172:175], v[214:217], v[78:81]
	v_mfma_f32_16x16x32_bf16 v[74:77], v[190:193], v[214:217], v[74:77]
	v_mfma_f32_16x16x32_bf16 v[70:73], v[172:175], v[222:225], v[70:73]
	v_mfma_f32_16x16x32_bf16 v[66:69], v[190:193], v[222:225], v[66:69]
	v_mfma_f32_16x16x32_bf16 v[110:113], v[176:179], v[202:205], v[110:113]
	v_mfma_f32_16x16x32_bf16 v[102:105], v[194:197], v[202:205], v[102:105]
	v_mfma_f32_16x16x32_bf16 v[94:97], v[176:179], v[210:213], v[94:97]
	v_mfma_f32_16x16x32_bf16 v[86:89], v[194:197], v[210:213], v[86:89]
	v_mfma_f32_16x16x32_bf16 v[78:81], v[176:179], v[218:221], v[78:81]
	v_mfma_f32_16x16x32_bf16 v[74:77], v[194:197], v[218:221], v[74:77]
	v_mfma_f32_16x16x32_bf16 v[70:73], v[176:179], v[226:229], v[70:73]
	v_mfma_f32_16x16x32_bf16 v[66:69], v[194:197], v[226:229], v[66:69]
	s_setprio 0
	s_barrier
	s_add_i32 s59, s59, s43
	v_lshl_add_u64 v[156:157], s[60:61], 0, v[0:1]
	s_mov_b32 m0, s59
	ds_read_b128 v[198:201], v138 offset:16384
	ds_read_b128 v[202:205], v138 offset:17408
	ds_read_b128 v[206:209], v138 offset:18432
	ds_read_b128 v[210:213], v138 offset:19456
	ds_read_b128 v[214:217], v138 offset:20480
	ds_read_b128 v[218:221], v138 offset:21504
	ds_read_b128 v[222:225], v138 offset:22528
	ds_read_b128 v[226:229], v138 offset:23552
	global_load_lds_dwordx4 v[156:157], off
	v_lshl_add_u64 v[158:159], v[156:157], 0, s[24:25]
	s_add_i32 m0, s59, 0x2000
	s_add_i32 s59, s62, s43
	global_load_lds_dwordx4 v[158:159], off
	v_lshl_add_u64 v[158:159], v[156:157], 0, s[22:23]
	s_mov_b32 m0, s59
	s_nop 0
	global_load_lds_dwordx4 v[158:159], off
	v_lshl_add_u64 v[158:159], v[156:157], 0, s[28:29]
	s_add_i32 m0, s59, 0x2000
	s_nop 0
	global_load_lds_dwordx4 v[158:159], off
	v_lshl_add_u64 v[158:159], s[18:19], 0, v[130:131]
	s_mov_b32 m0, s44
	v_lshl_add_u64 v[160:161], v[158:159], 0, s[48:49]
	global_load_lds_dwordx4 v[158:159], off
	s_mov_b32 m0, s45
	s_nop 0
	global_load_lds_dwordx4 v[160:161], off
	s_waitcnt vmcnt(8)
	s_waitcnt lgkmcnt(0)
	s_barrier
	s_setprio 1
	v_mfma_f32_16x16x32_bf16 v[62:65], v[140:143], v[198:201], v[62:65]
	v_mfma_f32_16x16x32_bf16 v[58:61], v[148:151], v[198:201], v[58:61]
	v_mfma_f32_16x16x32_bf16 v[54:57], v[140:143], v[206:209], v[54:57]
	v_mfma_f32_16x16x32_bf16 v[50:53], v[148:151], v[206:209], v[50:53]
	v_mfma_f32_16x16x32_bf16 v[38:41], v[140:143], v[214:217], v[38:41]
	v_mfma_f32_16x16x32_bf16 v[34:37], v[148:151], v[214:217], v[34:37]
	v_mfma_f32_16x16x32_bf16 v[22:25], v[140:143], v[222:225], v[22:25]
	v_mfma_f32_16x16x32_bf16 v[18:21], v[148:151], v[222:225], v[18:21]
	v_mfma_f32_16x16x32_bf16 v[62:65], v[144:147], v[202:205], v[62:65]
	v_mfma_f32_16x16x32_bf16 v[58:61], v[152:155], v[202:205], v[58:61]
	v_mfma_f32_16x16x32_bf16 v[54:57], v[144:147], v[210:213], v[54:57]
	v_mfma_f32_16x16x32_bf16 v[50:53], v[152:155], v[210:213], v[50:53]
	v_mfma_f32_16x16x32_bf16 v[38:41], v[144:147], v[218:221], v[38:41]
	v_mfma_f32_16x16x32_bf16 v[34:37], v[152:155], v[218:221], v[34:37]
	v_mfma_f32_16x16x32_bf16 v[22:25], v[144:147], v[226:229], v[22:25]
	v_mfma_f32_16x16x32_bf16 v[18:21], v[152:155], v[226:229], v[18:21]
	s_setprio 0
	s_setprio 1
	v_mfma_f32_16x16x32_bf16 v[46:49], v[172:175], v[198:201], v[46:49]
	v_mfma_f32_16x16x32_bf16 v[42:45], v[190:193], v[198:201], v[42:45]
	v_mfma_f32_16x16x32_bf16 v[30:33], v[172:175], v[206:209], v[30:33]
	v_mfma_f32_16x16x32_bf16 v[26:29], v[190:193], v[206:209], v[26:29]
	v_mfma_f32_16x16x32_bf16 v[14:17], v[172:175], v[214:217], v[14:17]
	v_mfma_f32_16x16x32_bf16 v[10:13], v[190:193], v[214:217], v[10:13]
	v_mfma_f32_16x16x32_bf16 v[6:9], v[172:175], v[222:225], v[6:9]
	v_mfma_f32_16x16x32_bf16 v[2:5], v[190:193], v[222:225], v[2:5]
	v_mfma_f32_16x16x32_bf16 v[46:49], v[176:179], v[202:205], v[46:49]
	v_mfma_f32_16x16x32_bf16 v[42:45], v[194:197], v[202:205], v[42:45]
	v_mfma_f32_16x16x32_bf16 v[30:33], v[176:179], v[210:213], v[30:33]
	v_mfma_f32_16x16x32_bf16 v[26:29], v[194:197], v[210:213], v[26:29]
	v_mfma_f32_16x16x32_bf16 v[14:17], v[176:179], v[218:221], v[14:17]
	v_mfma_f32_16x16x32_bf16 v[10:13], v[194:197], v[218:221], v[10:13]
	v_mfma_f32_16x16x32_bf16 v[6:9], v[176:179], v[226:229], v[6:9]
	v_mfma_f32_16x16x32_bf16 v[2:5], v[194:197], v[226:229], v[2:5]
	s_setprio 0
	s_barrier
	s_add_i32 s18, 0, 0x18000
	v_add_u32_e32 v139, s18, v137
	s_add_i32 s19, 0, 0x1c000
	ds_read_b128 v[140:143], v139
	ds_read_b128 v[144:147], v139 offset:1024
	ds_read_b128 v[148:151], v139 offset:2048
	ds_read_b128 v[152:155], v139 offset:3072
	v_add_u32_e32 v139, s19, v137
	ds_read_b128 v[172:175], v139
	ds_read_b128 v[176:179], v139 offset:1024
	ds_read_b128 v[190:193], v139 offset:2048
	ds_read_b128 v[194:197], v139 offset:3072
	s_mov_b32 m0, s46
	v_lshl_add_u64 v[160:161], v[158:159], 0, s[24:25]
	ds_read_b128 v[198:201], v138 offset:32768
	ds_read_b128 v[202:205], v138 offset:33792
	ds_read_b128 v[206:209], v138 offset:34816
	ds_read_b128 v[210:213], v138 offset:35840
	ds_read_b128 v[214:217], v138 offset:36864
	ds_read_b128 v[218:221], v138 offset:37888
	ds_read_b128 v[222:225], v138 offset:38912
	ds_read_b128 v[226:229], v138 offset:39936
	global_load_lds_dwordx4 v[160:161], off
	v_lshl_add_u64 v[160:161], v[158:159], 0, s[64:65]
	s_mov_b32 m0, s47
	s_nop 0
	global_load_lds_dwordx4 v[160:161], off
	s_waitcnt vmcnt(8)
	s_waitcnt lgkmcnt(0)
	s_barrier
	s_setprio 1
	v_mfma_f32_16x16x32_bf16 v[126:129], v[140:143], v[198:201], v[126:129]
	v_mfma_f32_16x16x32_bf16 v[122:125], v[148:151], v[198:201], v[122:125]
	v_mfma_f32_16x16x32_bf16 v[118:121], v[140:143], v[206:209], v[118:121]
	v_mfma_f32_16x16x32_bf16 v[114:117], v[148:151], v[206:209], v[114:117]
	v_mfma_f32_16x16x32_bf16 v[106:109], v[140:143], v[214:217], v[106:109]
	v_mfma_f32_16x16x32_bf16 v[98:101], v[148:151], v[214:217], v[98:101]
	v_mfma_f32_16x16x32_bf16 v[90:93], v[140:143], v[222:225], v[90:93]
	v_mfma_f32_16x16x32_bf16 v[82:85], v[148:151], v[222:225], v[82:85]
	v_mfma_f32_16x16x32_bf16 v[126:129], v[144:147], v[202:205], v[126:129]
	v_mfma_f32_16x16x32_bf16 v[122:125], v[152:155], v[202:205], v[122:125]
	v_mfma_f32_16x16x32_bf16 v[118:121], v[144:147], v[210:213], v[118:121]
	v_mfma_f32_16x16x32_bf16 v[114:117], v[152:155], v[210:213], v[114:117]
	v_mfma_f32_16x16x32_bf16 v[106:109], v[144:147], v[218:221], v[106:109]
	v_mfma_f32_16x16x32_bf16 v[98:101], v[152:155], v[218:221], v[98:101]
	v_mfma_f32_16x16x32_bf16 v[90:93], v[144:147], v[226:229], v[90:93]
	v_mfma_f32_16x16x32_bf16 v[82:85], v[152:155], v[226:229], v[82:85]
	s_setprio 0
	s_setprio 1
	v_mfma_f32_16x16x32_bf16 v[110:113], v[172:175], v[198:201], v[110:113]
	v_mfma_f32_16x16x32_bf16 v[102:105], v[190:193], v[198:201], v[102:105]
	v_mfma_f32_16x16x32_bf16 v[94:97], v[172:175], v[206:209], v[94:97]
	v_mfma_f32_16x16x32_bf16 v[86:89], v[190:193], v[206:209], v[86:89]
	v_mfma_f32_16x16x32_bf16 v[78:81], v[172:175], v[214:217], v[78:81]
	v_mfma_f32_16x16x32_bf16 v[74:77], v[190:193], v[214:217], v[74:77]
	v_mfma_f32_16x16x32_bf16 v[70:73], v[172:175], v[222:225], v[70:73]
	v_mfma_f32_16x16x32_bf16 v[66:69], v[190:193], v[222:225], v[66:69]
	v_mfma_f32_16x16x32_bf16 v[110:113], v[176:179], v[202:205], v[110:113]
	v_mfma_f32_16x16x32_bf16 v[102:105], v[194:197], v[202:205], v[102:105]
	v_mfma_f32_16x16x32_bf16 v[94:97], v[176:179], v[210:213], v[94:97]
	v_mfma_f32_16x16x32_bf16 v[86:89], v[194:197], v[210:213], v[86:89]
	v_mfma_f32_16x16x32_bf16 v[78:81], v[176:179], v[218:221], v[78:81]
	v_mfma_f32_16x16x32_bf16 v[74:77], v[194:197], v[218:221], v[74:77]
	v_mfma_f32_16x16x32_bf16 v[70:73], v[176:179], v[226:229], v[70:73]
	v_mfma_f32_16x16x32_bf16 v[66:69], v[194:197], v[226:229], v[66:69]
	s_setprio 0
	s_barrier
	s_add_i32 s18, s18, s43
	v_lshl_add_u64 v[160:161], v[156:157], 0, s[30:31]
	s_mov_b32 m0, s18
	ds_read_b128 v[198:201], v138 offset:49152
	ds_read_b128 v[202:205], v138 offset:50176
	ds_read_b128 v[206:209], v138 offset:51200
	ds_read_b128 v[210:213], v138 offset:52224
	ds_read_b128 v[214:217], v138 offset:53248
	ds_read_b128 v[218:221], v138 offset:54272
	ds_read_b128 v[222:225], v138 offset:55296
	ds_read_b128 v[226:229], v138 offset:56320
	global_load_lds_dwordx4 v[160:161], off
	v_lshl_add_u64 v[160:161], v[156:157], 0, s[34:35]
	s_add_i32 m0, s18, 0x2000
	s_add_i32 s18, s19, s43
	global_load_lds_dwordx4 v[160:161], off
	v_lshl_add_u64 v[160:161], v[156:157], 0, s[88:89]
	s_mov_b32 m0, s18
	v_lshl_add_u64 v[156:157], v[156:157], 0, s[90:91]
	global_load_lds_dwordx4 v[160:161], off
	s_add_i32 m0, s18, 0x2000
	s_nop 0
	global_load_lds_dwordx4 v[156:157], off
	v_lshl_add_u64 v[156:157], v[158:159], 0, s[30:31]
	s_mov_b32 m0, s52
	s_nop 0
	global_load_lds_dwordx4 v[156:157], off
	v_lshl_add_u64 v[156:157], v[158:159], 0, s[66:67]
	s_mov_b32 m0, s53
	s_nop 0
	global_load_lds_dwordx4 v[156:157], off
	s_waitcnt vmcnt(8)
	s_waitcnt lgkmcnt(0)
	s_barrier
	s_setprio 1
	v_mfma_f32_16x16x32_bf16 v[62:65], v[140:143], v[198:201], v[62:65]
	v_mfma_f32_16x16x32_bf16 v[58:61], v[148:151], v[198:201], v[58:61]
	v_mfma_f32_16x16x32_bf16 v[54:57], v[140:143], v[206:209], v[54:57]
	v_mfma_f32_16x16x32_bf16 v[50:53], v[148:151], v[206:209], v[50:53]
	v_mfma_f32_16x16x32_bf16 v[38:41], v[140:143], v[214:217], v[38:41]
	v_mfma_f32_16x16x32_bf16 v[34:37], v[148:151], v[214:217], v[34:37]
	v_mfma_f32_16x16x32_bf16 v[22:25], v[140:143], v[222:225], v[22:25]
	v_mfma_f32_16x16x32_bf16 v[18:21], v[148:151], v[222:225], v[18:21]
	v_mfma_f32_16x16x32_bf16 v[62:65], v[144:147], v[202:205], v[62:65]
	v_mfma_f32_16x16x32_bf16 v[58:61], v[152:155], v[202:205], v[58:61]
	v_mfma_f32_16x16x32_bf16 v[54:57], v[144:147], v[210:213], v[54:57]
	v_mfma_f32_16x16x32_bf16 v[50:53], v[152:155], v[210:213], v[50:53]
	v_mfma_f32_16x16x32_bf16 v[38:41], v[144:147], v[218:221], v[38:41]
	v_mfma_f32_16x16x32_bf16 v[34:37], v[152:155], v[218:221], v[34:37]
	v_mfma_f32_16x16x32_bf16 v[22:25], v[144:147], v[226:229], v[22:25]
	v_mfma_f32_16x16x32_bf16 v[18:21], v[152:155], v[226:229], v[18:21]
	s_setprio 0
	s_setprio 1
	v_mfma_f32_16x16x32_bf16 v[46:49], v[172:175], v[198:201], v[46:49]
	v_mfma_f32_16x16x32_bf16 v[42:45], v[190:193], v[198:201], v[42:45]
	v_mfma_f32_16x16x32_bf16 v[30:33], v[172:175], v[206:209], v[30:33]
	v_mfma_f32_16x16x32_bf16 v[26:29], v[190:193], v[206:209], v[26:29]
	v_mfma_f32_16x16x32_bf16 v[14:17], v[172:175], v[214:217], v[14:17]
	v_mfma_f32_16x16x32_bf16 v[10:13], v[190:193], v[214:217], v[10:13]
	v_mfma_f32_16x16x32_bf16 v[6:9], v[172:175], v[222:225], v[6:9]
	v_mfma_f32_16x16x32_bf16 v[2:5], v[190:193], v[222:225], v[2:5]
	v_mfma_f32_16x16x32_bf16 v[46:49], v[176:179], v[202:205], v[46:49]
	v_mfma_f32_16x16x32_bf16 v[42:45], v[194:197], v[202:205], v[42:45]
	v_mfma_f32_16x16x32_bf16 v[30:33], v[176:179], v[210:213], v[30:33]
	v_mfma_f32_16x16x32_bf16 v[26:29], v[194:197], v[210:213], v[26:29]
	v_mfma_f32_16x16x32_bf16 v[14:17], v[176:179], v[218:221], v[14:17]
	v_mfma_f32_16x16x32_bf16 v[10:13], v[194:197], v[218:221], v[10:13]
	v_mfma_f32_16x16x32_bf16 v[6:9], v[176:179], v[226:229], v[6:9]
	v_mfma_f32_16x16x32_bf16 v[2:5], v[194:197], v[226:229], v[2:5]
	s_setprio 0
	s_barrier
	s_add_i32 s58, s58, 2
	s_add_u32 s16, s16, 0x100
	s_addc_u32 s17, s17, 0
	s_add_u32 s55, s55, 0x100
	s_addc_u32 s57, s57, 0
	s_cmp_gt_u32 s58, 5
	s_cbranch_scc0 .LBB0_1509
	s_and_b64 vcc, exec, s[4:5]
	s_cbranch_vccz .LBB0_1512
	s_barrier

.LBB0_3117:
	s_add_u32 s40, s38, 0xfff00080
	s_addc_u32 s41, s39, -1
	s_add_i32 s69, 0, 0x10000
	s_cmp_eq_u32 s68, 60
	s_cselect_b32 s41, s17, s41
	s_cselect_b32 s40, s64, s40
	v_add_u32_e32 v145, s69, v155
	s_cselect_b32 s71, s15, s67
	s_cselect_b32 s70, s65, s66
	s_add_i32 s72, 0, 0x14000
	ds_read_b128 v[130:133], v145
	ds_read_b128 v[134:137], v145 offset:1024
	ds_read_b128 v[148:151], v145 offset:2048
	ds_read_b128 v[164:167], v145 offset:3072
	v_add_u32_e32 v145, s72, v155
	ds_read_b128 v[172:175], v145
	ds_read_b128 v[176:179], v145 offset:1024
	ds_read_b128 v[190:193], v145 offset:2048
	ds_read_b128 v[194:197], v145 offset:3072
	v_lshl_add_u64 v[152:153], s[38:39], 0, v[142:143]
	s_add_i32 m0, s54, 0xc000
	ds_read_b128 v[198:201], v157
	ds_read_b128 v[202:205], v157 offset:1024
	ds_read_b128 v[206:209], v157 offset:2048
	ds_read_b128 v[210:213], v157 offset:3072
	ds_read_b128 v[214:217], v157 offset:4096
	ds_read_b128 v[218:221], v157 offset:5120
	ds_read_b128 v[222:225], v157 offset:6144
	ds_read_b128 v[226:229], v157 offset:7168
	global_load_lds_dwordx4 v[152:153], off
	v_lshl_add_u64 v[152:153], v[152:153], 0, s[24:25]
	s_add_i32 m0, s54, 0xe000
	s_nop 0
	global_load_lds_dwordx4 v[152:153], off
	s_waitcnt vmcnt(8)
	s_waitcnt lgkmcnt(0)
	s_barrier
	s_setprio 1
	v_mfma_f32_16x16x32_bf16 v[126:129], v[130:133], v[198:201], v[126:129]
	v_mfma_f32_16x16x32_bf16 v[122:125], v[148:151], v[198:201], v[122:125]
	v_mfma_f32_16x16x32_bf16 v[110:113], v[130:133], v[206:209], v[110:113]
	v_mfma_f32_16x16x32_bf16 v[106:109], v[148:151], v[206:209], v[106:109]
	v_mfma_f32_16x16x32_bf16 v[94:97], v[130:133], v[214:217], v[94:97]
	v_mfma_f32_16x16x32_bf16 v[90:93], v[148:151], v[214:217], v[90:93]
	v_mfma_f32_16x16x32_bf16 v[78:81], v[130:133], v[222:225], v[78:81]
	v_mfma_f32_16x16x32_bf16 v[74:77], v[148:151], v[222:225], v[74:77]
	v_mfma_f32_16x16x32_bf16 v[126:129], v[134:137], v[202:205], v[126:129]
	v_mfma_f32_16x16x32_bf16 v[122:125], v[164:167], v[202:205], v[122:125]
	v_mfma_f32_16x16x32_bf16 v[110:113], v[134:137], v[210:213], v[110:113]
	v_mfma_f32_16x16x32_bf16 v[106:109], v[164:167], v[210:213], v[106:109]
	v_mfma_f32_16x16x32_bf16 v[94:97], v[134:137], v[218:221], v[94:97]
	v_mfma_f32_16x16x32_bf16 v[90:93], v[164:167], v[218:221], v[90:93]
	v_mfma_f32_16x16x32_bf16 v[78:81], v[134:137], v[226:229], v[78:81]
	v_mfma_f32_16x16x32_bf16 v[74:77], v[164:167], v[226:229], v[74:77]
	s_setprio 0
	s_setprio 1
	v_mfma_f32_16x16x32_bf16 v[118:121], v[172:175], v[198:201], v[118:121]
	v_mfma_f32_16x16x32_bf16 v[114:117], v[190:193], v[198:201], v[114:117]
	v_mfma_f32_16x16x32_bf16 v[102:105], v[172:175], v[206:209], v[102:105]
	v_mfma_f32_16x16x32_bf16 v[98:101], v[190:193], v[206:209], v[98:101]
	v_mfma_f32_16x16x32_bf16 v[86:89], v[172:175], v[214:217], v[86:89]
	v_mfma_f32_16x16x32_bf16 v[82:85], v[190:193], v[214:217], v[82:85]
	v_mfma_f32_16x16x32_bf16 v[70:73], v[172:175], v[222:225], v[70:73]
	v_mfma_f32_16x16x32_bf16 v[66:69], v[190:193], v[222:225], v[66:69]
	v_mfma_f32_16x16x32_bf16 v[118:121], v[176:179], v[202:205], v[118:121]
	v_mfma_f32_16x16x32_bf16 v[114:117], v[194:197], v[202:205], v[114:117]
	v_mfma_f32_16x16x32_bf16 v[102:105], v[176:179], v[210:213], v[102:105]
	v_mfma_f32_16x16x32_bf16 v[98:101], v[194:197], v[210:213], v[98:101]
	v_mfma_f32_16x16x32_bf16 v[86:89], v[176:179], v[218:221], v[86:89]
	v_mfma_f32_16x16x32_bf16 v[82:85], v[194:197], v[218:221], v[82:85]
	v_mfma_f32_16x16x32_bf16 v[70:73], v[176:179], v[226:229], v[70:73]
	v_mfma_f32_16x16x32_bf16 v[66:69], v[194:197], v[226:229], v[66:69]
	s_setprio 0
	s_barrier
	s_add_i32 s69, s69, s43
	v_lshl_add_u64 v[152:153], s[70:71], 0, v[140:141]
	s_mov_b32 m0, s69
	ds_read_b128 v[198:201], v157 offset:16384
	ds_read_b128 v[202:205], v157 offset:17408
	ds_read_b128 v[206:209], v157 offset:18432
	ds_read_b128 v[210:213], v157 offset:19456
	ds_read_b128 v[214:217], v157 offset:20480
	ds_read_b128 v[218:221], v157 offset:21504
	ds_read_b128 v[222:225], v157 offset:22528
	ds_read_b128 v[226:229], v157 offset:23552
	global_load_lds_dwordx4 v[152:153], off
	v_lshl_add_u64 v[180:181], v[152:153], 0, s[24:25]
	s_add_i32 m0, s69, 0x2000
	s_add_i32 s69, s72, s43
	global_load_lds_dwordx4 v[180:181], off
	v_lshl_add_u64 v[180:181], v[152:153], 0, s[22:23]
	s_mov_b32 m0, s69
	s_nop 0
	global_load_lds_dwordx4 v[180:181], off
	v_lshl_add_u64 v[180:181], v[152:153], 0, s[28:29]
	s_add_i32 m0, s69, 0x2000
	s_nop 0
	global_load_lds_dwordx4 v[180:181], off
	v_lshl_add_u64 v[180:181], s[40:41], 0, v[138:139]
	s_mov_b32 m0, s54
	v_lshl_add_u64 v[230:231], v[180:181], 0, s[24:25]
	global_load_lds_dwordx4 v[180:181], off
	s_mov_b32 m0, s55
	s_nop 0
	global_load_lds_dwordx4 v[230:231], off
	s_waitcnt vmcnt(8)
	s_waitcnt lgkmcnt(0)
	s_barrier
	s_setprio 1
	v_mfma_f32_16x16x32_bf16 v[62:65], v[130:133], v[198:201], v[62:65]
	v_mfma_f32_16x16x32_bf16 v[58:61], v[148:151], v[198:201], v[58:61]
	v_mfma_f32_16x16x32_bf16 v[46:49], v[130:133], v[206:209], v[46:49]
	v_mfma_f32_16x16x32_bf16 v[42:45], v[148:151], v[206:209], v[42:45]
	v_mfma_f32_16x16x32_bf16 v[30:33], v[130:133], v[214:217], v[30:33]
	v_mfma_f32_16x16x32_bf16 v[26:29], v[148:151], v[214:217], v[26:29]
	v_mfma_f32_16x16x32_bf16 v[14:17], v[130:133], v[222:225], v[14:17]
	v_mfma_f32_16x16x32_bf16 v[10:13], v[148:151], v[222:225], v[10:13]
	v_mfma_f32_16x16x32_bf16 v[62:65], v[134:137], v[202:205], v[62:65]
	v_mfma_f32_16x16x32_bf16 v[58:61], v[164:167], v[202:205], v[58:61]
	v_mfma_f32_16x16x32_bf16 v[46:49], v[134:137], v[210:213], v[46:49]
	v_mfma_f32_16x16x32_bf16 v[42:45], v[164:167], v[210:213], v[42:45]
	v_mfma_f32_16x16x32_bf16 v[30:33], v[134:137], v[218:221], v[30:33]
	v_mfma_f32_16x16x32_bf16 v[26:29], v[164:167], v[218:221], v[26:29]
	v_mfma_f32_16x16x32_bf16 v[14:17], v[134:137], v[226:229], v[14:17]
	v_mfma_f32_16x16x32_bf16 v[10:13], v[164:167], v[226:229], v[10:13]
	s_setprio 0
	s_setprio 1
	v_mfma_f32_16x16x32_bf16 v[54:57], v[172:175], v[198:201], v[54:57]
	v_mfma_f32_16x16x32_bf16 v[50:53], v[190:193], v[198:201], v[50:53]
	v_mfma_f32_16x16x32_bf16 v[38:41], v[172:175], v[206:209], v[38:41]
	v_mfma_f32_16x16x32_bf16 v[34:37], v[190:193], v[206:209], v[34:37]
	v_mfma_f32_16x16x32_bf16 v[22:25], v[172:175], v[214:217], v[22:25]
	v_mfma_f32_16x16x32_bf16 v[18:21], v[190:193], v[214:217], v[18:21]
	v_mfma_f32_16x16x32_bf16 v[6:9], v[172:175], v[222:225], v[6:9]
	v_mfma_f32_16x16x32_bf16 v[2:5], v[190:193], v[222:225], v[2:5]
	v_mfma_f32_16x16x32_bf16 v[54:57], v[176:179], v[202:205], v[54:57]
	v_mfma_f32_16x16x32_bf16 v[50:53], v[194:197], v[202:205], v[50:53]
	v_mfma_f32_16x16x32_bf16 v[38:41], v[176:179], v[210:213], v[38:41]
	v_mfma_f32_16x16x32_bf16 v[34:37], v[194:197], v[210:213], v[34:37]
	v_mfma_f32_16x16x32_bf16 v[22:25], v[176:179], v[218:221], v[22:25]
	v_mfma_f32_16x16x32_bf16 v[18:21], v[194:197], v[218:221], v[18:21]
	v_mfma_f32_16x16x32_bf16 v[6:9], v[176:179], v[226:229], v[6:9]
	v_mfma_f32_16x16x32_bf16 v[2:5], v[194:197], v[226:229], v[2:5]
	s_setprio 0
	s_barrier
	s_add_i32 s40, 0, 0x18000
	v_add_u32_e32 v145, s40, v155
	s_add_i32 s41, 0, 0x1c000
	ds_read_b128 v[130:133], v145
	ds_read_b128 v[134:137], v145 offset:1024
	ds_read_b128 v[148:151], v145 offset:2048
	ds_read_b128 v[164:167], v145 offset:3072
	v_add_u32_e32 v145, s41, v155
	ds_read_b128 v[172:175], v145
	ds_read_b128 v[176:179], v145 offset:1024
	ds_read_b128 v[190:193], v145 offset:2048
	ds_read_b128 v[194:197], v145 offset:3072
	s_mov_b32 m0, s57
	v_lshl_add_u64 v[230:231], v[180:181], 0, s[22:23]
	ds_read_b128 v[198:201], v157 offset:32768
	ds_read_b128 v[202:205], v157 offset:33792
	ds_read_b128 v[206:209], v157 offset:34816
	ds_read_b128 v[210:213], v157 offset:35840
	ds_read_b128 v[214:217], v157 offset:36864
	ds_read_b128 v[218:221], v157 offset:37888
	ds_read_b128 v[222:225], v157 offset:38912
	ds_read_b128 v[226:229], v157 offset:39936
	global_load_lds_dwordx4 v[230:231], off
	v_lshl_add_u64 v[230:231], v[180:181], 0, s[28:29]
	s_mov_b32 m0, s58
	s_nop 0
	global_load_lds_dwordx4 v[230:231], off
	s_waitcnt vmcnt(8)
	s_waitcnt lgkmcnt(0)
	s_barrier
	s_setprio 1
	v_mfma_f32_16x16x32_bf16 v[126:129], v[130:133], v[198:201], v[126:129]
	v_mfma_f32_16x16x32_bf16 v[122:125], v[148:151], v[198:201], v[122:125]
	v_mfma_f32_16x16x32_bf16 v[110:113], v[130:133], v[206:209], v[110:113]
	v_mfma_f32_16x16x32_bf16 v[106:109], v[148:151], v[206:209], v[106:109]
	v_mfma_f32_16x16x32_bf16 v[94:97], v[130:133], v[214:217], v[94:97]
	v_mfma_f32_16x16x32_bf16 v[90:93], v[148:151], v[214:217], v[90:93]
	v_mfma_f32_16x16x32_bf16 v[78:81], v[130:133], v[222:225], v[78:81]
	v_mfma_f32_16x16x32_bf16 v[74:77], v[148:151], v[222:225], v[74:77]
	v_mfma_f32_16x16x32_bf16 v[126:129], v[134:137], v[202:205], v[126:129]
	v_mfma_f32_16x16x32_bf16 v[122:125], v[164:167], v[202:205], v[122:125]
	v_mfma_f32_16x16x32_bf16 v[110:113], v[134:137], v[210:213], v[110:113]
	v_mfma_f32_16x16x32_bf16 v[106:109], v[164:167], v[210:213], v[106:109]
	v_mfma_f32_16x16x32_bf16 v[94:97], v[134:137], v[218:221], v[94:97]
	v_mfma_f32_16x16x32_bf16 v[90:93], v[164:167], v[218:221], v[90:93]
	v_mfma_f32_16x16x32_bf16 v[78:81], v[134:137], v[226:229], v[78:81]
	v_mfma_f32_16x16x32_bf16 v[74:77], v[164:167], v[226:229], v[74:77]
	s_setprio 0
	s_setprio 1
	v_mfma_f32_16x16x32_bf16 v[118:121], v[172:175], v[198:201], v[118:121]
	v_mfma_f32_16x16x32_bf16 v[114:117], v[190:193], v[198:201], v[114:117]
	v_mfma_f32_16x16x32_bf16 v[102:105], v[172:175], v[206:209], v[102:105]
	v_mfma_f32_16x16x32_bf16 v[98:101], v[190:193], v[206:209], v[98:101]
	v_mfma_f32_16x16x32_bf16 v[86:89], v[172:175], v[214:217], v[86:89]
	v_mfma_f32_16x16x32_bf16 v[82:85], v[190:193], v[214:217], v[82:85]
	v_mfma_f32_16x16x32_bf16 v[70:73], v[172:175], v[222:225], v[70:73]
	v_mfma_f32_16x16x32_bf16 v[66:69], v[190:193], v[222:225], v[66:69]
	v_mfma_f32_16x16x32_bf16 v[118:121], v[176:179], v[202:205], v[118:121]
	v_mfma_f32_16x16x32_bf16 v[114:117], v[194:197], v[202:205], v[114:117]
	v_mfma_f32_16x16x32_bf16 v[102:105], v[176:179], v[210:213], v[102:105]
	v_mfma_f32_16x16x32_bf16 v[98:101], v[194:197], v[210:213], v[98:101]
	v_mfma_f32_16x16x32_bf16 v[86:89], v[176:179], v[218:221], v[86:89]
	v_mfma_f32_16x16x32_bf16 v[82:85], v[194:197], v[218:221], v[82:85]
	v_mfma_f32_16x16x32_bf16 v[70:73], v[176:179], v[226:229], v[70:73]
	v_mfma_f32_16x16x32_bf16 v[66:69], v[194:197], v[226:229], v[66:69]
	s_setprio 0
	s_barrier
	s_add_i32 s40, s40, s43
	v_lshl_add_u64 v[230:231], v[152:153], 0, s[30:31]
	s_mov_b32 m0, s40
	ds_read_b128 v[198:201], v157 offset:49152
	ds_read_b128 v[202:205], v157 offset:50176
	ds_read_b128 v[206:209], v157 offset:51200
	ds_read_b128 v[210:213], v157 offset:52224
	ds_read_b128 v[214:217], v157 offset:53248
	ds_read_b128 v[218:221], v157 offset:54272
	ds_read_b128 v[222:225], v157 offset:55296
	ds_read_b128 v[226:229], v157 offset:56320
	global_load_lds_dwordx4 v[230:231], off
	v_lshl_add_u64 v[230:231], v[152:153], 0, s[34:35]
	s_add_i32 m0, s40, 0x2000
	s_add_i32 s40, s41, s43
	global_load_lds_dwordx4 v[230:231], off
	v_lshl_add_u64 v[230:231], v[152:153], 0, s[88:89]
	s_mov_b32 m0, s40
	v_lshl_add_u64 v[152:153], v[152:153], 0, s[90:91]
	global_load_lds_dwordx4 v[230:231], off
	s_add_i32 m0, s40, 0x2000
	s_nop 0
	global_load_lds_dwordx4 v[152:153], off
	v_lshl_add_u64 v[152:153], v[180:181], 0, s[30:31]
	s_mov_b32 m0, s59
	s_nop 0
	global_load_lds_dwordx4 v[152:153], off
	v_lshl_add_u64 v[152:153], v[180:181], 0, s[34:35]
	s_mov_b32 m0, s60
	s_nop 0
	global_load_lds_dwordx4 v[152:153], off
	s_waitcnt vmcnt(8)
	s_waitcnt lgkmcnt(0)
	s_barrier
	s_setprio 1
	v_mfma_f32_16x16x32_bf16 v[62:65], v[130:133], v[198:201], v[62:65]
	v_mfma_f32_16x16x32_bf16 v[58:61], v[148:151], v[198:201], v[58:61]
	v_mfma_f32_16x16x32_bf16 v[46:49], v[130:133], v[206:209], v[46:49]
	v_mfma_f32_16x16x32_bf16 v[42:45], v[148:151], v[206:209], v[42:45]
	v_mfma_f32_16x16x32_bf16 v[30:33], v[130:133], v[214:217], v[30:33]
	v_mfma_f32_16x16x32_bf16 v[26:29], v[148:151], v[214:217], v[26:29]
	v_mfma_f32_16x16x32_bf16 v[14:17], v[130:133], v[222:225], v[14:17]
	v_mfma_f32_16x16x32_bf16 v[10:13], v[148:151], v[222:225], v[10:13]
	v_mfma_f32_16x16x32_bf16 v[62:65], v[134:137], v[202:205], v[62:65]
	v_mfma_f32_16x16x32_bf16 v[58:61], v[164:167], v[202:205], v[58:61]
	v_mfma_f32_16x16x32_bf16 v[46:49], v[134:137], v[210:213], v[46:49]
	v_mfma_f32_16x16x32_bf16 v[42:45], v[164:167], v[210:213], v[42:45]
	v_mfma_f32_16x16x32_bf16 v[30:33], v[134:137], v[218:221], v[30:33]
	v_mfma_f32_16x16x32_bf16 v[26:29], v[164:167], v[218:221], v[26:29]
	v_mfma_f32_16x16x32_bf16 v[14:17], v[134:137], v[226:229], v[14:17]
	v_mfma_f32_16x16x32_bf16 v[10:13], v[164:167], v[226:229], v[10:13]
	s_setprio 0
	s_setprio 1
	v_mfma_f32_16x16x32_bf16 v[54:57], v[172:175], v[198:201], v[54:57]
	v_mfma_f32_16x16x32_bf16 v[50:53], v[190:193], v[198:201], v[50:53]
	v_mfma_f32_16x16x32_bf16 v[38:41], v[172:175], v[206:209], v[38:41]
	v_mfma_f32_16x16x32_bf16 v[34:37], v[190:193], v[206:209], v[34:37]
	v_mfma_f32_16x16x32_bf16 v[22:25], v[172:175], v[214:217], v[22:25]
	v_mfma_f32_16x16x32_bf16 v[18:21], v[190:193], v[214:217], v[18:21]
	v_mfma_f32_16x16x32_bf16 v[6:9], v[172:175], v[222:225], v[6:9]
	v_mfma_f32_16x16x32_bf16 v[2:5], v[190:193], v[222:225], v[2:5]
	v_mfma_f32_16x16x32_bf16 v[54:57], v[176:179], v[202:205], v[54:57]
	v_mfma_f32_16x16x32_bf16 v[50:53], v[194:197], v[202:205], v[50:53]
	v_mfma_f32_16x16x32_bf16 v[38:41], v[176:179], v[210:213], v[38:41]
	v_mfma_f32_16x16x32_bf16 v[34:37], v[194:197], v[210:213], v[34:37]
	v_mfma_f32_16x16x32_bf16 v[22:25], v[176:179], v[218:221], v[22:25]
	v_mfma_f32_16x16x32_bf16 v[18:21], v[194:197], v[218:221], v[18:21]
	v_mfma_f32_16x16x32_bf16 v[6:9], v[176:179], v[226:229], v[6:9]
	v_mfma_f32_16x16x32_bf16 v[2:5], v[194:197], v[226:229], v[2:5]
	s_setprio 0
	s_barrier
	s_add_i32 s68, s68, 2
	s_add_u32 s38, s38, 0x100
	s_addc_u32 s39, s39, 0
	s_add_u32 s66, s66, 0x100
	s_addc_u32 s67, s67, 0
	s_cmp_gt_u32 s68, 61
	s_cbranch_scc0 .LBB0_3117
	s_and_b64 vcc, exec, s[12:13]
	s_cbranch_vccz .LBB0_3120
	s_barrier

.LBB0_3143:
	s_add_u32 s42, s40, 0xfff00080
	s_addc_u32 s43, s41, -1
	s_add_i32 s74, 0, 0x10000
	s_cmp_eq_u32 s71, 60
	s_cselect_b32 s43, s19, s43
	s_cselect_b32 s42, s39, s42
	s_cselect_b32 s73, s17, s70
	s_cselect_b32 s72, s68, s69
	s_add_i32 s75, 0, 0x14000
	v_add_u32_e32 v146, s74, v151
	v_add_u32_e32 v162, s75, v151
	ds_read_b128 v[130:133], v146
	ds_read_b128 v[134:137], v146 offset:1024
	ds_read_b128 v[142:145], v146 offset:2048
	ds_read_b128 v[146:149], v146 offset:3072
	ds_read_b128 v[154:157], v162
	ds_read_b128 v[158:161], v162 offset:1024
	ds_read_b128 v[164:167], v162 offset:2048
	ds_read_b128 v[172:175], v162 offset:3072
	v_lshl_add_u64 v[180:181], s[40:41], 0, v[140:141]
	s_add_i32 m0, s57, 0xc000
	ds_read_b128 v[176:179], v153
	ds_read_b128 v[190:193], v153 offset:1024
	ds_read_b128 v[194:197], v153 offset:2048
	ds_read_b128 v[198:201], v153 offset:3072
	ds_read_b128 v[202:205], v153 offset:4096
	ds_read_b128 v[206:209], v153 offset:5120
	ds_read_b128 v[210:213], v153 offset:6144
	ds_read_b128 v[214:217], v153 offset:7168
	global_load_lds_dwordx4 v[180:181], off
	v_lshl_add_u64 v[180:181], v[180:181], 0, s[24:25]
	s_add_i32 m0, s57, 0xe000
	s_nop 0
	global_load_lds_dwordx4 v[180:181], off
	s_waitcnt vmcnt(8)
	s_waitcnt lgkmcnt(0)
	s_barrier
	s_setprio 1
	v_mfma_f32_16x16x32_bf16 v[126:129], v[130:133], v[176:179], v[126:129]
	v_mfma_f32_16x16x32_bf16 v[122:125], v[142:145], v[176:179], v[122:125]
	v_mfma_f32_16x16x32_bf16 v[110:113], v[130:133], v[194:197], v[110:113]
	v_mfma_f32_16x16x32_bf16 v[106:109], v[142:145], v[194:197], v[106:109]
	v_mfma_f32_16x16x32_bf16 v[94:97], v[130:133], v[202:205], v[94:97]
	v_mfma_f32_16x16x32_bf16 v[90:93], v[142:145], v[202:205], v[90:93]
	v_mfma_f32_16x16x32_bf16 v[78:81], v[130:133], v[210:213], v[78:81]
	v_mfma_f32_16x16x32_bf16 v[74:77], v[142:145], v[210:213], v[74:77]
	v_mfma_f32_16x16x32_bf16 v[126:129], v[134:137], v[190:193], v[126:129]
	v_mfma_f32_16x16x32_bf16 v[122:125], v[146:149], v[190:193], v[122:125]
	v_mfma_f32_16x16x32_bf16 v[110:113], v[134:137], v[198:201], v[110:113]
	v_mfma_f32_16x16x32_bf16 v[106:109], v[146:149], v[198:201], v[106:109]
	v_mfma_f32_16x16x32_bf16 v[94:97], v[134:137], v[206:209], v[94:97]
	v_mfma_f32_16x16x32_bf16 v[90:93], v[146:149], v[206:209], v[90:93]
	v_mfma_f32_16x16x32_bf16 v[78:81], v[134:137], v[214:217], v[78:81]
	v_mfma_f32_16x16x32_bf16 v[74:77], v[146:149], v[214:217], v[74:77]
	s_setprio 0
	s_setprio 1
	v_mfma_f32_16x16x32_bf16 v[118:121], v[154:157], v[176:179], v[118:121]
	v_mfma_f32_16x16x32_bf16 v[114:117], v[164:167], v[176:179], v[114:117]
	v_mfma_f32_16x16x32_bf16 v[102:105], v[154:157], v[194:197], v[102:105]
	v_mfma_f32_16x16x32_bf16 v[98:101], v[164:167], v[194:197], v[98:101]
	v_mfma_f32_16x16x32_bf16 v[86:89], v[154:157], v[202:205], v[86:89]
	v_mfma_f32_16x16x32_bf16 v[82:85], v[164:167], v[202:205], v[82:85]
	v_mfma_f32_16x16x32_bf16 v[70:73], v[154:157], v[210:213], v[70:73]
	v_mfma_f32_16x16x32_bf16 v[66:69], v[164:167], v[210:213], v[66:69]
	v_mfma_f32_16x16x32_bf16 v[118:121], v[158:161], v[190:193], v[118:121]
	v_mfma_f32_16x16x32_bf16 v[114:117], v[172:175], v[190:193], v[114:117]
	v_mfma_f32_16x16x32_bf16 v[102:105], v[158:161], v[198:201], v[102:105]
	v_mfma_f32_16x16x32_bf16 v[98:101], v[172:175], v[198:201], v[98:101]
	v_mfma_f32_16x16x32_bf16 v[86:89], v[158:161], v[206:209], v[86:89]
	v_mfma_f32_16x16x32_bf16 v[82:85], v[172:175], v[206:209], v[82:85]
	v_mfma_f32_16x16x32_bf16 v[70:73], v[158:161], v[214:217], v[70:73]
	v_mfma_f32_16x16x32_bf16 v[66:69], v[172:175], v[214:217], v[66:69]
	s_setprio 0
	s_barrier
	v_lshl_add_u64 v[180:181], s[72:73], 0, v[0:1]
	s_add_i32 s72, s74, s55
	s_mov_b32 m0, s72
	ds_read_b128 v[176:179], v153 offset:16384
	ds_read_b128 v[190:193], v153 offset:17408
	ds_read_b128 v[194:197], v153 offset:18432
	ds_read_b128 v[198:201], v153 offset:19456
	ds_read_b128 v[202:205], v153 offset:20480
	ds_read_b128 v[206:209], v153 offset:21504
	ds_read_b128 v[210:213], v153 offset:22528
	ds_read_b128 v[214:217], v153 offset:23552
	global_load_lds_dwordx4 v[180:181], off
	v_lshl_add_u64 v[218:219], v[180:181], 0, s[24:25]
	s_add_i32 m0, s72, 0x2000
	s_add_i32 s72, s75, s55
	global_load_lds_dwordx4 v[218:219], off
	v_lshl_add_u64 v[218:219], v[180:181], 0, s[22:23]
	s_mov_b32 m0, s72
	s_nop 0
	global_load_lds_dwordx4 v[218:219], off
	v_lshl_add_u64 v[218:219], v[180:181], 0, s[28:29]
	s_add_i32 m0, s72, 0x2000
	s_nop 0
	global_load_lds_dwordx4 v[218:219], off
	v_lshl_add_u64 v[218:219], s[42:43], 0, v[138:139]
	s_mov_b32 m0, s57
	v_lshl_add_u64 v[220:221], v[218:219], 0, s[24:25]
	global_load_lds_dwordx4 v[218:219], off
	s_mov_b32 m0, s58
	s_nop 0
	global_load_lds_dwordx4 v[220:221], off
	s_waitcnt vmcnt(8)
	s_waitcnt lgkmcnt(0)
	s_barrier
	s_setprio 1
	v_mfma_f32_16x16x32_bf16 v[62:65], v[130:133], v[176:179], v[62:65]
	v_mfma_f32_16x16x32_bf16 v[58:61], v[142:145], v[176:179], v[58:61]
	v_mfma_f32_16x16x32_bf16 v[46:49], v[130:133], v[194:197], v[46:49]
	v_mfma_f32_16x16x32_bf16 v[42:45], v[142:145], v[194:197], v[42:45]
	v_mfma_f32_16x16x32_bf16 v[30:33], v[130:133], v[202:205], v[30:33]
	v_mfma_f32_16x16x32_bf16 v[26:29], v[142:145], v[202:205], v[26:29]
	v_mfma_f32_16x16x32_bf16 v[14:17], v[130:133], v[210:213], v[14:17]
	v_mfma_f32_16x16x32_bf16 v[10:13], v[142:145], v[210:213], v[10:13]
	v_mfma_f32_16x16x32_bf16 v[62:65], v[134:137], v[190:193], v[62:65]
	v_mfma_f32_16x16x32_bf16 v[58:61], v[146:149], v[190:193], v[58:61]
	v_mfma_f32_16x16x32_bf16 v[46:49], v[134:137], v[198:201], v[46:49]
	v_mfma_f32_16x16x32_bf16 v[42:45], v[146:149], v[198:201], v[42:45]
	v_mfma_f32_16x16x32_bf16 v[30:33], v[134:137], v[206:209], v[30:33]
	v_mfma_f32_16x16x32_bf16 v[26:29], v[146:149], v[206:209], v[26:29]
	v_mfma_f32_16x16x32_bf16 v[14:17], v[134:137], v[214:217], v[14:17]
	v_mfma_f32_16x16x32_bf16 v[10:13], v[146:149], v[214:217], v[10:13]
	s_setprio 0
	s_setprio 1
	v_mfma_f32_16x16x32_bf16 v[54:57], v[154:157], v[176:179], v[54:57]
	v_mfma_f32_16x16x32_bf16 v[50:53], v[164:167], v[176:179], v[50:53]
	v_mfma_f32_16x16x32_bf16 v[38:41], v[154:157], v[194:197], v[38:41]
	v_mfma_f32_16x16x32_bf16 v[34:37], v[164:167], v[194:197], v[34:37]
	v_mfma_f32_16x16x32_bf16 v[22:25], v[154:157], v[202:205], v[22:25]
	v_mfma_f32_16x16x32_bf16 v[18:21], v[164:167], v[202:205], v[18:21]
	v_mfma_f32_16x16x32_bf16 v[6:9], v[154:157], v[210:213], v[6:9]
	v_mfma_f32_16x16x32_bf16 v[2:5], v[164:167], v[210:213], v[2:5]
	v_mfma_f32_16x16x32_bf16 v[54:57], v[158:161], v[190:193], v[54:57]
	v_mfma_f32_16x16x32_bf16 v[50:53], v[172:175], v[190:193], v[50:53]
	v_mfma_f32_16x16x32_bf16 v[38:41], v[158:161], v[198:201], v[38:41]
	v_mfma_f32_16x16x32_bf16 v[34:37], v[172:175], v[198:201], v[34:37]
	v_mfma_f32_16x16x32_bf16 v[22:25], v[158:161], v[206:209], v[22:25]
	v_mfma_f32_16x16x32_bf16 v[18:21], v[172:175], v[206:209], v[18:21]
	v_mfma_f32_16x16x32_bf16 v[6:9], v[158:161], v[214:217], v[6:9]
	v_mfma_f32_16x16x32_bf16 v[2:5], v[172:175], v[214:217], v[2:5]
	s_setprio 0
	s_barrier
	s_add_i32 s42, 0, 0x18000
	s_add_i32 s43, 0, 0x1c000
	v_add_u32_e32 v146, s42, v151
	v_add_u32_e32 v162, s43, v151
	ds_read_b128 v[130:133], v146
	ds_read_b128 v[134:137], v146 offset:1024
	ds_read_b128 v[142:145], v146 offset:2048
	ds_read_b128 v[146:149], v146 offset:3072
	ds_read_b128 v[154:157], v162
	ds_read_b128 v[158:161], v162 offset:1024
	ds_read_b128 v[164:167], v162 offset:2048
	ds_read_b128 v[172:175], v162 offset:3072
	s_mov_b32 m0, s59
	v_lshl_add_u64 v[220:221], v[218:219], 0, s[22:23]
	ds_read_b128 v[176:179], v153 offset:32768
	ds_read_b128 v[190:193], v153 offset:33792
	ds_read_b128 v[194:197], v153 offset:34816
	ds_read_b128 v[198:201], v153 offset:35840
	ds_read_b128 v[202:205], v153 offset:36864
	ds_read_b128 v[206:209], v153 offset:37888
	ds_read_b128 v[210:213], v153 offset:38912
	ds_read_b128 v[214:217], v153 offset:39936
	global_load_lds_dwordx4 v[220:221], off
	v_lshl_add_u64 v[220:221], v[218:219], 0, s[28:29]
	s_mov_b32 m0, s60
	s_nop 0
	global_load_lds_dwordx4 v[220:221], off
	s_waitcnt vmcnt(8)
	s_waitcnt lgkmcnt(0)
	s_barrier
	s_setprio 1
	v_mfma_f32_16x16x32_bf16 v[126:129], v[130:133], v[176:179], v[126:129]
	v_mfma_f32_16x16x32_bf16 v[122:125], v[142:145], v[176:179], v[122:125]
	v_mfma_f32_16x16x32_bf16 v[110:113], v[130:133], v[194:197], v[110:113]
	v_mfma_f32_16x16x32_bf16 v[106:109], v[142:145], v[194:197], v[106:109]
	v_mfma_f32_16x16x32_bf16 v[94:97], v[130:133], v[202:205], v[94:97]
	v_mfma_f32_16x16x32_bf16 v[90:93], v[142:145], v[202:205], v[90:93]
	v_mfma_f32_16x16x32_bf16 v[78:81], v[130:133], v[210:213], v[78:81]
	v_mfma_f32_16x16x32_bf16 v[74:77], v[142:145], v[210:213], v[74:77]
	v_mfma_f32_16x16x32_bf16 v[126:129], v[134:137], v[190:193], v[126:129]
	v_mfma_f32_16x16x32_bf16 v[122:125], v[146:149], v[190:193], v[122:125]
	v_mfma_f32_16x16x32_bf16 v[110:113], v[134:137], v[198:201], v[110:113]
	v_mfma_f32_16x16x32_bf16 v[106:109], v[146:149], v[198:201], v[106:109]
	v_mfma_f32_16x16x32_bf16 v[94:97], v[134:137], v[206:209], v[94:97]
	v_mfma_f32_16x16x32_bf16 v[90:93], v[146:149], v[206:209], v[90:93]
	v_mfma_f32_16x16x32_bf16 v[78:81], v[134:137], v[214:217], v[78:81]
	v_mfma_f32_16x16x32_bf16 v[74:77], v[146:149], v[214:217], v[74:77]
	s_setprio 0
	s_setprio 1
	v_mfma_f32_16x16x32_bf16 v[118:121], v[154:157], v[176:179], v[118:121]
	v_mfma_f32_16x16x32_bf16 v[114:117], v[164:167], v[176:179], v[114:117]
	v_mfma_f32_16x16x32_bf16 v[102:105], v[154:157], v[194:197], v[102:105]
	v_mfma_f32_16x16x32_bf16 v[98:101], v[164:167], v[194:197], v[98:101]
	v_mfma_f32_16x16x32_bf16 v[86:89], v[154:157], v[202:205], v[86:89]
	v_mfma_f32_16x16x32_bf16 v[82:85], v[164:167], v[202:205], v[82:85]
	v_mfma_f32_16x16x32_bf16 v[70:73], v[154:157], v[210:213], v[70:73]
	v_mfma_f32_16x16x32_bf16 v[66:69], v[164:167], v[210:213], v[66:69]
	v_mfma_f32_16x16x32_bf16 v[118:121], v[158:161], v[190:193], v[118:121]
	v_mfma_f32_16x16x32_bf16 v[114:117], v[172:175], v[190:193], v[114:117]
	v_mfma_f32_16x16x32_bf16 v[102:105], v[158:161], v[198:201], v[102:105]
	v_mfma_f32_16x16x32_bf16 v[98:101], v[172:175], v[198:201], v[98:101]
	v_mfma_f32_16x16x32_bf16 v[86:89], v[158:161], v[206:209], v[86:89]
	v_mfma_f32_16x16x32_bf16 v[82:85], v[172:175], v[206:209], v[82:85]
	v_mfma_f32_16x16x32_bf16 v[70:73], v[158:161], v[214:217], v[70:73]
	v_mfma_f32_16x16x32_bf16 v[66:69], v[172:175], v[214:217], v[66:69]
	s_setprio 0
	s_barrier
	s_add_i32 s42, s42, s55
	v_lshl_add_u64 v[220:221], v[180:181], 0, s[30:31]
	s_mov_b32 m0, s42
	ds_read_b128 v[176:179], v153 offset:49152
	ds_read_b128 v[190:193], v153 offset:50176
	ds_read_b128 v[194:197], v153 offset:51200
	ds_read_b128 v[198:201], v153 offset:52224
	ds_read_b128 v[202:205], v153 offset:53248
	ds_read_b128 v[206:209], v153 offset:54272
	ds_read_b128 v[210:213], v153 offset:55296
	ds_read_b128 v[214:217], v153 offset:56320
	global_load_lds_dwordx4 v[220:221], off
	v_lshl_add_u64 v[220:221], v[180:181], 0, s[34:35]
	s_add_i32 m0, s42, 0x2000
	s_add_i32 s42, s43, s55
	global_load_lds_dwordx4 v[220:221], off
	v_lshl_add_u64 v[220:221], v[180:181], 0, s[88:89]
	s_mov_b32 m0, s42
	v_lshl_add_u64 v[180:181], v[180:181], 0, s[90:91]
	global_load_lds_dwordx4 v[220:221], off
	s_add_i32 m0, s42, 0x2000
	s_nop 0
	global_load_lds_dwordx4 v[180:181], off
	v_lshl_add_u64 v[180:181], v[218:219], 0, s[30:31]
	s_mov_b32 m0, s65
	s_nop 0
	global_load_lds_dwordx4 v[180:181], off
	v_lshl_add_u64 v[180:181], v[218:219], 0, s[34:35]
	s_mov_b32 m0, s66
	s_nop 0
	global_load_lds_dwordx4 v[180:181], off
	s_waitcnt vmcnt(8)
	s_waitcnt lgkmcnt(0)
	s_barrier
	s_setprio 1
	v_mfma_f32_16x16x32_bf16 v[62:65], v[130:133], v[176:179], v[62:65]
	v_mfma_f32_16x16x32_bf16 v[58:61], v[142:145], v[176:179], v[58:61]
	v_mfma_f32_16x16x32_bf16 v[46:49], v[130:133], v[194:197], v[46:49]
	v_mfma_f32_16x16x32_bf16 v[42:45], v[142:145], v[194:197], v[42:45]
	v_mfma_f32_16x16x32_bf16 v[30:33], v[130:133], v[202:205], v[30:33]
	v_mfma_f32_16x16x32_bf16 v[26:29], v[142:145], v[202:205], v[26:29]
	v_mfma_f32_16x16x32_bf16 v[14:17], v[130:133], v[210:213], v[14:17]
	v_mfma_f32_16x16x32_bf16 v[10:13], v[142:145], v[210:213], v[10:13]
	v_mfma_f32_16x16x32_bf16 v[62:65], v[134:137], v[190:193], v[62:65]
	v_mfma_f32_16x16x32_bf16 v[58:61], v[146:149], v[190:193], v[58:61]
	v_mfma_f32_16x16x32_bf16 v[46:49], v[134:137], v[198:201], v[46:49]
	v_mfma_f32_16x16x32_bf16 v[42:45], v[146:149], v[198:201], v[42:45]
	v_mfma_f32_16x16x32_bf16 v[30:33], v[134:137], v[206:209], v[30:33]
	v_mfma_f32_16x16x32_bf16 v[26:29], v[146:149], v[206:209], v[26:29]
	v_mfma_f32_16x16x32_bf16 v[14:17], v[134:137], v[214:217], v[14:17]
	v_mfma_f32_16x16x32_bf16 v[10:13], v[146:149], v[214:217], v[10:13]
	s_setprio 0
	s_setprio 1
	v_mfma_f32_16x16x32_bf16 v[54:57], v[154:157], v[176:179], v[54:57]
	v_mfma_f32_16x16x32_bf16 v[50:53], v[164:167], v[176:179], v[50:53]
	v_mfma_f32_16x16x32_bf16 v[38:41], v[154:157], v[194:197], v[38:41]
	v_mfma_f32_16x16x32_bf16 v[34:37], v[164:167], v[194:197], v[34:37]
	v_mfma_f32_16x16x32_bf16 v[22:25], v[154:157], v[202:205], v[22:25]
	v_mfma_f32_16x16x32_bf16 v[18:21], v[164:167], v[202:205], v[18:21]
	v_mfma_f32_16x16x32_bf16 v[6:9], v[154:157], v[210:213], v[6:9]
	v_mfma_f32_16x16x32_bf16 v[2:5], v[164:167], v[210:213], v[2:5]
	v_mfma_f32_16x16x32_bf16 v[54:57], v[158:161], v[190:193], v[54:57]
	v_mfma_f32_16x16x32_bf16 v[50:53], v[172:175], v[190:193], v[50:53]
	v_mfma_f32_16x16x32_bf16 v[38:41], v[158:161], v[198:201], v[38:41]
	v_mfma_f32_16x16x32_bf16 v[34:37], v[172:175], v[198:201], v[34:37]
	v_mfma_f32_16x16x32_bf16 v[22:25], v[158:161], v[206:209], v[22:25]
	v_mfma_f32_16x16x32_bf16 v[18:21], v[172:175], v[206:209], v[18:21]
	v_mfma_f32_16x16x32_bf16 v[6:9], v[158:161], v[214:217], v[6:9]
	v_mfma_f32_16x16x32_bf16 v[2:5], v[172:175], v[214:217], v[2:5]
	s_setprio 0
	s_barrier
	s_add_i32 s71, s71, 2
	s_add_u32 s40, s40, 0x100
	s_addc_u32 s41, s41, 0
	s_add_u32 s69, s69, 0x100
	s_addc_u32 s70, s70, 0
	s_cmp_gt_u32 s71, 61
	s_cbranch_scc0 .LBB0_3143
	s_and_b64 vcc, exec, s[14:15]
	s_cbranch_vccz .LBB0_3146
	s_barrier
